# v5 + write-through (sc1) dwordx4 stores for all inter-phase outputs (P0-P5)
# baseline (speedup 1.0000x reference)
; #define GAS __attribute__((address_space(1)))
; __device__ __forceinline__ unsigned cvt_pk_bf16(float lo, float hi) { unsigned r; asm volatile("v_cvt_pk_bf16_f32 %0, %1, %2" : "=v"(r) : "v"(lo), "v"(hi)); return r; }
; template <int NB>
; __device__ __forceinline__ void p0_batch(int it0, int stride, int lane, const P0Ptrs& a) {
;     f32x4 v[NB][8], s0[NB], s1[NB]; P0Desc d[NB];
; #pragma unroll
;     for (int q = 0; q < NB; ++q) { const bool ok = it0 < NFAST / 4; d[q] = p0_desc(p0_super(ok ? it0 : 0, q), lane, a); if (!ok) d[q].dst = nullptr;
; #pragma unroll
;         for (int i = 0; i < 8; ++i) v[q][i] = __builtin_nontemporal_load((const f32x4*)(d[q].src + (size_t)i * d[q].nsrc));
;         const float* kp = d[q].ks ? d[q].ks : a.ffn_g;
;         s0[q] = *(const f32x4*)(kp); s1[q] = *(const f32x4*)(kp + 4); }
; #pragma unroll
;     for (int q = 0; q < NB; ++q) {
;         const float gs = d[q].gs; const bool hk = d[q].ks != nullptr;
;         const f32x4 t0 = hk ? s0[q] * gs : (f32x4){gs, gs, gs, gs}, t1 = hk ? s1[q] * gs : (f32x4){gs, gs, gs, gs};
; #pragma unroll
;         for (int i = 0; i < 4; ++i) { v[q][i] *= t0[i]; v[q][4 + i] *= t1[i]; }
;         if (d[q].dst) {
; #pragma unroll
;             for (int e = 0; e < 4; ++e) { u32x4 o; o.x = cvt_pk_bf16(v[q][0][e], v[q][1][e]); o.y = cvt_pk_bf16(v[q][2][e], v[q][3][e]); o.z = cvt_pk_bf16(v[q][4][e], v[q][5][e]); o.w = cvt_pk_bf16(v[q][6][e], v[q][7][e]);
;                 *(GAS u32x4*)(d[q].dst + (size_t)e * d[q].ldt) = o; } }
;     }
; }
.LBB0_120:
	s_waitcnt vmcnt(39)
	v_lshl_or_b32 v170, v122, 6, v172
	v_ashrrev_i32_e32 v171, 31, v170
	v_mul_lo_u32 v124, s94, v171
	v_mul_lo_u32 v125, s95, v170
	v_mad_u64_u32 v[122:123], s[58:59], s94, v170, 0
	v_add3_u32 v123, v123, v124, v125
	v_lshl_add_u64 v[122:123], v[122:123], 2, s[92:93]
	s_cmp_lg_u64 s[54:55], 0
	v_lshl_add_u64 v[122:123], v[162:163], 2, v[122:123]
	v_lshl_add_u64 v[124:125], v[170:171], 2, s[54:55]
	s_cselect_b64 vcc, -1, 0
	s_lshl_b64 s[54:55], s[94:95], 2
	s_waitcnt vmcnt(35)
	v_lshl_add_u64 v[130:131], v[122:123], 0, s[54:55]
	s_waitcnt vmcnt(30)
	v_cndmask_b32_e32 v155, 0, v125, vcc
	v_cndmask_b32_e32 v154, 0, v124, vcc
	global_load_dwordx4 v[122:125], v[122:123], off nt
	s_nop 0
	global_load_dwordx4 v[126:129], v[130:131], off nt
	v_lshl_add_u64 v[130:131], v[130:131], 0, s[54:55]
	v_lshl_add_u64 v[132:133], v[130:131], 0, s[54:55]
	global_load_dwordx4 v[134:137], v[130:131], off nt
	global_load_dwordx4 v[142:145], v[132:133], off nt
	v_lshl_add_u64 v[130:131], v[132:133], 0, s[54:55]
	v_lshl_add_u64 v[146:147], v[130:131], 0, s[54:55]
	v_mov_b32_e32 v156, s15
	v_cmp_eq_u64_e32 vcc, 0, v[154:155]
	global_load_dwordx4 v[130:133], v[130:131], off nt
	s_nop 0
	global_load_dwordx4 v[138:141], v[146:147], off nt
	v_lshl_add_u64 v[146:147], v[146:147], 0, s[54:55]
	v_cndmask_b32_e32 v155, v155, v156, vcc
	v_mov_b32_e32 v156, s14
	v_lshl_add_u64 v[150:151], v[146:147], 0, s[54:55]
	v_cndmask_b32_e32 v154, v154, v156, vcc
	global_load_dwordx4 v[146:149], v[146:147], off nt
	s_nop 0
	global_load_dwordx4 v[150:153], v[150:151], off nt
	s_nop 0
	global_load_dwordx4 v[158:161], v[154:155], off offset:16
	s_nop 0
	global_load_dwordx4 v[154:157], v[154:155], off
	s_cmp_eq_u64 s[70:71], 0
	s_cbranch_scc1 .LBB0_122
	v_mad_u64_u32 v[180:181], s[54:55], s72, v176, 0
	v_mov_b32_e32 v162, v181
	v_mad_u64_u32 v[182:183], s[54:55], s73, v176, v[162:163]
	v_mov_b32_e32 v181, v182
	s_waitcnt vmcnt(30)
	v_cndmask_b32_e64 v37, v37, 1.0, s[0:1]
	v_cndmask_b32_e64 v36, v36, 1.0, s[0:1]
	v_cndmask_b32_e64 v35, v35, 1.0, s[0:1]
	v_cndmask_b32_e64 v34, v34, 1.0, s[0:1]
	v_lshl_add_u64 v[180:181], v[180:181], 1, s[70:71]
	v_cndmask_b32_e64 v41, v41, 1.0, s[0:1]
	v_cndmask_b32_e64 v40, v40, 1.0, s[0:1]
	v_cndmask_b32_e64 v39, v39, 1.0, s[0:1]
	v_cndmask_b32_e64 v38, v38, 1.0, s[0:1]
	v_pk_mul_f32 v[34:35], s[10:11], v[34:35] op_sel_hi:[0,1]
	v_pk_mul_f32 v[36:37], s[10:11], v[36:37] op_sel_hi:[0,1]
	v_lshl_add_u64 v[164:165], v[164:165], 1, v[180:181]
	v_pk_mul_f32 v[38:39], s[10:11], v[38:39] op_sel_hi:[0,1]
	v_pk_mul_f32 v[40:41], s[10:11], v[40:41] op_sel_hi:[0,1]
	v_pk_mul_f32 v[24:25], v[24:25], v[36:37] op_sel:[0,1]
	v_pk_mul_f32 v[22:23], v[22:23], v[36:37] op_sel:[0,1]
	v_pk_mul_f32 v[16:17], v[16:17], v[36:37] op_sel_hi:[1,0]
	v_pk_mul_f32 v[14:15], v[14:15], v[36:37] op_sel_hi:[1,0]
	v_pk_mul_f32 v[8:9], v[8:9], v[34:35] op_sel:[0,1]
	v_pk_mul_f32 v[6:7], v[6:7], v[34:35] op_sel:[0,1]
	v_pk_mul_f32 v[36:37], v[4:5], v[34:35] op_sel_hi:[1,0]
	v_pk_mul_f32 v[34:35], v[2:3], v[34:35] op_sel_hi:[1,0]
	s_lshl_b64 s[0:1], s[72:73], 1
	v_cvt_pk_bf16_f32 v2, v34, v6
	v_pk_mul_f32 v[30:31], v[30:31], v[40:41] op_sel:[0,1]
	v_pk_mul_f32 v[26:27], v[26:27], v[40:41] op_sel_hi:[1,0]
	v_pk_mul_f32 v[18:19], v[18:19], v[38:39] op_sel:[0,1]
	v_pk_mul_f32 v[10:11], v[10:11], v[38:39] op_sel_hi:[1,0]
	v_cvt_pk_bf16_f32 v3, v14, v22
	v_pk_mul_f32 v[32:33], v[32:33], v[40:41] op_sel:[0,1]
	v_cvt_pk_bf16_f32 v4, v10, v18
	v_cvt_pk_bf16_f32 v5, v26, v30
	global_store_dwordx4 v[164:165], v[2:5], off sc1
	v_pk_mul_f32 v[28:29], v[28:29], v[40:41] op_sel_hi:[1,0]
	v_pk_mul_f32 v[20:21], v[20:21], v[38:39] op_sel:[0,1]
	v_cvt_pk_bf16_f32 v2, v35, v7
	v_lshl_add_u64 v[6:7], v[164:165], 0, s[0:1]
	v_cvt_pk_bf16_f32 v3, v15, v23
	v_cvt_pk_bf16_f32 v4, v11, v19
	v_cvt_pk_bf16_f32 v5, v27, v31
	global_store_dwordx4 v[6:7], v[2:5], off sc1
	v_lshl_add_u64 v[6:7], v[6:7], 0, s[0:1]
	v_pk_mul_f32 v[12:13], v[12:13], v[38:39] op_sel_hi:[1,0]
	v_cvt_pk_bf16_f32 v2, v36, v8
	v_cvt_pk_bf16_f32 v3, v16, v24
	s_nop 0
	v_cvt_pk_bf16_f32 v4, v12, v20
	v_cvt_pk_bf16_f32 v5, v28, v32
	global_store_dwordx4 v[6:7], v[2:5], off sc1
	v_lshl_add_u64 v[6:7], v[6:7], 0, s[0:1]
	s_nop 0
	v_cvt_pk_bf16_f32 v2, v37, v9
	v_cvt_pk_bf16_f32 v3, v17, v25
	v_cvt_pk_bf16_f32 v4, v13, v21
	v_cvt_pk_bf16_f32 v5, v29, v33
	global_store_dwordx4 v[6:7], v[2:5], off sc1
; #define GAS __attribute__((address_space(1)))
; __device__ __forceinline__ unsigned cvt_pk_bf16(float lo, float hi) { unsigned r; asm volatile("v_cvt_pk_bf16_f32 %0, %1, %2" : "=v"(r) : "v"(lo), "v"(hi)); return r; }
; template <int NB>
; __device__ __forceinline__ void p0_batch(int it0, int stride, int lane, const P0Ptrs& a) {
;     ...
; #pragma unroll
;     for (int q = 0; q < NB; ++q) {
;         const float gs = d[q].gs; const bool hk = d[q].ks != nullptr;
;         const f32x4 t0 = hk ? s0[q] * gs : (f32x4){gs, gs, gs, gs}, t1 = hk ? s1[q] * gs : (f32x4){gs, gs, gs, gs};
; #pragma unroll
;         for (int i = 0; i < 4; ++i) { v[q][i] *= t0[i]; v[q][4 + i] *= t1[i]; }
;         if (d[q].dst) {
; #pragma unroll
;             for (int e = 0; e < 4; ++e) { u32x4 o; o.x = cvt_pk_bf16(v[q][0][e], v[q][1][e]); o.y = cvt_pk_bf16(v[q][2][e], v[q][3][e]); o.z = cvt_pk_bf16(v[q][4][e], v[q][5][e]); o.w = cvt_pk_bf16(v[q][6][e], v[q][7][e]);
;                 *(GAS u32x4*)(d[q].dst + (size_t)e * d[q].ldt) = o; } }
;     }
.LBB0_122:
	s_cmp_eq_u64 s[76:77], 0
	s_cbranch_scc1 .LBB0_124
	s_waitcnt vmcnt(39)
	v_mad_u64_u32 v[2:3], s[0:1], s78, v177, 0
	v_mov_b32_e32 v4, v3
	v_mad_u64_u32 v[4:5], s[0:1], s79, v177, v[4:5]
	v_mov_b32_e32 v3, v4
	v_lshl_add_u64 v[2:3], v[2:3], 1, s[76:77]
	s_waitcnt vmcnt(38)
	v_lshl_add_u64 v[6:7], v[166:167], 1, v[2:3]
	s_waitcnt vmcnt(21)
	v_cndmask_b32_e64 v3, v81, 1.0, s[6:7]
	v_cndmask_b32_e64 v2, v80, 1.0, s[6:7]
	v_cndmask_b32_e64 v5, v79, 1.0, s[6:7]
	v_cndmask_b32_e64 v4, v78, 1.0, s[6:7]
	s_waitcnt vmcnt(20)
	v_cndmask_b32_e64 v9, v77, 1.0, s[6:7]
	v_cndmask_b32_e64 v8, v76, 1.0, s[6:7]
	v_cndmask_b32_e64 v11, v75, 1.0, s[6:7]
	v_cndmask_b32_e64 v10, v74, 1.0, s[6:7]
	v_pk_mul_f32 v[4:5], s[74:75], v[4:5] op_sel_hi:[0,1]
	v_pk_mul_f32 v[2:3], s[74:75], v[2:3] op_sel_hi:[0,1]
	v_pk_mul_f32 v[10:11], s[74:75], v[10:11] op_sel_hi:[0,1]
	v_pk_mul_f32 v[8:9], s[74:75], v[8:9] op_sel_hi:[0,1]
	s_lshl_b64 s[0:1], s[78:79], 1
	v_pk_mul_f32 v[12:13], v[72:73], v[2:3] op_sel:[0,1]
	v_pk_mul_f32 v[14:15], v[70:71], v[2:3] op_sel:[0,1]
	v_pk_mul_f32 v[16:17], v[64:65], v[8:9] op_sel:[0,1]
	v_pk_mul_f32 v[18:19], v[62:63], v[8:9] op_sel:[0,1]
	v_pk_mul_f32 v[20:21], v[68:69], v[2:3] op_sel_hi:[1,0]
	v_pk_mul_f32 v[22:23], v[66:67], v[2:3] op_sel_hi:[1,0]
	v_pk_mul_f32 v[24:25], v[56:57], v[8:9] op_sel_hi:[1,0]
	v_pk_mul_f32 v[8:9], v[54:55], v[8:9] op_sel_hi:[1,0]
	v_pk_mul_f32 v[26:27], v[60:61], v[4:5] op_sel:[0,1]
	v_pk_mul_f32 v[28:29], v[58:59], v[4:5] op_sel:[0,1]
	v_pk_mul_f32 v[30:31], v[48:49], v[10:11] op_sel:[0,1]
	v_pk_mul_f32 v[32:33], v[46:47], v[10:11] op_sel:[0,1]
	v_pk_mul_f32 v[34:35], v[52:53], v[4:5] op_sel_hi:[1,0]
	v_pk_mul_f32 v[36:37], v[50:51], v[4:5] op_sel_hi:[1,0]
	v_pk_mul_f32 v[38:39], v[44:45], v[10:11] op_sel_hi:[1,0]
	v_pk_mul_f32 v[10:11], v[42:43], v[10:11] op_sel_hi:[1,0]
	s_nop 0
	v_cvt_pk_bf16_f32 v2, v10, v32
	v_cvt_pk_bf16_f32 v3, v8, v18
	v_cvt_pk_bf16_f32 v4, v36, v28
	v_cvt_pk_bf16_f32 v5, v22, v14
	global_store_dwordx4 v[6:7], v[2:5], off sc1
	v_lshl_add_u64 v[6:7], v[6:7], 0, s[0:1]
	s_nop 0
	v_cvt_pk_bf16_f32 v2, v11, v33
	v_cvt_pk_bf16_f32 v3, v9, v19
	v_cvt_pk_bf16_f32 v4, v37, v29
	v_cvt_pk_bf16_f32 v5, v23, v15
	global_store_dwordx4 v[6:7], v[2:5], off sc1
	v_lshl_add_u64 v[6:7], v[6:7], 0, s[0:1]
	s_nop 0
	v_cvt_pk_bf16_f32 v2, v38, v30
	v_cvt_pk_bf16_f32 v3, v24, v16
	v_cvt_pk_bf16_f32 v4, v34, v26
	v_cvt_pk_bf16_f32 v5, v20, v12
	global_store_dwordx4 v[6:7], v[2:5], off sc1
	v_lshl_add_u64 v[6:7], v[6:7], 0, s[0:1]
	s_nop 0
	v_cvt_pk_bf16_f32 v2, v39, v31
	v_cvt_pk_bf16_f32 v3, v25, v17
	v_cvt_pk_bf16_f32 v4, v35, v27
	v_cvt_pk_bf16_f32 v5, v21, v13
	global_store_dwordx4 v[6:7], v[2:5], off sc1
.LBB0_124:
	s_cmp_eq_u64 s[82:83], 0
	s_cbranch_scc1 .LBB0_126
	s_waitcnt vmcnt(39)
	v_mad_u64_u32 v[2:3], s[0:1], s84, v178, 0
	v_mov_b32_e32 v4, v3
	v_mad_u64_u32 v[4:5], s[0:1], s85, v178, v[4:5]
	v_mov_b32_e32 v3, v4
	v_lshl_add_u64 v[2:3], v[2:3], 1, s[82:83]
	s_waitcnt vmcnt(38)
	v_lshl_add_u64 v[6:7], v[168:169], 1, v[2:3]
	s_waitcnt vmcnt(11)
	v_cndmask_b32_e64 v3, v121, 1.0, s[4:5]
	v_cndmask_b32_e64 v2, v120, 1.0, s[4:5]
	v_cndmask_b32_e64 v5, v119, 1.0, s[4:5]
	v_cndmask_b32_e64 v4, v118, 1.0, s[4:5]
	s_waitcnt vmcnt(10)
	v_cndmask_b32_e64 v9, v117, 1.0, s[4:5]
	v_cndmask_b32_e64 v8, v116, 1.0, s[4:5]
	v_cndmask_b32_e64 v11, v115, 1.0, s[4:5]
	v_cndmask_b32_e64 v10, v114, 1.0, s[4:5]
	v_pk_mul_f32 v[4:5], s[80:81], v[4:5] op_sel_hi:[0,1]
	v_pk_mul_f32 v[2:3], s[80:81], v[2:3] op_sel_hi:[0,1]
	v_pk_mul_f32 v[10:11], s[80:81], v[10:11] op_sel_hi:[0,1]
	v_pk_mul_f32 v[8:9], s[80:81], v[8:9] op_sel_hi:[0,1]
	s_lshl_b64 s[0:1], s[84:85], 1
	v_pk_mul_f32 v[12:13], v[112:113], v[2:3] op_sel:[0,1]
	v_pk_mul_f32 v[14:15], v[110:111], v[2:3] op_sel:[0,1]
	v_pk_mul_f32 v[16:17], v[104:105], v[8:9] op_sel:[0,1]
	v_pk_mul_f32 v[18:19], v[102:103], v[8:9] op_sel:[0,1]
	v_pk_mul_f32 v[20:21], v[108:109], v[2:3] op_sel_hi:[1,0]
	v_pk_mul_f32 v[22:23], v[106:107], v[2:3] op_sel_hi:[1,0]
	v_pk_mul_f32 v[24:25], v[96:97], v[8:9] op_sel_hi:[1,0]
	v_pk_mul_f32 v[8:9], v[94:95], v[8:9] op_sel_hi:[1,0]
	v_pk_mul_f32 v[26:27], v[100:101], v[4:5] op_sel:[0,1]
	v_pk_mul_f32 v[28:29], v[98:99], v[4:5] op_sel:[0,1]
	v_pk_mul_f32 v[30:31], v[88:89], v[10:11] op_sel:[0,1]
	v_pk_mul_f32 v[32:33], v[86:87], v[10:11] op_sel:[0,1]
	v_pk_mul_f32 v[34:35], v[92:93], v[4:5] op_sel_hi:[1,0]
	v_pk_mul_f32 v[36:37], v[90:91], v[4:5] op_sel_hi:[1,0]
	v_pk_mul_f32 v[38:39], v[84:85], v[10:11] op_sel_hi:[1,0]
	v_pk_mul_f32 v[10:11], v[82:83], v[10:11] op_sel_hi:[1,0]
	s_nop 0
	v_cvt_pk_bf16_f32 v2, v10, v32
	v_cvt_pk_bf16_f32 v3, v8, v18
	v_cvt_pk_bf16_f32 v4, v36, v28
	v_cvt_pk_bf16_f32 v5, v22, v14
	global_store_dwordx4 v[6:7], v[2:5], off sc1
	v_lshl_add_u64 v[6:7], v[6:7], 0, s[0:1]
	s_nop 0
	v_cvt_pk_bf16_f32 v2, v11, v33
	v_cvt_pk_bf16_f32 v3, v9, v19
	v_cvt_pk_bf16_f32 v4, v37, v29
	v_cvt_pk_bf16_f32 v5, v23, v15
	global_store_dwordx4 v[6:7], v[2:5], off sc1
	v_lshl_add_u64 v[6:7], v[6:7], 0, s[0:1]
	s_nop 0
	v_cvt_pk_bf16_f32 v2, v38, v30
	v_cvt_pk_bf16_f32 v3, v24, v16
	v_cvt_pk_bf16_f32 v4, v34, v26
	v_cvt_pk_bf16_f32 v5, v20, v12
	global_store_dwordx4 v[6:7], v[2:5], off sc1
	v_lshl_add_u64 v[6:7], v[6:7], 0, s[0:1]
	s_nop 0
	v_cvt_pk_bf16_f32 v2, v39, v31
	v_cvt_pk_bf16_f32 v3, v25, v17
	v_cvt_pk_bf16_f32 v4, v35, v27
	v_cvt_pk_bf16_f32 v5, v21, v13
	global_store_dwordx4 v[6:7], v[2:5], off sc1
; #define GAS __attribute__((address_space(1)))
; __device__ __forceinline__ unsigned cvt_pk_bf16(float lo, float hi) { unsigned r; asm volatile("v_cvt_pk_bf16_f32 %0, %1, %2" : "=v"(r) : "v"(lo), "v"(hi)); return r; }
; template <int NB>
; __device__ __forceinline__ void p0_batch(int it0, int stride, int lane, const P0Ptrs& a) {
;     ...
; #pragma unroll
;     for (int q = 0; q < NB; ++q) {
;         const float gs = d[q].gs; const bool hk = d[q].ks != nullptr;
;         const f32x4 t0 = hk ? s0[q] * gs : (f32x4){gs, gs, gs, gs}, t1 = hk ? s1[q] * gs : (f32x4){gs, gs, gs, gs};
; #pragma unroll
;         for (int i = 0; i < 4; ++i) { v[q][i] *= t0[i]; v[q][4 + i] *= t1[i]; }
;         if (d[q].dst) {
; #pragma unroll
;             for (int e = 0; e < 4; ++e) { u32x4 o; o.x = cvt_pk_bf16(v[q][0][e], v[q][1][e]); o.y = cvt_pk_bf16(v[q][2][e], v[q][3][e]); o.z = cvt_pk_bf16(v[q][4][e], v[q][5][e]); o.w = cvt_pk_bf16(v[q][6][e], v[q][7][e]);
;                 *(GAS u32x4*)(d[q].dst + (size_t)e * d[q].ldt) = o; } }
;     }
.LBB0_126:
	s_cmp_eq_u64 s[88:89], 0
	s_cbranch_scc1 .LBB0_12
	s_waitcnt vmcnt(39)
	v_mad_u64_u32 v[2:3], s[0:1], s90, v179, 0
	v_mov_b32_e32 v4, v3
	v_mad_u64_u32 v[4:5], s[0:1], s91, v179, v[4:5]
	v_mov_b32_e32 v3, v4
	v_lshl_add_u64 v[2:3], v[2:3], 1, s[88:89]
	s_waitcnt vmcnt(38)
	v_lshl_add_u64 v[6:7], v[170:171], 1, v[2:3]
	s_waitcnt vmcnt(1)
	v_cndmask_b32_e64 v3, v161, 1.0, vcc
	v_cndmask_b32_e64 v2, v160, 1.0, vcc
	v_cndmask_b32_e64 v5, v159, 1.0, vcc
	v_cndmask_b32_e64 v4, v158, 1.0, vcc
	s_waitcnt vmcnt(0)
	v_cndmask_b32_e64 v9, v157, 1.0, vcc
	v_cndmask_b32_e64 v8, v156, 1.0, vcc
	v_cndmask_b32_e64 v11, v155, 1.0, vcc
	v_cndmask_b32_e64 v10, v154, 1.0, vcc
	v_pk_mul_f32 v[4:5], s[86:87], v[4:5] op_sel_hi:[0,1]
	v_pk_mul_f32 v[2:3], s[86:87], v[2:3] op_sel_hi:[0,1]
	v_pk_mul_f32 v[10:11], s[86:87], v[10:11] op_sel_hi:[0,1]
	v_pk_mul_f32 v[8:9], s[86:87], v[8:9] op_sel_hi:[0,1]
	s_lshl_b64 s[0:1], s[90:91], 1
	v_pk_mul_f32 v[12:13], v[152:153], v[2:3] op_sel:[0,1]
	v_pk_mul_f32 v[14:15], v[150:151], v[2:3] op_sel:[0,1]
	v_pk_mul_f32 v[16:17], v[144:145], v[8:9] op_sel:[0,1]
	v_pk_mul_f32 v[18:19], v[142:143], v[8:9] op_sel:[0,1]
	v_pk_mul_f32 v[20:21], v[148:149], v[2:3] op_sel_hi:[1,0]
	v_pk_mul_f32 v[22:23], v[146:147], v[2:3] op_sel_hi:[1,0]
	v_pk_mul_f32 v[24:25], v[136:137], v[8:9] op_sel_hi:[1,0]
	v_pk_mul_f32 v[8:9], v[134:135], v[8:9] op_sel_hi:[1,0]
	v_pk_mul_f32 v[26:27], v[140:141], v[4:5] op_sel:[0,1]
	v_pk_mul_f32 v[28:29], v[138:139], v[4:5] op_sel:[0,1]
	v_pk_mul_f32 v[30:31], v[128:129], v[10:11] op_sel:[0,1]
	v_pk_mul_f32 v[32:33], v[126:127], v[10:11] op_sel:[0,1]
	v_pk_mul_f32 v[34:35], v[132:133], v[4:5] op_sel_hi:[1,0]
	v_pk_mul_f32 v[36:37], v[130:131], v[4:5] op_sel_hi:[1,0]
	v_pk_mul_f32 v[38:39], v[124:125], v[10:11] op_sel_hi:[1,0]
	v_pk_mul_f32 v[10:11], v[122:123], v[10:11] op_sel_hi:[1,0]
	s_nop 0
	v_cvt_pk_bf16_f32 v2, v10, v32
	v_cvt_pk_bf16_f32 v3, v8, v18
	v_cvt_pk_bf16_f32 v4, v36, v28
	v_cvt_pk_bf16_f32 v5, v22, v14
	global_store_dwordx4 v[6:7], v[2:5], off sc1
	v_lshl_add_u64 v[6:7], v[6:7], 0, s[0:1]
	s_nop 0
	v_cvt_pk_bf16_f32 v2, v11, v33
	v_cvt_pk_bf16_f32 v3, v9, v19
	v_cvt_pk_bf16_f32 v4, v37, v29
	v_cvt_pk_bf16_f32 v5, v23, v15
	global_store_dwordx4 v[6:7], v[2:5], off sc1
	v_lshl_add_u64 v[6:7], v[6:7], 0, s[0:1]
	s_nop 0
	v_cvt_pk_bf16_f32 v2, v38, v30
	v_cvt_pk_bf16_f32 v3, v24, v16
	v_cvt_pk_bf16_f32 v4, v34, v26
	v_cvt_pk_bf16_f32 v5, v20, v12
	global_store_dwordx4 v[6:7], v[2:5], off sc1
	v_lshl_add_u64 v[6:7], v[6:7], 0, s[0:1]
	s_nop 0
	v_cvt_pk_bf16_f32 v2, v39, v31
	v_cvt_pk_bf16_f32 v3, v25, v17
	v_cvt_pk_bf16_f32 v4, v35, v27
	v_cvt_pk_bf16_f32 v5, v21, v13
	global_store_dwordx4 v[6:7], v[2:5], off sc1
	s_branch .LBB0_12

; #define LAS __attribute__((address_space(3)))
; #define GAS __attribute__((address_space(1)))
; #define LDS_WAIT() asm volatile("s_waitcnt lgkmcnt(0)" ::: "memory")
; __device__ __forceinline__ unsigned pk2(float lo, float hi) { return cvt_pk_bf16(lo, hi); }
; template <class F>
; __device__ __forceinline__ void p0_item(const float* W, int Nsrc, bf16_t* WT, int ldt, const float* ks, float gs, LAS float* scr, int kb, int nb, int lane, F srccol) {
;     ...
;     LDS_WAIT(); asm volatile("" ::: "memory");
;     const int c = lane & 7;
; #pragma unroll
;     for (int j = 0; j < 4; ++j) { const int n = (lane >> 3) + 8 * j; const LAS float* s = scr + (8 * c) * 33 + n;
;         u32x4 o; o.x = pk2(s[0 * 33], s[1 * 33]); o.y = pk2(s[2 * 33], s[3 * 33]); o.z = pk2(s[4 * 33], s[5 * 33]); o.w = pk2(s[6 * 33], s[7 * 33]);
;         *(GAS u32x4*)(WT + (size_t)(n0 + n) * ldt + k0 + 8 * c) = o; }
;     LDS_WAIT(); asm volatile("" ::: "memory");
.LBB0_130:
	s_waitcnt lgkmcnt(0)
	s_lshl_b32 s4, s44, 3
	ds_read2_b32 v[22:23], v26 offset1:33
	s_andn2_b32 s4, s4, 63
	s_waitcnt lgkmcnt(0)
	v_cvt_pk_bf16_f32 v22, v22, v23
	ds_read2_b32 v[24:25], v26 offset0:66 offset1:99
	s_ashr_i32 s5, s4, 31
	s_waitcnt lgkmcnt(0)
	v_cvt_pk_bf16_f32 v23, v24, v25
	ds_read2_b32 v[24:25], v26 offset0:132 offset1:165
	v_mov_b32_e32 v15, v7
	v_lshl_add_u64 v[36:37], s[4:5], 1, v[10:11]
	s_waitcnt lgkmcnt(0)
	v_cvt_pk_bf16_f32 v24, v24, v25
	ds_read2_b32 v[34:35], v26 offset0:198 offset1:231
	s_waitcnt lgkmcnt(0)
	v_cvt_pk_bf16_f32 v25, v34, v35
	v_lshl_add_u64 v[38:39], v[36:37], 0, v[14:15]
	ds_read2_b32 v[34:35], v26 offset0:8 offset1:41
	global_store_dwordx4 v[38:39], v[22:25], off sc1
	v_mov_b32_e32 v17, v7
	v_lshl_add_u64 v[38:39], v[36:37], 0, v[16:17]
	s_waitcnt lgkmcnt(0)
	v_cvt_pk_bf16_f32 v22, v34, v35
	ds_read2_b32 v[24:25], v26 offset0:74 offset1:107
	s_waitcnt lgkmcnt(0)
	v_cvt_pk_bf16_f32 v23, v24, v25
	ds_read2_b32 v[24:25], v26 offset0:140 offset1:173
	s_waitcnt lgkmcnt(0)
	v_cvt_pk_bf16_f32 v24, v24, v25
	ds_read2_b32 v[34:35], v26 offset0:206 offset1:239
	s_waitcnt lgkmcnt(0)
	v_cvt_pk_bf16_f32 v25, v34, v35
	ds_read2_b32 v[34:35], v26 offset0:16 offset1:49
	global_store_dwordx4 v[38:39], v[22:25], off sc1
	v_mov_b32_e32 v19, v7
	v_lshl_add_u64 v[38:39], v[36:37], 0, v[18:19]
	s_waitcnt lgkmcnt(0)
	v_cvt_pk_bf16_f32 v22, v34, v35
	ds_read2_b32 v[24:25], v26 offset0:82 offset1:115
	s_waitcnt lgkmcnt(0)
	v_cvt_pk_bf16_f32 v23, v24, v25
	ds_read2_b32 v[24:25], v26 offset0:148 offset1:181
	s_waitcnt lgkmcnt(0)
	v_cvt_pk_bf16_f32 v24, v24, v25
	ds_read2_b32 v[34:35], v26 offset0:214 offset1:247
	s_waitcnt lgkmcnt(0)
	v_cvt_pk_bf16_f32 v25, v34, v35
	ds_read2_b32 v[34:35], v26 offset0:24 offset1:57
	global_store_dwordx4 v[38:39], v[22:25], off sc1
	v_mov_b32_e32 v21, v7
	s_waitcnt lgkmcnt(0)
	v_cvt_pk_bf16_f32 v22, v34, v35
	ds_read2_b32 v[24:25], v26 offset0:90 offset1:123
	s_waitcnt lgkmcnt(0)
	v_cvt_pk_bf16_f32 v23, v24, v25
	ds_read2_b32 v[24:25], v26 offset0:156 offset1:189
	s_waitcnt lgkmcnt(0)
	v_cvt_pk_bf16_f32 v24, v24, v25
	ds_read2_b32 v[34:35], v26 offset0:222 offset1:255
	s_waitcnt lgkmcnt(0)
	v_cvt_pk_bf16_f32 v25, v34, v35
	v_lshl_add_u64 v[34:35], v[36:37], 0, v[20:21]
	global_store_dwordx4 v[34:35], v[22:25], off sc1
	s_waitcnt lgkmcnt(0)

; #define LAS __attribute__((address_space(3)))
; #define GAS __attribute__((address_space(1)))
; #define LDS_WAIT() asm volatile("s_waitcnt lgkmcnt(0)" ::: "memory")
; __device__ __forceinline__ unsigned pk2(float lo, float hi) { return cvt_pk_bf16(lo, hi); }
; template <class F>
; __device__ __forceinline__ void p0_item(const float* W, int Nsrc, bf16_t* WT, int ldt, const float* ks, float gs, LAS float* scr, int kb, int nb, int lane, F srccol) {
;     ...
;     LDS_WAIT(); asm volatile("" ::: "memory");
;     const int c = lane & 7;
; #pragma unroll
;     for (int j = 0; j < 4; ++j) { const int n = (lane >> 3) + 8 * j; const LAS float* s = scr + (8 * c) * 33 + n;
;         u32x4 o; o.x = pk2(s[0 * 33], s[1 * 33]); o.y = pk2(s[2 * 33], s[3 * 33]); o.z = pk2(s[4 * 33], s[5 * 33]); o.w = pk2(s[6 * 33], s[7 * 33]);
;         *(GAS u32x4*)(WT + (size_t)(n0 + n) * ldt + k0 + 8 * c) = o; }
;     LDS_WAIT(); asm volatile("" ::: "memory");
.LBB0_151:
	s_waitcnt lgkmcnt(0)
	s_lshl_b32 s5, s44, 2
	ds_read2_b32 v[22:23], v26 offset1:33
	s_and_b32 s5, s5, 0x7fffffc0
	s_waitcnt lgkmcnt(0)
	v_cvt_pk_bf16_f32 v22, v22, v23
	ds_read2_b32 v[24:25], v26 offset0:66 offset1:99
	v_or_b32_e32 v6, s4, v5
	s_add_i32 s12, s5, 0xfffffc00
	s_waitcnt lgkmcnt(0)
	v_cvt_pk_bf16_f32 v23, v24, v25
	ds_read2_b32 v[24:25], v26 offset0:132 offset1:165
	v_lshlrev_b32_e32 v6, 12, v6
	v_lshl_add_u64 v[36:37], s[12:13], 1, v[8:9]
	s_waitcnt lgkmcnt(0)
	v_cvt_pk_bf16_f32 v24, v24, v25
	ds_read2_b32 v[34:35], v26 offset0:198 offset1:231
	s_waitcnt lgkmcnt(0)
	v_cvt_pk_bf16_f32 v25, v34, v35
	v_lshl_add_u64 v[38:39], v[36:37], 0, v[6:7]
	ds_read2_b32 v[34:35], v26 offset0:8 offset1:41
	global_store_dwordx4 v[38:39], v[22:25], off sc1
	v_or_b32_e32 v6, s4, v27
	v_lshlrev_b32_e32 v6, 12, v6
	s_waitcnt lgkmcnt(0)
	v_cvt_pk_bf16_f32 v22, v34, v35
	ds_read2_b32 v[24:25], v26 offset0:74 offset1:107
	s_waitcnt lgkmcnt(0)
	v_cvt_pk_bf16_f32 v23, v24, v25
	ds_read2_b32 v[24:25], v26 offset0:140 offset1:173
	s_waitcnt lgkmcnt(0)
	v_cvt_pk_bf16_f32 v24, v24, v25
	ds_read2_b32 v[34:35], v26 offset0:206 offset1:239
	s_waitcnt lgkmcnt(0)
	v_cvt_pk_bf16_f32 v25, v34, v35
	v_lshl_add_u64 v[38:39], v[36:37], 0, v[6:7]
	ds_read2_b32 v[34:35], v26 offset0:16 offset1:49
	global_store_dwordx4 v[38:39], v[22:25], off sc1
	v_or_b32_e32 v6, s4, v28
	v_lshlrev_b32_e32 v6, 12, v6
	s_waitcnt lgkmcnt(0)
	v_cvt_pk_bf16_f32 v22, v34, v35
	ds_read2_b32 v[24:25], v26 offset0:82 offset1:115
	s_waitcnt lgkmcnt(0)
	v_cvt_pk_bf16_f32 v23, v24, v25
	ds_read2_b32 v[24:25], v26 offset0:148 offset1:181
	s_waitcnt lgkmcnt(0)
	v_cvt_pk_bf16_f32 v24, v24, v25
	ds_read2_b32 v[34:35], v26 offset0:214 offset1:247
	s_waitcnt lgkmcnt(0)
	v_cvt_pk_bf16_f32 v25, v34, v35
	v_lshl_add_u64 v[38:39], v[36:37], 0, v[6:7]
	ds_read2_b32 v[34:35], v26 offset0:24 offset1:57
	global_store_dwordx4 v[38:39], v[22:25], off sc1
	v_or_b32_e32 v6, s4, v29
	v_lshlrev_b32_e32 v6, 12, v6
	s_waitcnt lgkmcnt(0)
	v_cvt_pk_bf16_f32 v22, v34, v35
	ds_read2_b32 v[24:25], v26 offset0:90 offset1:123
	s_waitcnt lgkmcnt(0)
	v_cvt_pk_bf16_f32 v23, v24, v25
	ds_read2_b32 v[24:25], v26 offset0:156 offset1:189
	s_waitcnt lgkmcnt(0)
	v_cvt_pk_bf16_f32 v24, v24, v25
	ds_read2_b32 v[34:35], v26 offset0:222 offset1:255
	s_waitcnt lgkmcnt(0)
	v_cvt_pk_bf16_f32 v25, v34, v35
	v_lshl_add_u64 v[34:35], v[36:37], 0, v[6:7]
	global_store_dwordx4 v[34:35], v[22:25], off sc1
	s_waitcnt lgkmcnt(0)
	s_mov_b64 s[4:5], 0

; __device__ __forceinline__ unsigned cvt_pk_bf16(float lo, float hi) { unsigned r; asm volatile("v_cvt_pk_bf16_f32 %0, %1, %2" : "=v"(r) : "v"(lo), "v"(hi)); return r; }
;     __device__ __forceinline__ void operator()(Acc& acc, const Unit& u, int slot, int cslot, int wr, int wc, int fr, int fq, LAS unsigned char* lds) const {
;     ...
;                     bool st = true; bf16_t* dst;
;                     if (ty == 0) dst = Q + row * 1536 + pn * 256 + bj * HALF + wc * 32 + 8 * fq;
;                     else if (ty == 1) dst = KV + row * 2048 + pn * 256 + bj * HALF + wc * 32 + 8 * fq;
;                     else { st = (bj == 0 && wc < 2); dst = KPE + row * 64 + wc * 32 + 8 * fq; }
;                     if (rbj == bj) {
;                         const f32x4 c01 = cs0[ai][m], c23 = cs1[ai][m];
;                         f32x4 r0, r1;
;                         r0[0] = v0[0] * c01[0] - v0[1] * c01[1]; r0[1] = v0[0] * c01[1] + v0[1] * c01[0];
;                         r0[2] = v0[2] * c01[2] - v0[3] * c01[3]; r0[3] = v0[2] * c01[3] + v0[3] * c01[2];
;                         r1[0] = v1[0] * c23[0] - v1[1] * c23[1]; r1[1] = v1[0] * c23[1] + v1[1] * c23[0];
;                         r1[2] = v1[2] * c23[2] - v1[3] * c23[3]; r1[3] = v1[2] * c23[3] + v1[3] * c23[2];
;                         v0 = r0; v1 = r1;
;                     }
;                     if (st) { u32x4 w; w.x = cvt_pk_bf16(v0[0], v0[1]); w.y = cvt_pk_bf16(v0[2], v0[3]); w.z = cvt_pk_bf16(v1[0], v1[1]); w.w = cvt_pk_bf16(v1[2], v1[3]);
;                         *(u32x4*)dst = w; }
.LBB0_475:
	s_lshl_b32 s68, s57, 1
	v_lshl_add_u64 v[206:207], v[206:207], 0, s[68:69]
	v_lshl_add_u64 v[226:227], v[140:141], 1, v[206:207]
	v_cvt_pk_bf16_f32 v206, v208, v209
	v_cvt_pk_bf16_f32 v207, v214, v215
	v_cvt_pk_bf16_f32 v208, v210, v211
	v_cvt_pk_bf16_f32 v209, v212, v213
	global_store_dwordx4 v[226:227], v[206:209], off sc1

; __device__ __forceinline__ unsigned cvt_pk_bf16(float lo, float hi) { unsigned r; asm volatile("v_cvt_pk_bf16_f32 %0, %1, %2" : "=v"(r) : "v"(lo), "v"(hi)); return r; }
;     __device__ __forceinline__ void operator()(Acc& acc, const Unit& u, int slot, int cslot, int wr, int wc, int fr, int fq, LAS unsigned char* lds) const {
;     ...
;                     bool st = true; bf16_t* dst;
;                     if (ty == 0) dst = Q + row * 1536 + pn * 256 + bj * HALF + wc * 32 + 8 * fq;
;                     else if (ty == 1) dst = KV + row * 2048 + pn * 256 + bj * HALF + wc * 32 + 8 * fq;
;                     else { st = (bj == 0 && wc < 2); dst = KPE + row * 64 + wc * 32 + 8 * fq; }
;                     if (rbj == bj) {
;                         const f32x4 c01 = cs0[ai][m], c23 = cs1[ai][m];
;                         f32x4 r0, r1;
;                         r0[0] = v0[0] * c01[0] - v0[1] * c01[1]; r0[1] = v0[0] * c01[1] + v0[1] * c01[0];
;                         r0[2] = v0[2] * c01[2] - v0[3] * c01[3]; r0[3] = v0[2] * c01[3] + v0[3] * c01[2];
;                         r1[0] = v1[0] * c23[0] - v1[1] * c23[1]; r1[1] = v1[0] * c23[1] + v1[1] * c23[0];
;                         r1[2] = v1[2] * c23[2] - v1[3] * c23[3]; r1[3] = v1[2] * c23[3] + v1[3] * c23[2];
;                         v0 = r0; v1 = r1;
;                     }
;                     if (st) { u32x4 w; w.x = cvt_pk_bf16(v0[0], v0[1]); w.y = cvt_pk_bf16(v0[2], v0[3]); w.z = cvt_pk_bf16(v1[0], v1[1]); w.w = cvt_pk_bf16(v1[2], v1[3]);
;                         *(u32x4*)dst = w; }
.LBB0_483:
	s_andn2_b64 vcc, exec, s[6:7]
	s_cbranch_vccnz .LBB0_485
	s_lshl_b32 s68, s57, 1
	v_lshl_add_u64 v[190:191], v[206:207], 0, s[68:69]
	v_lshl_add_u64 v[194:195], v[140:141], 1, v[190:191]
	v_cvt_pk_bf16_f32 v190, v200, v201
	v_cvt_pk_bf16_f32 v191, v204, v205
	v_cvt_pk_bf16_f32 v192, v198, v199
	v_cvt_pk_bf16_f32 v193, v202, v203
	global_store_dwordx4 v[194:195], v[190:193], off sc1

; __device__ __forceinline__ unsigned cvt_pk_bf16(float lo, float hi) { unsigned r; asm volatile("v_cvt_pk_bf16_f32 %0, %1, %2" : "=v"(r) : "v"(lo), "v"(hi)); return r; }
;     __device__ __forceinline__ void operator()(Acc& acc, const Unit& u, int slot, int cslot, int wr, int wc, int fr, int fq, LAS unsigned char* lds) const {
;     ...
;                     bool st = true; bf16_t* dst;
;                     if (ty == 0) dst = Q + row * 1536 + pn * 256 + bj * HALF + wc * 32 + 8 * fq;
;                     else if (ty == 1) dst = KV + row * 2048 + pn * 256 + bj * HALF + wc * 32 + 8 * fq;
;                     else { st = (bj == 0 && wc < 2); dst = KPE + row * 64 + wc * 32 + 8 * fq; }
;                     if (rbj == bj) {
;                         const f32x4 c01 = cs0[ai][m], c23 = cs1[ai][m];
;                         f32x4 r0, r1;
;                         r0[0] = v0[0] * c01[0] - v0[1] * c01[1]; r0[1] = v0[0] * c01[1] + v0[1] * c01[0];
;                         r0[2] = v0[2] * c01[2] - v0[3] * c01[3]; r0[3] = v0[2] * c01[3] + v0[3] * c01[2];
;                         r1[0] = v1[0] * c23[0] - v1[1] * c23[1]; r1[1] = v1[0] * c23[1] + v1[1] * c23[0];
;                         r1[2] = v1[2] * c23[2] - v1[3] * c23[3]; r1[3] = v1[2] * c23[3] + v1[3] * c23[2];
;                         v0 = r0; v1 = r1;
;                     }
;                     if (st) { u32x4 w; w.x = cvt_pk_bf16(v0[0], v0[1]); w.y = cvt_pk_bf16(v0[2], v0[3]); w.z = cvt_pk_bf16(v1[0], v1[1]); w.w = cvt_pk_bf16(v1[2], v1[3]);
;                         *(u32x4*)dst = w; }
.LBB0_505:
	s_andn2_b64 vcc, exec, s[74:75]
	s_cbranch_vccnz .LBB0_507
	s_lshl_b32 s68, s57, 1
	v_lshl_add_u64 v[182:183], v[198:199], 0, s[68:69]
	v_lshl_add_u64 v[186:187], v[140:141], 1, v[182:183]
	v_cvt_pk_bf16_f32 v182, v192, v193
	v_cvt_pk_bf16_f32 v183, v196, v197
	v_cvt_pk_bf16_f32 v184, v190, v191
	v_cvt_pk_bf16_f32 v185, v194, v195
	global_store_dwordx4 v[186:187], v[182:185], off sc1

; __device__ __forceinline__ unsigned cvt_pk_bf16(float lo, float hi) { unsigned r; asm volatile("v_cvt_pk_bf16_f32 %0, %1, %2" : "=v"(r) : "v"(lo), "v"(hi)); return r; }
;     __device__ __forceinline__ void operator()(Acc& acc, const Unit& u, int slot, int cslot, int wr, int wc, int fr, int fq, LAS unsigned char* lds) const {
;     ...
;                     bool st = true; bf16_t* dst;
;                     if (ty == 0) dst = Q + row * 1536 + pn * 256 + bj * HALF + wc * 32 + 8 * fq;
;                     else if (ty == 1) dst = KV + row * 2048 + pn * 256 + bj * HALF + wc * 32 + 8 * fq;
;                     else { st = (bj == 0 && wc < 2); dst = KPE + row * 64 + wc * 32 + 8 * fq; }
;                     if (rbj == bj) {
;                         const f32x4 c01 = cs0[ai][m], c23 = cs1[ai][m];
;                         f32x4 r0, r1;
;                         r0[0] = v0[0] * c01[0] - v0[1] * c01[1]; r0[1] = v0[0] * c01[1] + v0[1] * c01[0];
;                         r0[2] = v0[2] * c01[2] - v0[3] * c01[3]; r0[3] = v0[2] * c01[3] + v0[3] * c01[2];
;                         r1[0] = v1[0] * c23[0] - v1[1] * c23[1]; r1[1] = v1[0] * c23[1] + v1[1] * c23[0];
;                         r1[2] = v1[2] * c23[2] - v1[3] * c23[3]; r1[3] = v1[2] * c23[3] + v1[3] * c23[2];
;                         v0 = r0; v1 = r1;
;                     }
;                     if (st) { u32x4 w; w.x = cvt_pk_bf16(v0[0], v0[1]); w.y = cvt_pk_bf16(v0[2], v0[3]); w.z = cvt_pk_bf16(v1[0], v1[1]); w.w = cvt_pk_bf16(v1[2], v1[3]);
;                         *(u32x4*)dst = w; }
.LBB0_514:
	s_lshl_b32 s68, s57, 1
	v_lshl_add_u64 v[198:199], v[198:199], 0, s[68:69]
	v_lshl_add_u64 v[208:209], v[140:141], 1, v[198:199]
	v_cvt_pk_bf16_f32 v198, v200, v201
	v_cvt_pk_bf16_f32 v199, v206, v207
	v_cvt_pk_bf16_f32 v200, v204, v205
	v_cvt_pk_bf16_f32 v201, v202, v203
	global_store_dwordx4 v[208:209], v[198:201], off sc1
	s_and_b64 vcc, exec, s[4:5]
	s_cbranch_vccz .LBB0_499

; __device__ __forceinline__ unsigned cvt_pk_bf16(float lo, float hi) { unsigned r; asm volatile("v_cvt_pk_bf16_f32 %0, %1, %2" : "=v"(r) : "v"(lo), "v"(hi)); return r; }
;     __device__ __forceinline__ void operator()(Acc& acc, const Unit& u, int slot, int cslot, int wr, int wc, int fr, int fq, LAS unsigned char* lds) const {
;     ...
;                     bool st = true; bf16_t* dst;
;                     if (ty == 0) dst = Q + row * 1536 + pn * 256 + bj * HALF + wc * 32 + 8 * fq;
;                     else if (ty == 1) dst = KV + row * 2048 + pn * 256 + bj * HALF + wc * 32 + 8 * fq;
;                     else { st = (bj == 0 && wc < 2); dst = KPE + row * 64 + wc * 32 + 8 * fq; }
;                     if (rbj == bj) {
;                         const f32x4 c01 = cs0[ai][m], c23 = cs1[ai][m];
;                         f32x4 r0, r1;
;                         r0[0] = v0[0] * c01[0] - v0[1] * c01[1]; r0[1] = v0[0] * c01[1] + v0[1] * c01[0];
;                         r0[2] = v0[2] * c01[2] - v0[3] * c01[3]; r0[3] = v0[2] * c01[3] + v0[3] * c01[2];
;                         r1[0] = v1[0] * c23[0] - v1[1] * c23[1]; r1[1] = v1[0] * c23[1] + v1[1] * c23[0];
;                         r1[2] = v1[2] * c23[2] - v1[3] * c23[3]; r1[3] = v1[2] * c23[3] + v1[3] * c23[2];
;                         v0 = r0; v1 = r1;
;                     }
;                     if (st) { u32x4 w; w.x = cvt_pk_bf16(v0[0], v0[1]); w.y = cvt_pk_bf16(v0[2], v0[3]); w.z = cvt_pk_bf16(v1[0], v1[1]); w.w = cvt_pk_bf16(v1[2], v1[3]);
;                         *(u32x4*)dst = w; }
.LBB0_528:
	s_andn2_b64 vcc, exec, s[54:55]
	s_cbranch_vccnz .LBB0_530
	s_lshl_b32 s68, s57, 1
	v_lshl_add_u64 v[174:175], v[190:191], 0, s[68:69]
	v_lshl_add_u64 v[178:179], v[140:141], 1, v[174:175]
	v_cvt_pk_bf16_f32 v174, v184, v185
	v_cvt_pk_bf16_f32 v175, v188, v189
	v_cvt_pk_bf16_f32 v176, v182, v183
	v_cvt_pk_bf16_f32 v177, v186, v187
	global_store_dwordx4 v[178:179], v[174:177], off sc1

; __device__ __forceinline__ unsigned cvt_pk_bf16(float lo, float hi) { unsigned r; asm volatile("v_cvt_pk_bf16_f32 %0, %1, %2" : "=v"(r) : "v"(lo), "v"(hi)); return r; }
;     __device__ __forceinline__ void operator()(Acc& acc, const Unit& u, int slot, int cslot, int wr, int wc, int fr, int fq, LAS unsigned char* lds) const {
;     ...
;                     bool st = true; bf16_t* dst;
;                     if (ty == 0) dst = Q + row * 1536 + pn * 256 + bj * HALF + wc * 32 + 8 * fq;
;                     else if (ty == 1) dst = KV + row * 2048 + pn * 256 + bj * HALF + wc * 32 + 8 * fq;
;                     else { st = (bj == 0 && wc < 2); dst = KPE + row * 64 + wc * 32 + 8 * fq; }
;                     if (rbj == bj) {
;                         const f32x4 c01 = cs0[ai][m], c23 = cs1[ai][m];
;                         f32x4 r0, r1;
;                         r0[0] = v0[0] * c01[0] - v0[1] * c01[1]; r0[1] = v0[0] * c01[1] + v0[1] * c01[0];
;                         r0[2] = v0[2] * c01[2] - v0[3] * c01[3]; r0[3] = v0[2] * c01[3] + v0[3] * c01[2];
;                         r1[0] = v1[0] * c23[0] - v1[1] * c23[1]; r1[1] = v1[0] * c23[1] + v1[1] * c23[0];
;                         r1[2] = v1[2] * c23[2] - v1[3] * c23[3]; r1[3] = v1[2] * c23[3] + v1[3] * c23[2];
;                         v0 = r0; v1 = r1;
;                     }
;                     if (st) { u32x4 w; w.x = cvt_pk_bf16(v0[0], v0[1]); w.y = cvt_pk_bf16(v0[2], v0[3]); w.z = cvt_pk_bf16(v1[0], v1[1]); w.w = cvt_pk_bf16(v1[2], v1[3]);
;                         *(u32x4*)dst = w; }
.LBB0_537:
	s_lshl_b32 s68, s57, 1
	v_lshl_add_u64 v[190:191], v[190:191], 0, s[68:69]
	v_lshl_add_u64 v[200:201], v[140:141], 1, v[190:191]
	v_cvt_pk_bf16_f32 v190, v192, v193
	v_cvt_pk_bf16_f32 v191, v198, v199
	v_cvt_pk_bf16_f32 v192, v194, v195
	v_cvt_pk_bf16_f32 v193, v196, v197
	global_store_dwordx4 v[200:201], v[190:193], off sc1
	s_and_b64 vcc, exec, s[4:5]
	s_cbranch_vccz .LBB0_522

; __device__ __forceinline__ unsigned cvt_pk_bf16(float lo, float hi) { unsigned r; asm volatile("v_cvt_pk_bf16_f32 %0, %1, %2" : "=v"(r) : "v"(lo), "v"(hi)); return r; }
;     __device__ __forceinline__ void operator()(Acc& acc, const Unit& u, int slot, int cslot, int wr, int wc, int fr, int fq, LAS unsigned char* lds) const {
;     ...
;                     bool st = true; bf16_t* dst;
;                     if (ty == 0) dst = Q + row * 1536 + pn * 256 + bj * HALF + wc * 32 + 8 * fq;
;                     else if (ty == 1) dst = KV + row * 2048 + pn * 256 + bj * HALF + wc * 32 + 8 * fq;
;                     else { st = (bj == 0 && wc < 2); dst = KPE + row * 64 + wc * 32 + 8 * fq; }
;                     if (rbj == bj) {
;                         const f32x4 c01 = cs0[ai][m], c23 = cs1[ai][m];
;                         f32x4 r0, r1;
;                         r0[0] = v0[0] * c01[0] - v0[1] * c01[1]; r0[1] = v0[0] * c01[1] + v0[1] * c01[0];
;                         r0[2] = v0[2] * c01[2] - v0[3] * c01[3]; r0[3] = v0[2] * c01[3] + v0[3] * c01[2];
;                         r1[0] = v1[0] * c23[0] - v1[1] * c23[1]; r1[1] = v1[0] * c23[1] + v1[1] * c23[0];
;                         r1[2] = v1[2] * c23[2] - v1[3] * c23[3]; r1[3] = v1[2] * c23[3] + v1[3] * c23[2];
;                         v0 = r0; v1 = r1;
;                     }
;                     if (st) { u32x4 w; w.x = cvt_pk_bf16(v0[0], v0[1]); w.y = cvt_pk_bf16(v0[2], v0[3]); w.z = cvt_pk_bf16(v1[0], v1[1]); w.w = cvt_pk_bf16(v1[2], v1[3]);
;                         *(u32x4*)dst = w; }
.LBB0_551:
	s_andn2_b64 vcc, exec, s[54:55]
	s_cbranch_vccnz .LBB0_553
	s_lshl_b32 s68, s57, 1
	v_lshl_add_u64 v[166:167], v[182:183], 0, s[68:69]
	v_lshl_add_u64 v[170:171], v[140:141], 1, v[166:167]
	v_cvt_pk_bf16_f32 v166, v176, v177
	v_cvt_pk_bf16_f32 v167, v180, v181
	v_cvt_pk_bf16_f32 v168, v174, v175
	v_cvt_pk_bf16_f32 v169, v178, v179
	global_store_dwordx4 v[170:171], v[166:169], off sc1

; __device__ __forceinline__ unsigned cvt_pk_bf16(float lo, float hi) { unsigned r; asm volatile("v_cvt_pk_bf16_f32 %0, %1, %2" : "=v"(r) : "v"(lo), "v"(hi)); return r; }
;     __device__ __forceinline__ void operator()(Acc& acc, const Unit& u, int slot, int cslot, int wr, int wc, int fr, int fq, LAS unsigned char* lds) const {
;     ...
;                     bool st = true; bf16_t* dst;
;                     if (ty == 0) dst = Q + row * 1536 + pn * 256 + bj * HALF + wc * 32 + 8 * fq;
;                     else if (ty == 1) dst = KV + row * 2048 + pn * 256 + bj * HALF + wc * 32 + 8 * fq;
;                     else { st = (bj == 0 && wc < 2); dst = KPE + row * 64 + wc * 32 + 8 * fq; }
;                     if (rbj == bj) {
;                         const f32x4 c01 = cs0[ai][m], c23 = cs1[ai][m];
;                         f32x4 r0, r1;
;                         r0[0] = v0[0] * c01[0] - v0[1] * c01[1]; r0[1] = v0[0] * c01[1] + v0[1] * c01[0];
;                         r0[2] = v0[2] * c01[2] - v0[3] * c01[3]; r0[3] = v0[2] * c01[3] + v0[3] * c01[2];
;                         r1[0] = v1[0] * c23[0] - v1[1] * c23[1]; r1[1] = v1[0] * c23[1] + v1[1] * c23[0];
;                         r1[2] = v1[2] * c23[2] - v1[3] * c23[3]; r1[3] = v1[2] * c23[3] + v1[3] * c23[2];
;                         v0 = r0; v1 = r1;
;                     }
;                     if (st) { u32x4 w; w.x = cvt_pk_bf16(v0[0], v0[1]); w.y = cvt_pk_bf16(v0[2], v0[3]); w.z = cvt_pk_bf16(v1[0], v1[1]); w.w = cvt_pk_bf16(v1[2], v1[3]);
;                         *(u32x4*)dst = w; }
.LBB0_560:
	s_lshl_b32 s68, s57, 1
	v_lshl_add_u64 v[182:183], v[182:183], 0, s[68:69]
	v_lshl_add_u64 v[192:193], v[140:141], 1, v[182:183]
	v_cvt_pk_bf16_f32 v182, v184, v185
	v_cvt_pk_bf16_f32 v183, v190, v191
	v_cvt_pk_bf16_f32 v184, v186, v187
	v_cvt_pk_bf16_f32 v185, v188, v189
	global_store_dwordx4 v[192:193], v[182:185], off sc1
	s_and_b64 vcc, exec, s[4:5]
	s_cbranch_vccz .LBB0_545

; __device__ __forceinline__ unsigned cvt_pk_bf16(float lo, float hi) { unsigned r; asm volatile("v_cvt_pk_bf16_f32 %0, %1, %2" : "=v"(r) : "v"(lo), "v"(hi)); return r; }
;     __device__ __forceinline__ void operator()(Acc& acc, const Unit& u, int slot, int cslot, int wr, int wc, int fr, int fq, LAS unsigned char* lds) const {
;     ...
;                     bool st = true; bf16_t* dst;
;                     if (ty == 0) dst = Q + row * 1536 + pn * 256 + bj * HALF + wc * 32 + 8 * fq;
;                     else if (ty == 1) dst = KV + row * 2048 + pn * 256 + bj * HALF + wc * 32 + 8 * fq;
;                     else { st = (bj == 0 && wc < 2); dst = KPE + row * 64 + wc * 32 + 8 * fq; }
;                     if (rbj == bj) {
;                         const f32x4 c01 = cs0[ai][m], c23 = cs1[ai][m];
;                         f32x4 r0, r1;
;                         r0[0] = v0[0] * c01[0] - v0[1] * c01[1]; r0[1] = v0[0] * c01[1] + v0[1] * c01[0];
;                         r0[2] = v0[2] * c01[2] - v0[3] * c01[3]; r0[3] = v0[2] * c01[3] + v0[3] * c01[2];
;                         r1[0] = v1[0] * c23[0] - v1[1] * c23[1]; r1[1] = v1[0] * c23[1] + v1[1] * c23[0];
;                         r1[2] = v1[2] * c23[2] - v1[3] * c23[3]; r1[3] = v1[2] * c23[3] + v1[3] * c23[2];
;                         v0 = r0; v1 = r1;
;                     }
;                     if (st) { u32x4 w; w.x = cvt_pk_bf16(v0[0], v0[1]); w.y = cvt_pk_bf16(v0[2], v0[3]); w.z = cvt_pk_bf16(v1[0], v1[1]); w.w = cvt_pk_bf16(v1[2], v1[3]);
;                         *(u32x4*)dst = w; }
.LBB0_574:
	s_andn2_b64 vcc, exec, s[54:55]
	s_cbranch_vccnz .LBB0_576
	s_lshl_b32 s68, s57, 1
	v_lshl_add_u64 v[158:159], v[174:175], 0, s[68:69]
	v_lshl_add_u64 v[162:163], v[140:141], 1, v[158:159]
	v_cvt_pk_bf16_f32 v158, v168, v169
	v_cvt_pk_bf16_f32 v159, v172, v173
	v_cvt_pk_bf16_f32 v160, v166, v167
	v_cvt_pk_bf16_f32 v161, v170, v171
	global_store_dwordx4 v[162:163], v[158:161], off sc1

; __device__ __forceinline__ unsigned cvt_pk_bf16(float lo, float hi) { unsigned r; asm volatile("v_cvt_pk_bf16_f32 %0, %1, %2" : "=v"(r) : "v"(lo), "v"(hi)); return r; }
;     __device__ __forceinline__ void operator()(Acc& acc, const Unit& u, int slot, int cslot, int wr, int wc, int fr, int fq, LAS unsigned char* lds) const {
;     ...
;                     bool st = true; bf16_t* dst;
;                     if (ty == 0) dst = Q + row * 1536 + pn * 256 + bj * HALF + wc * 32 + 8 * fq;
;                     else if (ty == 1) dst = KV + row * 2048 + pn * 256 + bj * HALF + wc * 32 + 8 * fq;
;                     else { st = (bj == 0 && wc < 2); dst = KPE + row * 64 + wc * 32 + 8 * fq; }
;                     if (rbj == bj) {
;                         const f32x4 c01 = cs0[ai][m], c23 = cs1[ai][m];
;                         f32x4 r0, r1;
;                         r0[0] = v0[0] * c01[0] - v0[1] * c01[1]; r0[1] = v0[0] * c01[1] + v0[1] * c01[0];
;                         r0[2] = v0[2] * c01[2] - v0[3] * c01[3]; r0[3] = v0[2] * c01[3] + v0[3] * c01[2];
;                         r1[0] = v1[0] * c23[0] - v1[1] * c23[1]; r1[1] = v1[0] * c23[1] + v1[1] * c23[0];
;                         r1[2] = v1[2] * c23[2] - v1[3] * c23[3]; r1[3] = v1[2] * c23[3] + v1[3] * c23[2];
;                         v0 = r0; v1 = r1;
;                     }
;                     if (st) { u32x4 w; w.x = cvt_pk_bf16(v0[0], v0[1]); w.y = cvt_pk_bf16(v0[2], v0[3]); w.z = cvt_pk_bf16(v1[0], v1[1]); w.w = cvt_pk_bf16(v1[2], v1[3]);
;                         *(u32x4*)dst = w; }
.LBB0_583:
	s_lshl_b32 s68, s57, 1
	v_lshl_add_u64 v[174:175], v[174:175], 0, s[68:69]
	v_lshl_add_u64 v[184:185], v[140:141], 1, v[174:175]
	v_cvt_pk_bf16_f32 v174, v176, v177
	v_cvt_pk_bf16_f32 v175, v182, v183
	v_cvt_pk_bf16_f32 v176, v178, v179
	v_cvt_pk_bf16_f32 v177, v180, v181
	global_store_dwordx4 v[184:185], v[174:177], off sc1
	s_and_b64 vcc, exec, s[4:5]
	s_cbranch_vccz .LBB0_568

; __device__ __forceinline__ unsigned cvt_pk_bf16(float lo, float hi) { unsigned r; asm volatile("v_cvt_pk_bf16_f32 %0, %1, %2" : "=v"(r) : "v"(lo), "v"(hi)); return r; }
;     __device__ __forceinline__ void operator()(Acc& acc, const Unit& u, int slot, int cslot, int wr, int wc, int fr, int fq, LAS unsigned char* lds) const {
;     ...
;                     bool st = true; bf16_t* dst;
;                     if (ty == 0) dst = Q + row * 1536 + pn * 256 + bj * HALF + wc * 32 + 8 * fq;
;                     else if (ty == 1) dst = KV + row * 2048 + pn * 256 + bj * HALF + wc * 32 + 8 * fq;
;                     else { st = (bj == 0 && wc < 2); dst = KPE + row * 64 + wc * 32 + 8 * fq; }
;                     if (rbj == bj) {
;                         const f32x4 c01 = cs0[ai][m], c23 = cs1[ai][m];
;                         f32x4 r0, r1;
;                         r0[0] = v0[0] * c01[0] - v0[1] * c01[1]; r0[1] = v0[0] * c01[1] + v0[1] * c01[0];
;                         r0[2] = v0[2] * c01[2] - v0[3] * c01[3]; r0[3] = v0[2] * c01[3] + v0[3] * c01[2];
;                         r1[0] = v1[0] * c23[0] - v1[1] * c23[1]; r1[1] = v1[0] * c23[1] + v1[1] * c23[0];
;                         r1[2] = v1[2] * c23[2] - v1[3] * c23[3]; r1[3] = v1[2] * c23[3] + v1[3] * c23[2];
;                         v0 = r0; v1 = r1;
;                     }
;                     if (st) { u32x4 w; w.x = cvt_pk_bf16(v0[0], v0[1]); w.y = cvt_pk_bf16(v0[2], v0[3]); w.z = cvt_pk_bf16(v1[0], v1[1]); w.w = cvt_pk_bf16(v1[2], v1[3]);
;                         *(u32x4*)dst = w; }
.LBB0_597:
	s_andn2_b64 vcc, exec, s[54:55]
	s_cbranch_vccnz .LBB0_599
	s_lshl_b32 s68, s57, 1
	v_lshl_add_u64 v[150:151], v[166:167], 0, s[68:69]
	v_lshl_add_u64 v[154:155], v[140:141], 1, v[150:151]
	v_cvt_pk_bf16_f32 v150, v160, v161
	v_cvt_pk_bf16_f32 v151, v164, v165
	v_cvt_pk_bf16_f32 v152, v158, v159
	v_cvt_pk_bf16_f32 v153, v162, v163
	global_store_dwordx4 v[154:155], v[150:153], off sc1

; __device__ __forceinline__ unsigned cvt_pk_bf16(float lo, float hi) { unsigned r; asm volatile("v_cvt_pk_bf16_f32 %0, %1, %2" : "=v"(r) : "v"(lo), "v"(hi)); return r; }
;     __device__ __forceinline__ void operator()(Acc& acc, const Unit& u, int slot, int cslot, int wr, int wc, int fr, int fq, LAS unsigned char* lds) const {
;     ...
;                     bool st = true; bf16_t* dst;
;                     if (ty == 0) dst = Q + row * 1536 + pn * 256 + bj * HALF + wc * 32 + 8 * fq;
;                     else if (ty == 1) dst = KV + row * 2048 + pn * 256 + bj * HALF + wc * 32 + 8 * fq;
;                     else { st = (bj == 0 && wc < 2); dst = KPE + row * 64 + wc * 32 + 8 * fq; }
;                     if (rbj == bj) {
;                         const f32x4 c01 = cs0[ai][m], c23 = cs1[ai][m];
;                         f32x4 r0, r1;
;                         r0[0] = v0[0] * c01[0] - v0[1] * c01[1]; r0[1] = v0[0] * c01[1] + v0[1] * c01[0];
;                         r0[2] = v0[2] * c01[2] - v0[3] * c01[3]; r0[3] = v0[2] * c01[3] + v0[3] * c01[2];
;                         r1[0] = v1[0] * c23[0] - v1[1] * c23[1]; r1[1] = v1[0] * c23[1] + v1[1] * c23[0];
;                         r1[2] = v1[2] * c23[2] - v1[3] * c23[3]; r1[3] = v1[2] * c23[3] + v1[3] * c23[2];
;                         v0 = r0; v1 = r1;
;                     }
;                     if (st) { u32x4 w; w.x = cvt_pk_bf16(v0[0], v0[1]); w.y = cvt_pk_bf16(v0[2], v0[3]); w.z = cvt_pk_bf16(v1[0], v1[1]); w.w = cvt_pk_bf16(v1[2], v1[3]);
;                         *(u32x4*)dst = w; }
.LBB0_606:
	s_lshl_b32 s68, s57, 1
	v_lshl_add_u64 v[166:167], v[166:167], 0, s[68:69]
	v_lshl_add_u64 v[176:177], v[140:141], 1, v[166:167]
	v_cvt_pk_bf16_f32 v166, v168, v169
	v_cvt_pk_bf16_f32 v167, v174, v175
	v_cvt_pk_bf16_f32 v168, v170, v171
	v_cvt_pk_bf16_f32 v169, v172, v173
	global_store_dwordx4 v[176:177], v[166:169], off sc1
	s_and_b64 vcc, exec, s[4:5]
	s_cbranch_vccz .LBB0_591

; __device__ __forceinline__ unsigned cvt_pk_bf16(float lo, float hi) { unsigned r; asm volatile("v_cvt_pk_bf16_f32 %0, %1, %2" : "=v"(r) : "v"(lo), "v"(hi)); return r; }
;     __device__ __forceinline__ void operator()(Acc& acc, const Unit& u, int slot, int cslot, int wr, int wc, int fr, int fq, LAS unsigned char* lds) const {
;     ...
;                     bool st = true; bf16_t* dst;
;                     if (ty == 0) dst = Q + row * 1536 + pn * 256 + bj * HALF + wc * 32 + 8 * fq;
;                     else if (ty == 1) dst = KV + row * 2048 + pn * 256 + bj * HALF + wc * 32 + 8 * fq;
;                     else { st = (bj == 0 && wc < 2); dst = KPE + row * 64 + wc * 32 + 8 * fq; }
;                     if (rbj == bj) {
;                         const f32x4 c01 = cs0[ai][m], c23 = cs1[ai][m];
;                         f32x4 r0, r1;
;                         r0[0] = v0[0] * c01[0] - v0[1] * c01[1]; r0[1] = v0[0] * c01[1] + v0[1] * c01[0];
;                         r0[2] = v0[2] * c01[2] - v0[3] * c01[3]; r0[3] = v0[2] * c01[3] + v0[3] * c01[2];
;                         r1[0] = v1[0] * c23[0] - v1[1] * c23[1]; r1[1] = v1[0] * c23[1] + v1[1] * c23[0];
;                         r1[2] = v1[2] * c23[2] - v1[3] * c23[3]; r1[3] = v1[2] * c23[3] + v1[3] * c23[2];
;                         v0 = r0; v1 = r1;
;                     }
;                     if (st) { u32x4 w; w.x = cvt_pk_bf16(v0[0], v0[1]); w.y = cvt_pk_bf16(v0[2], v0[3]); w.z = cvt_pk_bf16(v1[0], v1[1]); w.w = cvt_pk_bf16(v1[2], v1[3]);
;                         *(u32x4*)dst = w; }
.LBB0_620:
	s_andn2_b64 vcc, exec, s[54:55]
	s_cbranch_vccnz .LBB0_622
	s_lshl_b32 s68, s57, 1
	v_lshl_add_u64 v[142:143], v[158:159], 0, s[68:69]
	v_lshl_add_u64 v[146:147], v[140:141], 1, v[142:143]
	v_cvt_pk_bf16_f32 v142, v152, v153
	v_cvt_pk_bf16_f32 v143, v156, v157
	v_cvt_pk_bf16_f32 v144, v150, v151
	v_cvt_pk_bf16_f32 v145, v154, v155
	global_store_dwordx4 v[146:147], v[142:145], off sc1

; __device__ __forceinline__ unsigned cvt_pk_bf16(float lo, float hi) { unsigned r; asm volatile("v_cvt_pk_bf16_f32 %0, %1, %2" : "=v"(r) : "v"(lo), "v"(hi)); return r; }
;     __device__ __forceinline__ void operator()(Acc& acc, const Unit& u, int slot, int cslot, int wr, int wc, int fr, int fq, LAS unsigned char* lds) const {
;     ...
;                     bool st = true; bf16_t* dst;
;                     if (ty == 0) dst = Q + row * 1536 + pn * 256 + bj * HALF + wc * 32 + 8 * fq;
;                     else if (ty == 1) dst = KV + row * 2048 + pn * 256 + bj * HALF + wc * 32 + 8 * fq;
;                     else { st = (bj == 0 && wc < 2); dst = KPE + row * 64 + wc * 32 + 8 * fq; }
;                     if (rbj == bj) {
;                         const f32x4 c01 = cs0[ai][m], c23 = cs1[ai][m];
;                         f32x4 r0, r1;
;                         r0[0] = v0[0] * c01[0] - v0[1] * c01[1]; r0[1] = v0[0] * c01[1] + v0[1] * c01[0];
;                         r0[2] = v0[2] * c01[2] - v0[3] * c01[3]; r0[3] = v0[2] * c01[3] + v0[3] * c01[2];
;                         r1[0] = v1[0] * c23[0] - v1[1] * c23[1]; r1[1] = v1[0] * c23[1] + v1[1] * c23[0];
;                         r1[2] = v1[2] * c23[2] - v1[3] * c23[3]; r1[3] = v1[2] * c23[3] + v1[3] * c23[2];
;                         v0 = r0; v1 = r1;
;                     }
;                     if (st) { u32x4 w; w.x = cvt_pk_bf16(v0[0], v0[1]); w.y = cvt_pk_bf16(v0[2], v0[3]); w.z = cvt_pk_bf16(v1[0], v1[1]); w.w = cvt_pk_bf16(v1[2], v1[3]);
;                         *(u32x4*)dst = w; }
.LBB0_629:
	s_lshl_b32 s68, s57, 1
	v_lshl_add_u64 v[158:159], v[158:159], 0, s[68:69]
	v_lshl_add_u64 v[168:169], v[140:141], 1, v[158:159]
	v_cvt_pk_bf16_f32 v158, v160, v161
	v_cvt_pk_bf16_f32 v159, v166, v167
	v_cvt_pk_bf16_f32 v160, v162, v163
	v_cvt_pk_bf16_f32 v161, v164, v165
	global_store_dwordx4 v[168:169], v[158:161], off sc1
	s_and_b64 vcc, exec, s[4:5]
	s_cbranch_vccz .LBB0_614

; __device__ __forceinline__ unsigned cvt_pk_bf16(float lo, float hi) { unsigned r; asm volatile("v_cvt_pk_bf16_f32 %0, %1, %2" : "=v"(r) : "v"(lo), "v"(hi)); return r; }
;     __device__ __forceinline__ void operator()(Acc& acc, const Unit& u, int slot, int cslot, int wr, int wc, int fr, int fq, LAS unsigned char* lds) const {
;     ...
;                     bool st = true; bf16_t* dst;
;                     if (ty == 0) dst = Q + row * 1536 + pn * 256 + bj * HALF + wc * 32 + 8 * fq;
;                     else if (ty == 1) dst = KV + row * 2048 + pn * 256 + bj * HALF + wc * 32 + 8 * fq;
;                     else { st = (bj == 0 && wc < 2); dst = KPE + row * 64 + wc * 32 + 8 * fq; }
;                     if (rbj == bj) {
;                         const f32x4 c01 = cs0[ai][m], c23 = cs1[ai][m];
;                         f32x4 r0, r1;
;                         r0[0] = v0[0] * c01[0] - v0[1] * c01[1]; r0[1] = v0[0] * c01[1] + v0[1] * c01[0];
;                         r0[2] = v0[2] * c01[2] - v0[3] * c01[3]; r0[3] = v0[2] * c01[3] + v0[3] * c01[2];
;                         r1[0] = v1[0] * c23[0] - v1[1] * c23[1]; r1[1] = v1[0] * c23[1] + v1[1] * c23[0];
;                         r1[2] = v1[2] * c23[2] - v1[3] * c23[3]; r1[3] = v1[2] * c23[3] + v1[3] * c23[2];
;                         v0 = r0; v1 = r1;
;                     }
;                     if (st) { u32x4 w; w.x = cvt_pk_bf16(v0[0], v0[1]); w.y = cvt_pk_bf16(v0[2], v0[3]); w.z = cvt_pk_bf16(v1[0], v1[1]); w.w = cvt_pk_bf16(v1[2], v1[3]);
;                         *(u32x4*)dst = w; }
.LBB0_650:
	s_lshl_b32 s68, s57, 1
	v_lshl_add_u64 v[132:133], v[150:151], 0, s[68:69]
	v_lshl_add_u64 v[136:137], v[140:141], 1, v[132:133]
	v_cvt_pk_bf16_f32 v132, v144, v145
	v_cvt_pk_bf16_f32 v133, v148, v149
	v_cvt_pk_bf16_f32 v134, v142, v143
	v_cvt_pk_bf16_f32 v135, v146, v147
	global_store_dwordx4 v[136:137], v[132:135], off sc1
	s_andn2_b64 vcc, exec, s[92:93]
	s_cbranch_vccz .LBB0_644

; __device__ __forceinline__ unsigned cvt_pk_bf16(float lo, float hi) { unsigned r; asm volatile("v_cvt_pk_bf16_f32 %0, %1, %2" : "=v"(r) : "v"(lo), "v"(hi)); return r; }
;     __device__ __forceinline__ void operator()(Acc& acc, const Unit& u, int slot, int cslot, int wr, int wc, int fr, int fq, LAS unsigned char* lds) const {
;     ...
;                     bool st = true; bf16_t* dst;
;                     if (ty == 0) dst = Q + row * 1536 + pn * 256 + bj * HALF + wc * 32 + 8 * fq;
;                     else if (ty == 1) dst = KV + row * 2048 + pn * 256 + bj * HALF + wc * 32 + 8 * fq;
;                     else { st = (bj == 0 && wc < 2); dst = KPE + row * 64 + wc * 32 + 8 * fq; }
;                     if (rbj == bj) {
;                         const f32x4 c01 = cs0[ai][m], c23 = cs1[ai][m];
;                         f32x4 r0, r1;
;                         r0[0] = v0[0] * c01[0] - v0[1] * c01[1]; r0[1] = v0[0] * c01[1] + v0[1] * c01[0];
;                         r0[2] = v0[2] * c01[2] - v0[3] * c01[3]; r0[3] = v0[2] * c01[3] + v0[3] * c01[2];
;                         r1[0] = v1[0] * c23[0] - v1[1] * c23[1]; r1[1] = v1[0] * c23[1] + v1[1] * c23[0];
;                         r1[2] = v1[2] * c23[2] - v1[3] * c23[3]; r1[3] = v1[2] * c23[3] + v1[3] * c23[2];
;                         v0 = r0; v1 = r1;
;                     }
;                     if (st) { u32x4 w; w.x = cvt_pk_bf16(v0[0], v0[1]); w.y = cvt_pk_bf16(v0[2], v0[3]); w.z = cvt_pk_bf16(v1[0], v1[1]); w.w = cvt_pk_bf16(v1[2], v1[3]);
;                         *(u32x4*)dst = w; }
.LBB0_653:
	s_lshl_b32 s68, s57, 1
	v_lshl_add_u64 v[150:151], v[150:151], 0, s[68:69]
	v_lshl_add_u64 v[160:161], v[140:141], 1, v[150:151]
	v_cvt_pk_bf16_f32 v150, v152, v153
	v_cvt_pk_bf16_f32 v151, v158, v159
	v_cvt_pk_bf16_f32 v152, v154, v155
	v_cvt_pk_bf16_f32 v153, v156, v157
	global_store_dwordx4 v[160:161], v[150:153], off sc1
	s_and_b64 vcc, exec, s[4:5]
	s_cbranch_vccz .LBB0_637

; __device__ __forceinline__ float bf_lo(unsigned w) { return __uint_as_float(w << 16); }
; __device__ __forceinline__ float bf_hi(unsigned w) { return __uint_as_float(w & 0xffff0000u); }
; __global__ void __launch_bounds__(512, 2) hymba_fwd(Args args) {
;     ...
;                 const int row0 = rb * 8, t0 = row0 & (SEQ - 1);
; #pragma unroll 1
;                 for (int hb = 0; hb < 2; ++hb) {
;                     const int rw0 = row0 + 4 * hb, tt0 = t0 + 4 * hb;
;                     u32x4 chr[6][2], gbr[4][2];
; #pragma unroll
;                     for (int r = 0; r < 6; ++r) { const bool ok = !((r == 0 && tt0 == 0) || (r == 5 && tt0 + 4 == SEQ));
;                         const u32x4* ch = (const u32x4*)(Gb + (size_t)(ok ? rw0 - 1 + r : rw0) * 2048 + 1024 + col0);
;                         chr[r][0] = ch[0]; chr[r][1] = ch[1];
;                         if (!ok) { chr[r][0] = (u32x4){0u, 0u, 0u, 0u}; chr[r][1] = (u32x4){0u, 0u, 0u, 0u}; } }
; #pragma unroll
;                     for (int r = 0; r < 4; ++r) { const u32x4* gbp = (const u32x4*)(Gb + (size_t)(rw0 + r) * 2048 + col0); gbr[r][0] = gbp[0]; gbr[r][1] = gbp[1]; }
; #pragma unroll
;                     for (int r = 0; r < 4; ++r) {
;                         const int row = rw0 + r;
;                         float y[16]; float ss = 0.f;
; #pragma unroll
;                         for (int q = 0; q < 2; ++q) { const u32x4 a = gbr[r][q], pu = chr[r][q], pc = chr[r + 1][q], pd = chr[r + 2][q];
; #pragma unroll
;                             for (int e = 0; e < 4; ++e) {
;                                 const int i0 = q * 8 + 2 * e, i1 = i0 + 1;
;                                 const float c0 = w0[i0 >> 2][i0 & 3] * bf_lo(pu[e]) + w1[i0 >> 2][i0 & 3] * bf_lo(pc[e]) + w2[i0 >> 2][i0 & 3] * bf_lo(pd[e]);
;                                 const float c1 = w0[i1 >> 2][i1 & 3] * bf_hi(pu[e]) + w1[i1 >> 2][i1 & 3] * bf_hi(pc[e]) + w2[i1 >> 2][i1 & 3] * bf_hi(pd[e]);
;                                 y[i0] = bf_lo(a[e]) * c0; y[i1] = bf_hi(a[e]) * c1; ss += y[i0] * y[i0] + y[i1] * y[i1]; } }
.LBB0_741:
	s_or_b32 s42, s46, s44
	s_or_b32 s40, s46, s45
	s_cmp_lg_u32 s40, 0
	v_cndmask_b32_e64 v50, 0, 1, s[0:1]
	s_cselect_b64 s[0:1], -1, 0
	s_cmp_lg_u64 s[0:1], 0
	s_subb_u32 s6, s42, 0
	s_ashr_i32 s7, s6, 31
	s_lshl_b64 s[48:49], s[6:7], 12
	v_lshl_add_u64 v[54:55], v[110:111], 0, s[48:49]
	v_cmp_ne_u32_e32 vcc, 1, v50
	global_load_dwordx4 v[50:53], v[54:55], off offset:2064
	s_nop 0
	global_load_dwordx4 v[54:57], v[54:55], off offset:2048
	s_or_b32 s6, s42, 1
	s_ashr_i32 s7, s6, 31
	s_lshl_b64 s[10:11], s[6:7], 12
	s_or_b32 s6, s42, 2
	s_ashr_i32 s7, s6, 31
	s_lshl_b64 s[8:9], s[6:7], 12
	s_or_b32 s6, s42, 3
	s_ashr_i32 s43, s42, 31
	s_ashr_i32 s7, s6, 31
	s_lshl_b64 s[38:39], s[42:43], 12
	s_lshl_b64 s[6:7], s[6:7], 12
	s_add_i32 s43, s42, 4
	s_cmpk_eq_i32 s40, 0xffc
	s_cselect_b64 s[40:41], -1, 0
	s_and_b64 s[50:51], s[40:41], exec
	s_cselect_b32 s42, s42, s43
	s_ashr_i32 s43, s42, 31
	s_lshl_b64 s[42:43], s[42:43], 12
	v_lshl_add_u64 v[66:67], v[110:111], 0, s[38:39]
	v_lshl_add_u64 v[68:69], v[110:111], 0, s[10:11]
	v_lshl_add_u64 v[70:71], v[110:111], 0, s[8:9]
	v_lshl_add_u64 v[162:163], v[110:111], 0, s[6:7]
	v_lshl_add_u64 v[58:59], v[110:111], 0, s[42:43]
	global_load_dwordx4 v[78:81], v[66:67], off offset:2064
	global_load_dwordx4 v[90:93], v[66:67], off offset:2048
	global_load_dwordx4 v[102:105], v[68:69], off offset:2064
	global_load_dwordx4 v[106:109], v[68:69], off offset:2048
	global_load_dwordx4 v[86:89], v[70:71], off offset:2064
	global_load_dwordx4 v[94:97], v[70:71], off offset:2048
	s_mov_b32 s46, 4
	s_and_b64 vcc, exec, vcc
	s_waitcnt vmcnt(7)
	v_cndmask_b32_e64 v192, 0, v53, s[0:1]
	s_waitcnt vmcnt(6)
	v_cndmask_b32_e64 v170, 0, v57, s[0:1]
	v_cndmask_b32_e64 v164, 0, v56, s[0:1]
	v_cndmask_b32_e64 v165, 0, v55, s[0:1]
	v_cndmask_b32_e64 v171, 0, v54, s[0:1]
	v_cndmask_b32_e64 v193, 0, v52, s[0:1]
	v_cndmask_b32_e64 v198, 0, v51, s[0:1]
	v_cndmask_b32_e64 v172, 0, v50, s[0:1]
	global_load_dwordx4 v[54:57], v[162:163], off offset:2064
	global_load_dwordx4 v[62:65], v[162:163], off offset:2048
	global_load_dwordx4 v[50:53], v[58:59], off offset:2064
	s_nop 0
	global_load_dwordx4 v[58:61], v[58:59], off offset:2048
	v_lshlrev_b32_e32 v186, 16, v171
	v_lshlrev_b32_e32 v182, 16, v165
	v_and_b32_e32 v180, 0xffff0000, v165
	v_and_b32_e32 v184, 0xffff0000, v171
	v_lshlrev_b32_e32 v174, 16, v164
	v_lshlrev_b32_e32 v176, 16, v170
	v_and_b32_e32 v164, 0xffff0000, v164
	v_lshlrev_b32_e32 v178, 16, v172
	v_and_b32_e32 v172, 0xffff0000, v172
	s_waitcnt vmcnt(7)
	v_lshlrev_b32_e32 v179, 16, v102
	s_waitcnt vmcnt(6)
	v_lshlrev_b32_e32 v187, 16, v106
	v_pk_mul_f32 v[190:191], v[140:141], v[186:187]
	v_and_b32_e32 v185, 0xffff0000, v106
	v_lshlrev_b32_e32 v183, 16, v107
	v_and_b32_e32 v173, 0xffff0000, v102
	v_lshlrev_b32_e32 v106, 16, v192
	v_and_b32_e32 v102, 0xffff0000, v192
	v_lshlrev_b32_e32 v192, 16, v90
	v_pk_mul_f32 v[222:223], v[136:137], v[182:183]
	v_lshlrev_b32_e32 v177, 16, v109
	v_lshlrev_b32_e32 v175, 16, v108
	v_and_b32_e32 v165, 0xffff0000, v108
	v_and_b32_e32 v108, 0xffff0000, v193
	v_and_b32_e32 v181, 0xffff0000, v107
	v_lshlrev_b32_e32 v171, 16, v103
	v_lshlrev_b32_e32 v107, 16, v105
	v_pk_mul_f32 v[218:219], v[132:133], v[174:175]
	v_pk_mul_f32 v[188:189], v[142:143], v[184:185]
	v_pk_mul_f32 v[216:217], v[128:129], v[176:177]
	v_pk_mul_f32 v[220:221], v[138:139], v[180:181]
	v_pk_mul_f32 v[194:195], v[134:135], v[164:165]
	v_pk_mul_f32 v[210:211], v[124:125], v[178:179]
	v_pk_mul_f32 v[208:209], v[126:127], v[172:173]
	v_pk_mul_f32 v[206:207], v[112:113], v[106:107]
	s_waitcnt vmcnt(1)
	v_cndmask_b32_e64 v232, v53, 0, s[40:41]
	s_waitcnt vmcnt(0)
	v_cndmask_b32_e64 v236, v61, 0, s[40:41]
	v_cndmask_b32_e64 v237, v60, 0, s[40:41]
	v_cndmask_b32_e64 v238, v59, 0, s[40:41]
	v_cndmask_b32_e64 v239, v58, 0, s[40:41]
	v_cndmask_b32_e64 v233, v52, 0, s[40:41]
	v_cndmask_b32_e64 v234, v51, 0, s[40:41]
	v_cndmask_b32_e64 v235, v50, 0, s[40:41]
	global_load_dwordx4 v[82:85], v[66:67], off offset:16
	global_load_dwordx4 v[166:169], v[66:67], off
	global_load_dwordx4 v[74:77], v[68:69], off offset:16
	global_load_dwordx4 v[98:101], v[68:69], off
	global_load_dwordx4 v[58:61], v[70:71], off offset:16
	s_nop 0
	global_load_dwordx4 v[70:73], v[70:71], off
	s_nop 0
	global_load_dwordx4 v[50:53], v[162:163], off offset:16
	global_load_dwordx4 v[66:69], v[162:163], off
	v_lshlrev_b32_e32 v163, 16, v104
	v_lshlrev_b32_e32 v162, 16, v193
	v_lshlrev_b32_e32 v193, 16, v94
	v_pk_mul_f32 v[202:203], v[116:117], v[162:163]
	s_waitcnt vmcnt(6)
	v_lshlrev_b32_e32 v182, 16, v167
	v_and_b32_e32 v242, 0xffff0000, v167
	v_and_b32_e32 v167, 0xffff0000, v109
	v_and_b32_e32 v109, 0xffff0000, v104
	v_fma_f32 v104, v46, v192, v190
	v_lshlrev_b32_e32 v186, 16, v166
	v_add_f32_e32 v104, v104, v191
	v_lshlrev_b32_e32 v245, 16, v169
	v_and_b32_e32 v246, 0xffff0000, v169
	v_and_b32_e32 v169, 0xffff0000, v103
	v_and_b32_e32 v103, 0xffff0000, v105
	v_mul_f32_e32 v240, v104, v186
	v_pk_mul_f32 v[104:105], v[140:141], v[192:193]
	v_and_b32_e32 v191, 0xffff0000, v94
	v_fma_f32 v104, v46, v187, v104
	v_and_b32_e32 v190, 0xffff0000, v90
	v_add_f32_e32 v174, v104, v105
	v_pk_mul_f32 v[104:105], v[142:143], v[190:191]
	v_fma_f32 v90, v47, v190, v188
	v_fma_f32 v94, v47, v185, v104
	v_add_f32_e32 v94, v94, v105
	s_waitcnt vmcnt(4)
; __device__ __forceinline__ float bf_lo(unsigned w) { return __uint_as_float(w << 16); }
; __device__ __forceinline__ float bf_hi(unsigned w) { return __uint_as_float(w & 0xffff0000u); }
; __global__ void __launch_bounds__(512, 2) hymba_fwd(Args args) {
;     ...
;                         for (int q = 0; q < 2; ++q) { const u32x4 a = gbr[r][q], pu = chr[r][q], pc = chr[r + 1][q], pd = chr[r + 2][q];
; #pragma unroll
;                             for (int e = 0; e < 4; ++e) {
;                                 const int i0 = q * 8 + 2 * e, i1 = i0 + 1;
;                                 const float c0 = w0[i0 >> 2][i0 & 3] * bf_lo(pu[e]) + w1[i0 >> 2][i0 & 3] * bf_lo(pc[e]) + w2[i0 >> 2][i0 & 3] * bf_lo(pd[e]);
;                                 const float c1 = w0[i1 >> 2][i1 & 3] * bf_hi(pu[e]) + w1[i1 >> 2][i1 & 3] * bf_hi(pc[e]) + w2[i1 >> 2][i1 & 3] * bf_hi(pd[e]);
;                                 y[i0] = bf_lo(a[e]) * c0; y[i1] = bf_hi(a[e]) * c1; ss += y[i0] * y[i0] + y[i1] * y[i1]; } }
;                         ss = wave_sum(ss); const float rstd = rsqrtf(ss * (1.f / 1024.f) + EPS);
	v_lshlrev_b32_e32 v104, 16, v98
	v_and_b32_e32 v98, 0xffff0000, v98
	v_lshlrev_b32_e32 v188, 16, v91
	v_add_f32_e32 v90, v90, v189
	v_mul_f32_e32 v176, v94, v98
	v_lshlrev_b32_e32 v189, 16, v95
	v_fma_f32 v98, v48, v188, v222
	v_mul_f32_e32 v174, v174, v104
	v_add_f32_e32 v98, v98, v223
	v_pk_mul_f32 v[104:105], v[136:137], v[188:189]
	v_mul_f32_e32 v190, v98, v182
	v_fma_f32 v98, v48, v183, v104
	v_and_b32_e32 v104, 0xffff0000, v91
	v_fma_f32 v91, v49, v104, v220
	v_and_b32_e32 v241, 0xffff0000, v166
	v_add_f32_e32 v91, v91, v221
	v_mul_f32_e32 v192, v90, v241
	v_mul_f32_e32 v188, v91, v242
	v_mul_f32_e32 v90, v192, v192
	v_mul_f32_e32 v91, v188, v188
	v_fmac_f32_e32 v90, v240, v240
	v_add_f32_e32 v98, v98, v105
	v_and_b32_e32 v105, 0xffff0000, v95
	v_fmac_f32_e32 v91, v190, v190
	v_add_f32_e32 v186, v90, v91
	v_pk_mul_f32 v[90:91], v[138:139], v[104:105]
	v_mul_f32_e32 v94, v176, v176
	v_fma_f32 v90, v49, v181, v90
	v_add_f32_e32 v90, v90, v91
	v_lshlrev_b32_e32 v91, 16, v99
	v_mul_f32_e32 v104, v98, v91
	v_and_b32_e32 v91, 0xffff0000, v99
	v_mul_f32_e32 v182, v90, v91
	v_mul_f32_e32 v90, v182, v182
	v_fmac_f32_e32 v94, v174, v174
	v_fmac_f32_e32 v90, v104, v104
	v_lshlrev_b32_e32 v98, 16, v92
	v_add_f32_e32 v220, v94, v90
	v_fma_f32 v90, v42, v98, v218
	v_lshlrev_b32_e32 v243, 16, v168
	v_lshlrev_b32_e32 v99, 16, v96
	v_add_f32_e32 v90, v90, v219
	v_mul_f32_e32 v218, v90, v243
	v_pk_mul_f32 v[90:91], v[132:133], v[98:99]
	v_and_b32_e32 v94, 0xffff0000, v92
	v_fma_f32 v90, v42, v175, v90
	v_add_f32_e32 v98, v90, v91
	v_fma_f32 v90, v43, v94, v194
	v_and_b32_e32 v244, 0xffff0000, v168
	v_add_f32_e32 v90, v90, v195
	v_mul_f32_e32 v219, v90, v244
	v_mul_f32_e32 v90, v219, v219
	v_and_b32_e32 v95, 0xffff0000, v96
	v_fmac_f32_e32 v90, v218, v218
	v_add_f32_e32 v92, v186, v90
	v_pk_mul_f32 v[90:91], v[134:135], v[94:95]
	v_lshlrev_b32_e32 v194, 16, v93
	v_fma_f32 v90, v43, v165, v90
	v_add_f32_e32 v90, v90, v91
	v_lshlrev_b32_e32 v91, 16, v100
	v_mul_f32_e32 v94, v98, v91
	v_and_b32_e32 v91, 0xffff0000, v100
	v_mul_f32_e32 v98, v90, v91
	v_mul_f32_e32 v90, v98, v98
	v_fmac_f32_e32 v90, v94, v94
	v_add_f32_e32 v100, v220, v90
	v_fma_f32 v90, v44, v194, v216
	v_lshlrev_b32_e32 v195, 16, v97
	v_add_f32_e32 v90, v90, v217
	v_and_b32_e32 v166, 0xffff0000, v170
	v_mul_f32_e32 v241, v90, v245
	v_pk_mul_f32 v[90:91], v[128:129], v[194:195]
	v_pk_mul_f32 v[196:197], v[130:131], v[166:167]
	v_fma_f32 v90, v44, v177, v90
	v_and_b32_e32 v96, 0xffff0000, v93
	v_add_f32_e32 v186, v90, v91
	v_fma_f32 v90, v45, v96, v196
	v_add_f32_e32 v90, v90, v197
	v_mul_f32_e32 v194, v90, v246
	v_mul_f32_e32 v90, v194, v194
	v_and_b32_e32 v97, 0xffff0000, v97
	v_fmac_f32_e32 v90, v241, v241
	v_add_f32_e32 v244, v92, v90
	v_pk_mul_f32 v[90:91], v[130:131], v[96:97]
	v_lshlrev_b32_e32 v170, 16, v198
	v_fma_f32 v90, v45, v167, v90
	v_add_f32_e32 v90, v90, v91
	v_lshlrev_b32_e32 v91, 16, v101
	v_mul_f32_e32 v96, v186, v91
	v_and_b32_e32 v91, 0xffff0000, v101
	v_mul_f32_e32 v186, v90, v91
	v_mul_f32_e32 v90, v186, v186
	v_fmac_f32_e32 v90, v96, v96
	v_pk_mul_f32 v[214:215], v[120:121], v[170:171]
	v_add_f32_e32 v245, v100, v90
	v_lshlrev_b32_e32 v100, 16, v78
	v_lshlrev_b32_e32 v90, 16, v79
	v_mov_b32_e32 v222, v100
	v_mov_b32_e32 v223, v90
	v_mov_b32_e32 v242, v210
	v_mov_b32_e32 v243, v214
	v_and_b32_e32 v168, 0xffff0000, v198
	v_pk_fma_f32 v[222:223], v[34:35], v[222:223], v[242:243]
	v_mov_b32_e32 v214, v211
	v_pk_mul_f32 v[212:213], v[122:123], v[168:169]
	v_lshlrev_b32_e32 v101, 16, v86
	v_and_b32_e32 v197, 0xffff0000, v86
	v_and_b32_e32 v196, 0xffff0000, v78
	v_and_b32_e32 v86, 0xffff0000, v79
	v_lshlrev_b32_e32 v79, 16, v83
	v_lshlrev_b32_e32 v78, 16, v82
	v_pk_add_f32 v[210:211], v[222:223], v[214:215]
	v_and_b32_e32 v83, 0xffff0000, v83
	v_pk_mul_f32 v[214:215], v[210:211], v[78:79]
	v_mov_b32_e32 v78, v196
	v_mov_b32_e32 v79, v86
	v_mov_b32_e32 v210, v208
	v_mov_b32_e32 v211, v212
	v_pk_fma_f32 v[78:79], v[40:41], v[78:79], v[210:211]
	v_mov_b32_e32 v212, v209
	v_and_b32_e32 v82, 0xffff0000, v82
	v_pk_add_f32 v[78:79], v[78:79], v[212:213]
	v_lshlrev_b32_e32 v91, 16, v87
	v_pk_mul_f32 v[212:213], v[78:79], v[82:83]
	v_pk_mul_f32 v[92:93], v[124:125], v[100:101]
	v_pk_mul_f32 v[78:79], v[212:213], v[212:213]
	v_pk_mul_f32 v[220:221], v[120:121], v[90:91]
	v_pk_fma_f32 v[78:79], v[214:215], v[214:215], v[78:79]
	v_and_b32_e32 v87, 0xffff0000, v87
	v_add_f32_e32 v78, v244, v78
	v_pk_mul_f32 v[216:217], v[126:127], v[196:197]
	v_add_f32_e32 v90, v78, v79
	v_pk_mul_f32 v[78:79], v[122:123], v[86:87]
	v_mov_b32_e32 v82, v179
	v_mov_b32_e32 v83, v171
	v_mov_b32_e32 v208, v92
	v_mov_b32_e32 v209, v220
	v_pk_fma_f32 v[82:83], v[34:35], v[82:83], v[208:209]
	v_mov_b32_e32 v220, v93
	v_mov_b32_e32 v92, v173
	v_mov_b32_e32 v93, v169
	v_mov_b32_e32 v208, v216
	v_mov_b32_e32 v209, v78
	v_pk_fma_f32 v[92:93], v[40:41], v[92:93], v[208:209]
	v_mov_b32_e32 v78, v217
	v_pk_add_f32 v[78:79], v[92:93], v[78:79]
	v_lshlrev_b32_e32 v93, 16, v75
	v_lshlrev_b32_e32 v92, 16, v74
	v_and_b32_e32 v75, 0xffff0000, v75
	v_and_b32_e32 v74, 0xffff0000, v74
	v_pk_add_f32 v[82:83], v[82:83], v[220:221]
	v_pk_mul_f32 v[210:211], v[78:79], v[74:75]
	v_pk_mul_f32 v[208:209], v[82:83], v[92:93]
	v_pk_mul_f32 v[74:75], v[210:211], v[210:211]
	v_lshlrev_b32_e32 v82, 16, v80
	v_pk_fma_f32 v[74:75], v[208:209], v[208:209], v[74:75]
	v_lshlrev_b32_e32 v78, 16, v81
	v_add_f32_e32 v74, v245, v74
	v_add_f32_e32 v86, v74, v75
	v_lshlrev_b32_e32 v83, 16, v88
	v_and_b32_e32 v93, 0xffff0000, v88
	v_lshlrev_b32_e32 v79, 16, v89
	v_and_b32_e32 v75, 0xffff0000, v89
	v_mov_b32_e32 v88, v82
	v_mov_b32_e32 v89, v78
	v_mov_b32_e32 v242, v202
	v_mov_b32_e32 v243, v206
	v_pk_fma_f32 v[88:89], v[6:7], v[88:89], v[242:243]
	v_mov_b32_e32 v206, v203
	v_pk_mul_f32 v[200:201], v[118:119], v[108:109]
	v_pk_mul_f32 v[204:205], v[114:115], v[102:103]
	v_and_b32_e32 v92, 0xffff0000, v80
	v_and_b32_e32 v74, 0xffff0000, v81
	v_lshlrev_b32_e32 v81, 16, v85
	v_lshlrev_b32_e32 v80, 16, v84
	v_pk_add_f32 v[88:89], v[88:89], v[206:207]
	v_mov_b32_e32 v202, v200
	v_pk_mul_f32 v[80:81], v[88:89], v[80:81]
	v_mov_b32_e32 v88, v92
	v_mov_b32_e32 v89, v74
	v_mov_b32_e32 v203, v204
	v_pk_fma_f32 v[88:89], v[36:37], v[88:89], v[202:203]
	v_mov_b32_e32 v204, v201
	v_and_b32_e32 v85, 0xffff0000, v85
	v_and_b32_e32 v84, 0xffff0000, v84
	v_pk_add_f32 v[88:89], v[88:89], v[204:205]
	v_pk_mul_f32 v[222:223], v[112:113], v[78:79]
	v_pk_mul_f32 v[84:85], v[88:89], v[84:85]
	v_pk_mul_f32 v[216:217], v[116:117], v[82:83]
	v_pk_mul_f32 v[88:89], v[84:85], v[84:85]
	v_lshl_add_u64 v[198:199], v[38:39], 0, s[38:39]
	v_pk_fma_f32 v[88:89], v[80:81], v[80:81], v[88:89]
	v_pk_mul_f32 v[220:221], v[118:119], v[92:93]
	v_add_f32_e32 v78, v90, v88
	v_add_f32_e32 v78, v78, v89
	ds_bpermute_b32 v82, v1, v78
	v_mov_b32_e32 v89, v222
	v_mov_b32_e32 v222, v217
	s_waitcnt vmcnt(2)
; __device__ __forceinline__ unsigned cvt_pk_bf16(float lo, float hi) { unsigned r; asm volatile("v_cvt_pk_bf16_f32 %0, %1, %2" : "=v"(r) : "v"(lo), "v"(hi)); return r; }
; __global__ void __launch_bounds__(512, 2) hymba_fwd(Args args) {
;     ...
;                         ss = wave_sum(ss); const float rstd = rsqrtf(ss * (1.f / 1024.f) + EPS);
;                         u32x4 o0, o1;
;                         o0.x = cvt_pk_bf16(y[0] * rstd, y[1] * rstd); o0.y = cvt_pk_bf16(y[2] * rstd, y[3] * rstd); o0.z = cvt_pk_bf16(y[4] * rstd, y[5] * rstd); o0.w = cvt_pk_bf16(y[6] * rstd, y[7] * rstd);
;                         o1.x = cvt_pk_bf16(y[8] * rstd, y[9] * rstd); o1.y = cvt_pk_bf16(y[10] * rstd, y[11] * rstd); o1.z = cvt_pk_bf16(y[12] * rstd, y[13] * rstd); o1.w = cvt_pk_bf16(y[14] * rstd, y[15] * rstd);
;                         u32x4* op = (u32x4*)(MG + (size_t)row * DM + 1024 + col0); op[0] = o0; op[1] = o1;
	v_lshlrev_b32_e32 v90, 16, v73
	s_waitcnt lgkmcnt(0)
	v_add_f32_e32 v78, v78, v82
	ds_bpermute_b32 v82, v226, v78
	s_waitcnt lgkmcnt(0)
	v_add_f32_e32 v78, v78, v82
	ds_bpermute_b32 v82, v227, v78
	s_waitcnt lgkmcnt(0)
	v_add_f32_e32 v78, v78, v82
	ds_bpermute_b32 v82, v228, v78
	s_waitcnt lgkmcnt(0)
	v_add_f32_e32 v78, v78, v82
	ds_bpermute_b32 v82, v229, v78
	s_waitcnt lgkmcnt(0)
	v_add_f32_e32 v78, v78, v82
	ds_bpermute_b32 v82, v230, v78
	s_waitcnt lgkmcnt(0)
	v_add_f32_e32 v78, v78, v82
	v_fmamk_f32 v78, v78, 0x3a800000, v231
	v_cmp_gt_f32_e64 s[0:1], s3, v78
	v_mul_f32_e32 v82, 0x4b800000, v78
	s_nop 0
	v_cndmask_b32_e64 v78, v78, v82, s[0:1]
	v_rsq_f32_e32 v78, v78
	s_nop 0
	v_mul_f32_e32 v82, 0x45800000, v78
	v_cndmask_b32_e64 v78, v78, v82, s[0:1]
	v_mul_f32_e32 v82, v240, v78
	v_mul_f32_e32 v88, v192, v78
	v_cvt_pk_bf16_f32 v200, v82, v88
	v_mul_f32_e32 v82, v190, v78
	v_mul_f32_e32 v88, v188, v78
	v_cvt_pk_bf16_f32 v201, v82, v88
	v_mul_f32_e32 v82, v218, v78
	v_mul_f32_e32 v88, v219, v78
	v_cvt_pk_bf16_f32 v202, v82, v88
	v_mul_f32_e32 v82, v241, v78
	v_mul_f32_e32 v88, v194, v78
	v_cvt_pk_bf16_f32 v203, v82, v88
	v_mul_f32_e32 v82, v214, v78
	v_mul_f32_e32 v88, v212, v78
	v_cvt_pk_bf16_f32 v204, v82, v88
	v_mul_f32_e32 v82, v215, v78
	v_mul_f32_e32 v80, v80, v78
	v_mul_f32_e32 v88, v213, v78
	v_cvt_pk_bf16_f32 v205, v82, v88
	v_mul_f32_e32 v82, v84, v78
	v_cvt_pk_bf16_f32 v206, v80, v82
	v_mul_f32_e32 v80, v81, v78
	v_mul_f32_e32 v78, v85, v78
	v_cvt_pk_bf16_f32 v207, v80, v78
	v_pk_mul_f32 v[80:81], v[114:115], v[74:75]
	v_mov_b32_e32 v84, v163
	v_mov_b32_e32 v85, v107
	v_mov_b32_e32 v88, v216
	global_store_dwordx4 v[198:199], v[200:203], off offset:2048 sc1
	global_store_dwordx4 v[198:199], v[204:207], off offset:2064 sc1
	v_pk_fma_f32 v[84:85], v[6:7], v[84:85], v[88:89]
	v_mov_b32_e32 v88, v109
	v_mov_b32_e32 v89, v103
	v_mov_b32_e32 v198, v220
	v_mov_b32_e32 v199, v80
	v_pk_fma_f32 v[88:89], v[36:37], v[88:89], v[198:199]
	v_mov_b32_e32 v80, v221
	v_pk_add_f32 v[80:81], v[88:89], v[80:81]
	v_lshlrev_b32_e32 v89, 16, v77
	v_lshlrev_b32_e32 v88, 16, v76
	v_and_b32_e32 v77, 0xffff0000, v77
	v_and_b32_e32 v76, 0xffff0000, v76
	v_pk_add_f32 v[84:85], v[84:85], v[222:223]
	v_pk_mul_f32 v[76:77], v[80:81], v[76:77]
	v_pk_mul_f32 v[84:85], v[84:85], v[88:89]
	v_pk_mul_f32 v[80:81], v[76:77], v[76:77]
	v_and_b32_e32 v89, 0xffff0000, v72
	v_pk_fma_f32 v[80:81], v[84:85], v[84:85], v[80:81]
	s_nop 0
	v_add_f32_e32 v74, v86, v80
	v_add_f32_e32 v74, v74, v81
	ds_bpermute_b32 v78, v1, v74
	v_lshlrev_b32_e32 v86, 16, v72
	v_lshlrev_b32_e32 v72, 16, v62
	v_and_b32_e32 v81, 0xffff0000, v71
	s_waitcnt lgkmcnt(0)
	v_add_f32_e32 v74, v74, v78
	ds_bpermute_b32 v78, v226, v74
	s_waitcnt lgkmcnt(0)
	v_add_f32_e32 v74, v74, v78
	ds_bpermute_b32 v78, v227, v74
	s_waitcnt lgkmcnt(0)
	v_add_f32_e32 v74, v74, v78
	ds_bpermute_b32 v78, v228, v74
	s_waitcnt lgkmcnt(0)
	v_add_f32_e32 v74, v74, v78
	ds_bpermute_b32 v78, v229, v74
	s_waitcnt lgkmcnt(0)
	v_add_f32_e32 v74, v74, v78
	ds_bpermute_b32 v78, v230, v74
	s_waitcnt lgkmcnt(0)
	v_add_f32_e32 v74, v74, v78
	v_fmamk_f32 v74, v74, 0x3a800000, v231
	v_cmp_gt_f32_e64 s[0:1], s3, v74
	v_mul_f32_e32 v78, 0x4b800000, v74
	s_nop 0
	v_cndmask_b32_e64 v74, v74, v78, s[0:1]
	v_rsq_f32_e32 v74, v74
	s_nop 0
	v_mul_f32_e32 v78, 0x45800000, v74
	v_cndmask_b32_e64 v74, v74, v78, s[0:1]
	v_mul_f32_e32 v78, v174, v74
	v_mul_f32_e32 v80, v176, v74
	v_cvt_pk_bf16_f32 v198, v78, v80
	v_mul_f32_e32 v78, v104, v74
	v_mul_f32_e32 v80, v182, v74
	v_cvt_pk_bf16_f32 v199, v78, v80
	v_mul_f32_e32 v78, v94, v74
	v_mul_f32_e32 v80, v98, v74
	v_cvt_pk_bf16_f32 v200, v78, v80
	v_mul_f32_e32 v78, v96, v74
	v_mul_f32_e32 v80, v186, v74
	v_cvt_pk_bf16_f32 v201, v78, v80
	v_mul_f32_e32 v78, v208, v74
	v_mul_f32_e32 v80, v210, v74
	v_cvt_pk_bf16_f32 v202, v78, v80
	v_mul_f32_e32 v78, v209, v74
	v_mul_f32_e32 v76, v76, v74
	v_mul_f32_e32 v80, v211, v74
	v_cvt_pk_bf16_f32 v203, v78, v80
	v_mul_f32_e32 v78, v84, v74
	v_cvt_pk_bf16_f32 v204, v78, v76
	v_mul_f32_e32 v76, v85, v74
	v_mul_f32_e32 v74, v77, v74
	v_cvt_pk_bf16_f32 v205, v76, v74
	v_lshl_add_u64 v[76:77], v[38:39], 0, s[10:11]
	v_and_b32_e32 v94, 0xffff0000, v73
	v_lshlrev_b32_e32 v73, 16, v239
	global_store_dwordx4 v[76:77], v[198:201], off offset:2048 sc1
	global_store_dwordx4 v[76:77], v[202:205], off offset:2064 sc1
	v_pk_mov_b32 v[76:77], v[186:187], v[72:73] op_sel:[1,0]
	v_pk_mul_f32 v[72:73], v[158:159], v[72:73]
	v_pk_mul_f32 v[76:77], v[140:141], v[76:77]
	v_lshlrev_b32_e32 v74, 16, v70
	v_fma_f32 v76, v46, v193, v76
	v_add_f32_e32 v76, v76, v77
	v_fma_f32 v72, v22, v193, v72
	v_mul_f32_e32 v96, v76, v74
	v_add_f32_e32 v74, v72, v73
	v_and_b32_e32 v73, 0xffff0000, v239
	v_and_b32_e32 v72, 0xffff0000, v62
	v_pk_mov_b32 v[76:77], v[184:185], v[72:73] op_sel:[1,0]
	v_and_b32_e32 v78, 0xffff0000, v70
	v_pk_mul_f32 v[76:77], v[142:143], v[76:77]
	v_pk_mul_f32 v[72:73], v[30:31], v[72:73]
	v_fma_f32 v62, v47, v191, v76
	v_add_f32_e32 v62, v62, v77
	v_mul_f32_e32 v98, v62, v78
	v_fma_f32 v62, v23, v191, v72
	s_waitcnt vmcnt(4)
; __device__ __forceinline__ float bf_lo(unsigned w) { return __uint_as_float(w << 16); }
; __device__ __forceinline__ float bf_hi(unsigned w) { return __uint_as_float(w & 0xffff0000u); }
; __global__ void __launch_bounds__(512, 2) hymba_fwd(Args args) {
;     ...
;                         for (int q = 0; q < 2; ++q) { const u32x4 a = gbr[r][q], pu = chr[r][q], pc = chr[r + 1][q], pd = chr[r + 2][q];
; #pragma unroll
;                             for (int e = 0; e < 4; ++e) {
;                                 const int i0 = q * 8 + 2 * e, i1 = i0 + 1;
;                                 const float c0 = w0[i0 >> 2][i0 & 3] * bf_lo(pu[e]) + w1[i0 >> 2][i0 & 3] * bf_lo(pc[e]) + w2[i0 >> 2][i0 & 3] * bf_lo(pd[e]);
;                                 const float c1 = w0[i1 >> 2][i1 & 3] * bf_hi(pu[e]) + w1[i1 >> 2][i1 & 3] * bf_hi(pc[e]) + w2[i1 >> 2][i1 & 3] * bf_hi(pd[e]);
;                                 y[i0] = bf_lo(a[e]) * c0; y[i1] = bf_hi(a[e]) * c1; ss += y[i0] * y[i0] + y[i1] * y[i1]; } }
	v_lshlrev_b32_e32 v72, 16, v66
	v_add_f32_e32 v62, v62, v73
	v_mul_f32_e32 v82, v74, v72
	v_lshlrev_b32_e32 v73, 16, v238
	v_lshlrev_b32_e32 v72, 16, v63
	v_pk_mov_b32 v[76:77], v[182:183], v[72:73] op_sel:[1,0]
	v_and_b32_e32 v66, 0xffff0000, v66
	v_pk_mul_f32 v[76:77], v[136:137], v[76:77]
	v_mul_f32_e32 v84, v62, v66
	v_fma_f32 v62, v48, v189, v76
	v_lshlrev_b32_e32 v80, 16, v71
	v_add_f32_e32 v62, v62, v77
	v_pk_mul_f32 v[72:73], v[156:157], v[72:73]
	v_mul_f32_e32 v100, v62, v80
	v_fma_f32 v62, v24, v189, v72
	v_add_f32_e32 v74, v62, v73
	v_and_b32_e32 v73, 0xffff0000, v238
	v_and_b32_e32 v72, 0xffff0000, v63
	v_pk_mov_b32 v[62:63], v[180:181], v[72:73] op_sel:[1,0]
	v_mul_f32_e32 v78, v98, v98
	v_pk_mul_f32 v[62:63], v[138:139], v[62:63]
	v_fmac_f32_e32 v78, v96, v96
	v_fma_f32 v62, v49, v105, v62
	v_add_f32_e32 v62, v62, v63
	v_mul_f32_e32 v104, v62, v81
	v_mul_f32_e32 v62, v104, v104
	v_fmac_f32_e32 v62, v100, v100
	v_add_f32_e32 v76, v78, v62
	v_pk_mul_f32 v[62:63], v[32:33], v[72:73]
	v_mul_f32_e32 v66, v84, v84
	v_fma_f32 v62, v25, v105, v62
	v_add_f32_e32 v62, v62, v63
	v_lshlrev_b32_e32 v63, 16, v67
	v_mul_f32_e32 v85, v74, v63
	v_and_b32_e32 v63, 0xffff0000, v67
	v_mul_f32_e32 v88, v62, v63
	v_mul_f32_e32 v62, v88, v88
	v_fmac_f32_e32 v66, v82, v82
	v_fmac_f32_e32 v62, v85, v85
	v_add_f32_e32 v72, v66, v62
	v_lshlrev_b32_e32 v63, 16, v237
	v_lshlrev_b32_e32 v62, 16, v64
	v_pk_mov_b32 v[66:67], v[174:175], v[62:63] op_sel:[1,0]
	v_pk_mul_f32 v[62:63], v[154:155], v[62:63]
	v_pk_mul_f32 v[66:67], v[132:133], v[66:67]
	v_fma_f32 v62, v10, v99, v62
	v_fma_f32 v66, v42, v99, v66
	v_add_f32_e32 v66, v66, v67
	v_add_f32_e32 v73, v62, v63
	v_and_b32_e32 v63, 0xffff0000, v237
	v_and_b32_e32 v62, 0xffff0000, v64
	v_mul_f32_e32 v105, v66, v86
	v_pk_mov_b32 v[66:67], v[164:165], v[62:63] op_sel:[1,0]
	v_pk_mul_f32 v[62:63], v[18:19], v[62:63]
	v_pk_mul_f32 v[66:67], v[134:135], v[66:67]
	v_fma_f32 v62, v11, v95, v62
	v_fma_f32 v64, v43, v95, v66
	v_add_f32_e32 v64, v64, v67
	v_add_f32_e32 v62, v62, v63
	v_lshlrev_b32_e32 v63, 16, v68
	v_mul_f32_e32 v99, v64, v89
	v_mul_f32_e32 v89, v73, v63
	v_and_b32_e32 v63, 0xffff0000, v68
	v_mul_f32_e32 v92, v62, v63
	v_mul_f32_e32 v62, v92, v92
	v_fmac_f32_e32 v62, v89, v89
	v_add_f32_e32 v68, v72, v62
	v_lshlrev_b32_e32 v63, 16, v236
	v_lshlrev_b32_e32 v62, 16, v65
	v_mul_f32_e32 v64, v99, v99
	v_pk_mov_b32 v[66:67], v[176:177], v[62:63] op_sel:[1,0]
	v_fmac_f32_e32 v64, v105, v105
	v_pk_mul_f32 v[66:67], v[128:129], v[66:67]
	v_pk_mul_f32 v[62:63], v[152:153], v[62:63]
	v_add_f32_e32 v74, v76, v64
	v_fma_f32 v64, v44, v195, v66
	v_fma_f32 v62, v12, v195, v62
	v_add_f32_e32 v64, v64, v67
	v_add_f32_e32 v66, v62, v63
	v_and_b32_e32 v63, 0xffff0000, v236
	v_and_b32_e32 v62, 0xffff0000, v65
	v_mul_f32_e32 v164, v64, v90
	v_pk_mov_b32 v[64:65], v[166:167], v[62:63] op_sel:[1,0]
	v_pk_mul_f32 v[62:63], v[20:21], v[62:63]
	v_pk_mul_f32 v[64:65], v[130:131], v[64:65]
	v_fma_f32 v62, v13, v97, v62
	v_fma_f32 v64, v45, v97, v64
	v_add_f32_e32 v64, v64, v65
	v_add_f32_e32 v62, v62, v63
	v_lshlrev_b32_e32 v63, 16, v69
	v_mul_f32_e32 v165, v64, v94
	v_mul_f32_e32 v94, v66, v63
	v_and_b32_e32 v63, 0xffff0000, v69
	v_mul_f32_e32 v95, v62, v63
	v_mul_f32_e32 v62, v95, v95
	v_mul_f32_e32 v64, v165, v165
	v_fmac_f32_e32 v62, v94, v94
	v_fmac_f32_e32 v64, v164, v164
	v_add_f32_e32 v78, v68, v62
	v_lshlrev_b32_e32 v63, 16, v235
	v_lshlrev_b32_e32 v62, 16, v54
	v_add_f32_e32 v74, v74, v64
	v_pk_mov_b32 v[64:65], v[178:179], v[62:63] op_sel:[1,0]
	v_mov_b32_e32 v86, v197
	v_pk_mul_f32 v[76:77], v[124:125], v[64:65]
	v_and_b32_e32 v65, 0xffff0000, v235
	v_and_b32_e32 v64, 0xffff0000, v54
	v_pk_mov_b32 v[66:67], v[172:173], v[64:65] op_sel:[1,0]
	v_lshlrev_b32_e32 v167, 16, v59
	v_pk_mul_f32 v[68:69], v[126:127], v[66:67]
	v_lshlrev_b32_e32 v67, 16, v234
	v_lshlrev_b32_e32 v66, 16, v55
	v_pk_mov_b32 v[72:73], v[170:171], v[66:67] op_sel:[1,0]
	v_lshlrev_b32_e32 v166, 16, v58
	v_pk_mul_f32 v[80:81], v[120:121], v[72:73]
	v_and_b32_e32 v73, 0xffff0000, v234
	v_and_b32_e32 v72, 0xffff0000, v55
	v_pk_mov_b32 v[54:55], v[168:169], v[72:73] op_sel:[1,0]
	v_and_b32_e32 v169, 0xffff0000, v59
	v_pk_mul_f32 v[54:55], v[122:123], v[54:55]
	v_and_b32_e32 v168, 0xffff0000, v58
	v_mov_b32_e32 v58, v76
	v_mov_b32_e32 v59, v80
	v_mov_b32_e32 v80, v77
	v_mov_b32_e32 v76, v68
	v_mov_b32_e32 v77, v54
	v_mov_b32_e32 v90, v101
	v_pk_fma_f32 v[76:77], v[40:41], v[86:87], v[76:77]
	v_mov_b32_e32 v54, v69
	v_pk_fma_f32 v[58:59], v[34:35], v[90:91], v[58:59]
	v_pk_add_f32 v[54:55], v[76:77], v[54:55]
	v_pk_add_f32 v[58:59], v[58:59], v[80:81]
	v_pk_mul_f32 v[68:69], v[54:55], v[168:169]
	v_pk_mul_f32 v[58:59], v[58:59], v[166:167]
	v_pk_mul_f32 v[54:55], v[68:69], v[68:69]
	v_pk_mul_f32 v[62:63], v[150:151], v[62:63]
	v_pk_fma_f32 v[54:55], v[58:59], v[58:59], v[54:55]
	v_pk_mul_f32 v[66:67], v[148:149], v[66:67]
	v_add_f32_e32 v54, v74, v54
	v_add_f32_e32 v97, v54, v55
	v_pk_mul_f32 v[54:55], v[16:17], v[72:73]
	v_mov_b32_e32 v72, v62
	v_mov_b32_e32 v73, v66
	v_pk_mul_f32 v[64:65], v[14:15], v[64:65]
	v_pk_fma_f32 v[72:73], v[2:3], v[90:91], v[72:73]
	v_mov_b32_e32 v66, v63
	v_pk_add_f32 v[62:63], v[72:73], v[66:67]
	v_mov_b32_e32 v66, v64
	v_mov_b32_e32 v67, v54
	v_pk_fma_f32 v[66:67], v[8:9], v[86:87], v[66:67]
	v_mov_b32_e32 v54, v65
	v_pk_add_f32 v[64:65], v[66:67], v[54:55]
	v_lshlrev_b32_e32 v55, 16, v51
	v_lshlrev_b32_e32 v54, 16, v50
	v_and_b32_e32 v51, 0xffff0000, v51
	v_and_b32_e32 v50, 0xffff0000, v50
	v_pk_mul_f32 v[50:51], v[64:65], v[50:51]
	v_pk_mul_f32 v[54:55], v[62:63], v[54:55]
	v_pk_mul_f32 v[62:63], v[50:51], v[50:51]
; __device__ __forceinline__ unsigned cvt_pk_bf16(float lo, float hi) { unsigned r; asm volatile("v_cvt_pk_bf16_f32 %0, %1, %2" : "=v"(r) : "v"(lo), "v"(hi)); return r; }
; __global__ void __launch_bounds__(512, 2) hymba_fwd(Args args) {
;     ...
;                         ss = wave_sum(ss); const float rstd = rsqrtf(ss * (1.f / 1024.f) + EPS);
;                         u32x4 o0, o1;
;                         o0.x = cvt_pk_bf16(y[0] * rstd, y[1] * rstd); o0.y = cvt_pk_bf16(y[2] * rstd, y[3] * rstd); o0.z = cvt_pk_bf16(y[4] * rstd, y[5] * rstd); o0.w = cvt_pk_bf16(y[6] * rstd, y[7] * rstd);
;                         o1.x = cvt_pk_bf16(y[8] * rstd, y[9] * rstd); o1.y = cvt_pk_bf16(y[10] * rstd, y[11] * rstd); o1.z = cvt_pk_bf16(y[12] * rstd, y[13] * rstd); o1.w = cvt_pk_bf16(y[14] * rstd, y[15] * rstd);
;                         u32x4* op = (u32x4*)(MG + (size_t)row * DM + 1024 + col0); op[0] = o0; op[1] = o1;
;                     }
;                 }
	v_and_b32_e32 v91, 0xffff0000, v232
	v_pk_fma_f32 v[62:63], v[54:55], v[54:55], v[62:63]
	v_and_b32_e32 v90, 0xffff0000, v57
	v_add_f32_e32 v62, v78, v62
	v_add_f32_e32 v101, v62, v63
	v_lshlrev_b32_e32 v63, 16, v233
	v_lshlrev_b32_e32 v62, 16, v56
	v_pk_mov_b32 v[64:65], v[162:163], v[62:63] op_sel:[1,0]
	v_pk_mul_f32 v[66:67], v[146:147], v[62:63]
	v_and_b32_e32 v63, 0xffff0000, v233
	v_and_b32_e32 v62, 0xffff0000, v56
	v_pk_mov_b32 v[72:73], v[108:109], v[62:63] op_sel:[1,0]
	v_pk_mul_f32 v[76:77], v[26:27], v[62:63]
	v_lshlrev_b32_e32 v63, 16, v232
	v_lshlrev_b32_e32 v62, 16, v57
	v_pk_mov_b32 v[80:81], v[106:107], v[62:63] op_sel:[1,0]
	v_pk_mul_f32 v[64:65], v[116:117], v[64:65]
	v_pk_mul_f32 v[80:81], v[112:113], v[80:81]
	v_pk_mov_b32 v[56:57], v[102:103], v[90:91] op_sel:[1,0]
	v_mov_b32_e32 v78, v83
	v_mov_b32_e32 v102, v64
	v_mov_b32_e32 v103, v80
	v_pk_fma_f32 v[102:103], v[6:7], v[78:79], v[102:103]
	v_mov_b32_e32 v80, v65
	v_pk_mul_f32 v[72:73], v[118:119], v[72:73]
	v_pk_mul_f32 v[86:87], v[144:145], v[62:63]
	v_pk_mul_f32 v[56:57], v[114:115], v[56:57]
	v_lshlrev_b32_e32 v63, 16, v61
	v_lshlrev_b32_e32 v62, 16, v60
	v_pk_add_f32 v[64:65], v[102:103], v[80:81]
	v_mov_b32_e32 v74, v93
	v_pk_mul_f32 v[64:65], v[64:65], v[62:63]
	v_mov_b32_e32 v62, v72
	v_mov_b32_e32 v63, v56
	v_pk_fma_f32 v[62:63], v[36:37], v[74:75], v[62:63]
	v_mov_b32_e32 v56, v73
	v_and_b32_e32 v61, 0xffff0000, v61
	v_and_b32_e32 v60, 0xffff0000, v60
	v_pk_add_f32 v[56:57], v[62:63], v[56:57]
	v_lshl_add_u64 v[70:71], v[38:39], 0, s[8:9]
	v_pk_mul_f32 v[72:73], v[56:57], v[60:61]
	s_nop 0
	v_pk_mul_f32 v[56:57], v[72:73], v[72:73]
	s_nop 0
	v_pk_fma_f32 v[56:57], v[64:65], v[64:65], v[56:57]
	s_nop 0
	v_add_f32_e32 v56, v97, v56
	v_add_f32_e32 v56, v56, v57
	ds_bpermute_b32 v57, v1, v56
	s_waitcnt lgkmcnt(0)
	v_add_f32_e32 v56, v56, v57
	ds_bpermute_b32 v57, v226, v56
	s_waitcnt lgkmcnt(0)
	v_add_f32_e32 v56, v56, v57
	ds_bpermute_b32 v57, v227, v56
	s_waitcnt lgkmcnt(0)
	v_add_f32_e32 v56, v56, v57
	ds_bpermute_b32 v57, v228, v56
	s_waitcnt lgkmcnt(0)
	v_add_f32_e32 v56, v56, v57
	ds_bpermute_b32 v57, v229, v56
	s_waitcnt lgkmcnt(0)
	v_add_f32_e32 v56, v56, v57
	ds_bpermute_b32 v57, v230, v56
	s_waitcnt lgkmcnt(0)
	v_add_f32_e32 v56, v56, v57
	v_fmamk_f32 v56, v56, 0x3a800000, v231
	v_cmp_gt_f32_e64 s[0:1], s3, v56
	v_mul_f32_e32 v57, 0x4b800000, v56
	s_nop 0
	v_cndmask_b32_e64 v56, v56, v57, s[0:1]
	v_rsq_f32_e32 v56, v56
	s_nop 0
	v_mul_f32_e32 v57, 0x45800000, v56
	v_cndmask_b32_e64 v80, v56, v57, s[0:1]
	v_mul_f32_e32 v56, v96, v80
	v_mul_f32_e32 v57, v98, v80
	v_cvt_pk_bf16_f32 v60, v56, v57
	v_mul_f32_e32 v56, v100, v80
	v_mul_f32_e32 v57, v104, v80
	v_cvt_pk_bf16_f32 v61, v56, v57
	v_mul_f32_e32 v56, v105, v80
	v_mul_f32_e32 v57, v99, v80
	v_cvt_pk_bf16_f32 v62, v56, v57
	v_mul_f32_e32 v56, v164, v80
	v_mul_f32_e32 v57, v165, v80
	v_cvt_pk_bf16_f32 v63, v56, v57
	v_mul_f32_e32 v56, v58, v80
	v_mul_f32_e32 v57, v68, v80
	v_cvt_pk_bf16_f32 v56, v56, v57
	v_mul_f32_e32 v57, v59, v80
	v_mul_f32_e32 v58, v69, v80
	v_cvt_pk_bf16_f32 v57, v57, v58
	v_mul_f32_e32 v58, v64, v80
	v_mul_f32_e32 v59, v72, v80
	v_cvt_pk_bf16_f32 v58, v58, v59
	v_mul_f32_e32 v59, v65, v80
	v_mul_f32_e32 v64, v73, v80
	v_cvt_pk_bf16_f32 v59, v59, v64
	global_store_dwordx4 v[70:71], v[60:63], off offset:2048 sc1
	global_store_dwordx4 v[70:71], v[56:59], off offset:2064 sc1
	s_nop 0
	v_mov_b32_e32 v60, v76
	v_pk_mul_f32 v[56:57], v[28:29], v[90:91]
	v_mov_b32_e32 v58, v66
	v_mov_b32_e32 v61, v56
	v_mov_b32_e32 v59, v86
	v_pk_fma_f32 v[60:61], v[4:5], v[74:75], v[60:61]
	v_mov_b32_e32 v56, v77
	v_pk_fma_f32 v[58:59], v[160:161], v[78:79], v[58:59]
	v_mov_b32_e32 v86, v67
	v_pk_add_f32 v[56:57], v[60:61], v[56:57]
	v_lshlrev_b32_e32 v61, 16, v53
	v_lshlrev_b32_e32 v60, 16, v52
	v_and_b32_e32 v53, 0xffff0000, v53
	v_and_b32_e32 v52, 0xffff0000, v52
	v_pk_add_f32 v[58:59], v[58:59], v[86:87]
	v_pk_mul_f32 v[52:53], v[56:57], v[52:53]
	v_pk_mul_f32 v[60:61], v[58:59], v[60:61]
	v_pk_mul_f32 v[56:57], v[52:53], v[52:53]
	s_nop 0
	v_pk_fma_f32 v[56:57], v[60:61], v[60:61], v[56:57]
	s_nop 0
	v_add_f32_e32 v56, v101, v56
	v_add_f32_e32 v56, v56, v57
	ds_bpermute_b32 v57, v1, v56
	s_waitcnt lgkmcnt(0)
	v_add_f32_e32 v56, v56, v57
	ds_bpermute_b32 v57, v226, v56
	s_waitcnt lgkmcnt(0)
	v_add_f32_e32 v56, v56, v57
	ds_bpermute_b32 v57, v227, v56
	s_waitcnt lgkmcnt(0)
	v_add_f32_e32 v56, v56, v57
	ds_bpermute_b32 v57, v228, v56
	s_waitcnt lgkmcnt(0)
	v_add_f32_e32 v56, v56, v57
	ds_bpermute_b32 v57, v229, v56
	s_waitcnt lgkmcnt(0)
	v_add_f32_e32 v56, v56, v57
	ds_bpermute_b32 v57, v230, v56
	s_waitcnt lgkmcnt(0)
	v_add_f32_e32 v56, v56, v57
	v_fmamk_f32 v56, v56, 0x3a800000, v231
	v_cmp_gt_f32_e64 s[0:1], s3, v56
	v_mul_f32_e32 v57, 0x4b800000, v56
	s_nop 0
	v_cndmask_b32_e64 v56, v56, v57, s[0:1]
	v_rsq_f32_e32 v56, v56
	s_nop 0
	v_mul_f32_e32 v57, 0x45800000, v56
	v_cndmask_b32_e64 v62, v56, v57, s[0:1]
	v_mul_f32_e32 v56, v82, v62
	v_mul_f32_e32 v57, v84, v62
	v_cvt_pk_bf16_f32 v56, v56, v57
	v_mul_f32_e32 v57, v85, v62
	v_mul_f32_e32 v58, v88, v62
	v_cvt_pk_bf16_f32 v57, v57, v58
	v_mul_f32_e32 v58, v89, v62
	v_mul_f32_e32 v59, v92, v62
	v_cvt_pk_bf16_f32 v58, v58, v59
	v_mul_f32_e32 v59, v94, v62
	v_mul_f32_e32 v54, v54, v62
	v_mul_f32_e32 v50, v50, v62
	v_mul_f32_e32 v63, v95, v62
	v_cvt_pk_bf16_f32 v59, v59, v63
	v_cvt_pk_bf16_f32 v50, v54, v50
	v_mul_f32_e32 v54, v55, v62
	v_mul_f32_e32 v51, v51, v62
	v_cvt_pk_bf16_f32 v51, v54, v51
	v_mul_f32_e32 v54, v60, v62
	v_mul_f32_e32 v52, v52, v62
	v_cvt_pk_bf16_f32 v52, v54, v52
	v_mul_f32_e32 v54, v61, v62
	v_mul_f32_e32 v53, v53, v62
	v_cvt_pk_bf16_f32 v53, v54, v53
	v_lshl_add_u64 v[54:55], v[38:39], 0, s[6:7]
	s_mov_b64 s[0:1], 0
	global_store_dwordx4 v[54:55], v[56:59], off offset:2048 sc1
	global_store_dwordx4 v[54:55], v[50:53], off offset:2064 sc1
	s_cbranch_vccz .LBB0_741
	s_add_i32 s34, s34, s97
	s_cmpk_gt_i32 s34, 0x7ff
	s_cbranch_scc0 .LBB0_740

; #define MX3(a, b, c) __builtin_fmaxf(__builtin_fmaxf((a), (b)), (c))
; template <int G> __device__ __forceinline__ void fin_gap(f32x16& P0, f32x16& P1, float (&sacc)[4], unsigned (&cv)[16], u32x4 (&pw)[4]) {
;   if constexpr (G < 16) { P1[G] = __builtin_amdgcn_exp2f(P1[G]); sacc[G & 3] += P0[G]; }
;   else { constexpr int r = 2 * (G - 16); sacc[r & 3] += P1[r]; sacc[(r + 1) & 3] += P1[r + 1]; }
;   if constexpr (G < 4) cv[G] = cvtpk_c(P0[2 * G], P0[2 * G + 1]);
;   else if constexpr (G >= 6 && G < 10) { constexpr int i = G - 2; cv[i] = cvtpk_c(P0[2 * i], P0[2 * i + 1]); }
;   else if constexpr (G >= 12 && G < 16) { constexpr int i = G - 4, j = i - 8; cv[i] = cvtpk_c(P1[2 * j], P1[2 * j + 1]); }
;   else if constexpr (G >= 18 && G < 22) { constexpr int i = G - 6, j = i - 8; cv[i] = cvtpk_c(P1[2 * j], P1[2 * j + 1]); }
;   if constexpr (G == 4 || G == 10 || G == 16 || G == 22) { constexpr int q = (G - 4) / 6; auto r0 = __builtin_amdgcn_permlane32_swap(cv[4 * q], cv[4 * q + 2], false, false); pw[q].x = r0[0]; pw[q].z = r0[1]; }
;   if constexpr (G == 5 || G == 11 || G == 17 || G == 23) { constexpr int q = (G - 5) / 6; auto r1 = __builtin_amdgcn_permlane32_swap(cv[4 * q + 1], cv[4 * q + 3], false, false); pw[q].y = r1[0]; pw[q].w = r1[1]; }
; }
; template <int G> __device__ __forceinline__ void par_gap(f32x16& C0, f32x16& C1, float& ma, float& mb, float mn) {
;   if constexpr (G == 0) { ma = MX3(C0[0], C0[1], C1[0]); mb = MX3(C0[2], C0[3], C1[1]); ma = MX3(ma, C1[2], C1[3]); ma = MX3(ma, C0[4], C0[5]); }
;   else if constexpr (G == 1) { mb = MX3(mb, C0[6], C0[7]); ma = MX3(ma, C1[4], C1[5]); mb = MX3(mb, C1[6], C1[7]); ma = MX3(ma, C0[8], C0[9]); }
;   else if constexpr (G == 2) { mb = MX3(mb, C0[10], C0[11]); ma = MX3(ma, C1[8], C1[9]); mb = MX3(mb, C1[10], C1[11]); ma = MX3(ma, C0[12], C0[13]); }
;   else if constexpr (G == 3) { mb = MX3(mb, C0[14], C0[15]); ma = MX3(ma, C1[12], C1[13]); mb = MX3(mb, C1[14], C1[15]); }
;   else if constexpr (G == 4) { _Pragma("unroll") for (int r = 0; r < 8; ++r) C0[r] -= mn; }
;   else if constexpr (G == 5) { _Pragma("unroll") for (int r = 8; r < 16; ++r) C0[r] -= mn; }
;   else if constexpr (G == 6) { _Pragma("unroll") for (int r = 0; r < 8; ++r) C1[r] -= mn; }
;   else if constexpr (G == 7) { _Pragma("unroll") for (int r = 8; r < 16; ++r) C1[r] -= mn; }
.LBB0_775:
	v_sub_f32_e32 v84, v84, v140
	v_sub_f32_e32 v85, v85, v140
	v_sub_f32_e32 v86, v86, v140
	v_sub_f32_e32 v87, v87, v140
	v_sub_f32_e32 v88, v88, v140
	v_sub_f32_e32 v89, v89, v140
	v_sub_f32_e32 v90, v90, v140
	v_sub_f32_e32 v91, v91, v140
	v_exp_f32_e32 v84, v84
	v_exp_f32_e32 v85, v85
	v_exp_f32_e32 v86, v86
	v_exp_f32_e32 v87, v87
	v_sub_f32_e32 v92, v92, v140
	v_sub_f32_e32 v93, v93, v140
	v_sub_f32_e32 v94, v94, v140
	v_sub_f32_e32 v95, v95, v140
	v_exp_f32_e32 v88, v88
	v_exp_f32_e32 v89, v89
	v_exp_f32_e32 v90, v90
	v_exp_f32_e32 v91, v91
	v_sub_f32_e32 v96, v96, v140
	v_sub_f32_e32 v97, v97, v140
	v_sub_f32_e32 v98, v98, v140
	v_sub_f32_e32 v99, v99, v140
	v_exp_f32_e32 v92, v92
	v_exp_f32_e32 v93, v93
	v_exp_f32_e32 v94, v94
	v_exp_f32_e32 v95, v95
	v_sub_f32_e32 v68, v68, v140
	v_sub_f32_e32 v70, v70, v140
	v_exp_f32_e32 v96, v96
	v_exp_f32_e32 v97, v97
	v_exp_f32_e32 v98, v98
	v_exp_f32_e32 v99, v99
	v_sub_f32_e32 v69, v69, v140
	v_sub_f32_e32 v71, v71, v140
	v_sub_f32_e32 v72, v72, v140
	v_sub_f32_e32 v74, v74, v140
	v_sub_f32_e32 v73, v73, v140
	v_sub_f32_e32 v75, v75, v140
	v_exp_f32_e32 v102, v68
	v_add_f32_e32 v103, 0, v84
	v_cvt_pk_bf16_f32 v68, v84, v85
	v_exp_f32_e32 v84, v69
	v_add_f32_e32 v85, 0, v85
	v_cvt_pk_bf16_f32 v69, v86, v87
	v_exp_f32_e32 v104, v70
	v_add_f32_e32 v86, 0, v86
	v_exp_f32_e32 v105, v71
	v_add_f32_e32 v87, 0, v87
	v_sub_f32_e32 v76, v76, v140
	v_sub_f32_e32 v77, v77, v140
	v_sub_f32_e32 v78, v78, v140
	v_sub_f32_e32 v79, v79, v140
	v_cvt_pk_bf16_f32 v70, v88, v89
	v_cvt_pk_bf16_f32 v71, v90, v91
	v_exp_f32_e32 v106, v72
	v_add_f32_e32 v88, v88, v103
	v_exp_f32_e32 v103, v73
	v_add_f32_e32 v85, v89, v85
	v_exp_f32_e32 v89, v74
	v_add_f32_e32 v86, v90, v86
	v_exp_f32_e32 v90, v75
	v_add_f32_e32 v87, v91, v87
	v_sub_f32_e32 v80, v80, v140
	v_sub_f32_e32 v81, v81, v140
	v_sub_f32_e32 v82, v82, v140
	v_sub_f32_e32 v83, v83, v140
	v_exp_f32_e32 v91, v76
	v_add_f32_e32 v76, v92, v88
	v_exp_f32_e32 v88, v77
	v_add_f32_e32 v77, v93, v85
	v_exp_f32_e32 v85, v78
	v_add_f32_e32 v78, v94, v86
	v_exp_f32_e32 v86, v79
	v_add_f32_e32 v79, v95, v87
	v_cvt_pk_bf16_f32 v72, v92, v93
	v_cvt_pk_bf16_f32 v73, v94, v95
	v_exp_f32_e32 v87, v80
	v_add_f32_e32 v80, v96, v76
	v_exp_f32_e32 v92, v81
	v_add_f32_e32 v81, v97, v77
	v_exp_f32_e32 v93, v82
	v_add_f32_e32 v82, v98, v78
	v_exp_f32_e32 v94, v83
	v_add_f32_e32 v83, v99, v79
	v_add_f32_e32 v80, v102, v80
	v_add_f32_e32 v81, v84, v81
	v_add_f32_e32 v82, v104, v82
	v_add_f32_e32 v83, v105, v83
	v_cvt_pk_bf16_f32 v76, v102, v84
	v_cvt_pk_bf16_f32 v79, v89, v90
	v_add_f32_e32 v84, v106, v80
	v_add_f32_e32 v95, v103, v81
	v_add_f32_e32 v89, v89, v82
	v_add_f32_e32 v83, v90, v83
	v_cvt_pk_bf16_f32 v80, v91, v88
	v_cvt_pk_bf16_f32 v81, v85, v86
	v_add_f32_e32 v84, v91, v84
	v_add_f32_e32 v88, v88, v95
	v_add_f32_e32 v85, v85, v89
	v_add_f32_e32 v86, v86, v83
	v_cvt_pk_bf16_f32 v82, v87, v92
	v_add_f32_e32 v84, v87, v84
	v_add_f32_e32 v87, v92, v88
	v_add_f32_e32 v85, v93, v85
	v_add_f32_e32 v86, v94, v86
	v_add_f32_e32 v84, v84, v87
	v_add_f32_e32 v85, v85, v86
	s_waitcnt vmcnt(0)
	v_add_f32_e32 v84, v84, v85
	v_mov_b32_e32 v85, v84
	v_cvt_pk_bf16_f32 v74, v96, v97
	v_cvt_pk_bf16_f32 v75, v98, v99
	v_cvt_pk_bf16_f32 v77, v104, v105
	v_cvt_pk_bf16_f32 v78, v106, v103
	v_cvt_pk_bf16_f32 v83, v93, v94
	v_permlane32_swap_b32_e32 v84, v85
	s_barrier
	v_permlane32_swap_b32_e32 v68, v70
	v_permlane32_swap_b32_e32 v69, v71
	v_permlane32_swap_b32_e32 v72, v74
	v_permlane32_swap_b32_e32 v73, v75
	v_permlane32_swap_b32_e32 v76, v78
	v_permlane32_swap_b32_e32 v77, v79
	v_permlane32_swap_b32_e32 v80, v82
	v_permlane32_swap_b32_e32 v81, v83
	ds_read_b64_tr_b16 v[86:87], v167 offset:16384
	ds_read_b64_tr_b16 v[88:89], v167 offset:18432
	ds_read_b64_tr_b16 v[90:91], v167 offset:20480
	ds_read_b64_tr_b16 v[92:93], v167 offset:22528
	ds_read_b64_tr_b16 v[94:95], v167 offset:24576
	ds_read_b64_tr_b16 v[96:97], v167 offset:26624
	ds_read_b64_tr_b16 v[102:103], v167 offset:28672
	ds_read_b64_tr_b16 v[104:105], v167 offset:30720
	s_waitcnt lgkmcnt(6)
	v_mfma_f32_32x32x16_bf16 v[4:19], v[68:71], v[86:89], v[4:19]
	ds_read_b64_tr_b16 v[106:107], v167 offset:16896
	ds_read_b64_tr_b16 v[108:109], v167 offset:18944
	s_waitcnt lgkmcnt(6)
	v_mfma_f32_32x32x16_bf16 v[4:19], v[72:75], v[90:93], v[4:19]
	ds_read_b64_tr_b16 v[86:87], v167 offset:20992
	ds_read_b64_tr_b16 v[88:89], v167 offset:23040
	s_waitcnt lgkmcnt(6)
	v_mfma_f32_32x32x16_bf16 v[4:19], v[76:79], v[94:97], v[4:19]
	ds_read_b64_tr_b16 v[90:91], v167 offset:25088
	ds_read_b64_tr_b16 v[92:93], v167 offset:27136
	s_waitcnt lgkmcnt(6)
	v_mfma_f32_32x32x16_bf16 v[4:19], v[80:83], v[102:105], v[4:19]
	ds_read_b64_tr_b16 v[94:95], v167 offset:29184
	ds_read_b64_tr_b16 v[96:97], v167 offset:31232
	s_waitcnt lgkmcnt(6)
	v_mfma_f32_32x32x16_bf16 v[52:67], v[68:71], v[106:109], v[52:67]
	ds_read_b64_tr_b16 v[102:103], v167 offset:17408
	ds_read_b64_tr_b16 v[104:105], v167 offset:19456
	s_waitcnt lgkmcnt(6)
	v_mfma_f32_32x32x16_bf16 v[52:67], v[72:75], v[86:89], v[52:67]
	ds_read_b64_tr_b16 v[106:107], v167 offset:21504
	ds_read_b64_tr_b16 v[108:109], v167 offset:23552
	s_waitcnt lgkmcnt(6)
	v_mfma_f32_32x32x16_bf16 v[52:67], v[76:79], v[90:93], v[52:67]
	ds_read_b64_tr_b16 v[86:87], v167 offset:25600
	ds_read_b64_tr_b16 v[88:89], v167 offset:27648
	s_waitcnt lgkmcnt(6)
	v_mfma_f32_32x32x16_bf16 v[52:67], v[80:83], v[94:97], v[52:67]
	ds_read_b64_tr_b16 v[90:91], v167 offset:29696
	ds_read_b64_tr_b16 v[92:93], v167 offset:31744
	s_waitcnt lgkmcnt(6)
; #define LAS __attribute__((address_space(3)))
; __device__ __forceinline__ unsigned cvt_pk_bf16(float lo, float hi) { unsigned r; asm volatile("v_cvt_pk_bf16_f32 %0, %1, %2" : "=v"(r) : "v"(lo), "v"(hi)); return r; }
; #define SBAR() __builtin_amdgcn_sched_barrier(0)
; __device__ __forceinline__ int crow(int r, int hi) { return (r & 3) + 8 * (r >> 2) + 4 * hi; }
; #define PV_TILE(VB, C0, C1, alC, PAR) do { s16x4 va_[8], vb_[8]; float ma_ = 0.f, mb_ = 0.f, mn_ = 0.f; VRD8(VB, 0, va_); SBAR(); \
;     PV_BLK(VB, 0, va_, vb_, C0, C1, PAR); if (PAR) { DECIDE(alC); } SBAR(); \
;     PV_BLK(VB, 1, vb_, va_, C0, C1, PAR); PV_BLK(VB, 2, va_, vb_, C0, C1, PAR); PV_BLK(VB, 3, vb_, va_, C0, C1, PAR); } while (0)
; template <int ABL> __device__ __forceinline__ void attn_unit(int b, int h, int qb, const bf16_t* Q, const bf16_t* KV, const bf16_t* KPE, bf16_t* MG, float* ssqa, LAS unsigned char* L) {
;     ...
;   SBAR(); PV_TILE(Vp + SHM_V, pB0, pB1, alB, false);
;   if (hi == 0) li_l[r32] = l_reg; asm volatile("s_waitcnt lgkmcnt(0)" ::: "memory");
;   float rli[16];
; #pragma unroll
;   for (int r = 0; r < 16; ++r) rli[r] = __builtin_amdgcn_rcpf(li_l[crow(r, hi)]);
;   __syncthreads();
;   { LAS bf16_t* stg = (LAS bf16_t*)(L + wid * 8192);
; #pragma unroll
;     for (int r = 0; r < 16; ++r) { const int orow = crow(r, hi);
; #pragma unroll
;       for (int d0 = 0; d0 < 4; ++d0) stg[orow * 128 + d0 * 32 + r32] = (bf16_t)(cvt_pk_bf16(o[d0][r] * rli[r], 0.f) & 0xffffu); }
	v_mfma_f32_32x32x16_bf16 v[36:51], v[68:71], v[102:105], v[36:51]
	ds_read_b64_tr_b16 v[94:95], v167 offset:17920
	ds_read_b64_tr_b16 v[96:97], v167 offset:19968
	s_waitcnt lgkmcnt(6)
	v_mfma_f32_32x32x16_bf16 v[36:51], v[72:75], v[106:109], v[36:51]
	ds_read_b64_tr_b16 v[102:103], v167 offset:22016
	ds_read_b64_tr_b16 v[104:105], v167 offset:24064
	s_waitcnt lgkmcnt(6)
	v_mfma_f32_32x32x16_bf16 v[36:51], v[76:79], v[86:89], v[36:51]
	ds_read_b64_tr_b16 v[106:107], v167 offset:26112
	ds_read_b64_tr_b16 v[108:109], v167 offset:28160
	s_waitcnt lgkmcnt(6)
	v_mfma_f32_32x32x16_bf16 v[36:51], v[80:83], v[90:93], v[36:51]
	ds_read_b64_tr_b16 v[86:87], v167 offset:30208
	ds_read_b64_tr_b16 v[88:89], v167 offset:32256
	s_waitcnt lgkmcnt(6)
	v_mfma_f32_32x32x16_bf16 v[20:35], v[68:71], v[94:97], v[20:35]
	s_waitcnt lgkmcnt(4)
	v_mfma_f32_32x32x16_bf16 v[20:35], v[72:75], v[102:105], v[20:35]
	s_waitcnt lgkmcnt(2)
	v_mfma_f32_32x32x16_bf16 v[20:35], v[76:79], v[106:109], v[20:35]
	s_waitcnt lgkmcnt(0)
	v_mfma_f32_32x32x16_bf16 v[20:35], v[80:83], v[86:89], v[20:35]
	s_and_saveexec_b64 s[54:55], s[0:1]
	v_add_f32_e32 v1, v1, v100
	v_fmac_f32_e32 v1, v2, v204
	v_add_f32_e32 v2, v84, v85
	v_fmac_f32_e32 v2, v1, v101
	ds_write_b32 v166, v2
	s_or_b64 exec, exec, s[54:55]
	s_waitcnt lgkmcnt(0)
	v_add_u32_e32 v1, s57, v165
	ds_read_b128 v[68:71], v1
	ds_read_b128 v[72:75], v1 offset:32
	v_lshlrev_b32_e32 v83, 1, v163
	s_lshl_b32 s0, s56, 8
	s_add_u32 s0, s16, s0
	s_waitcnt lgkmcnt(1)
	v_rcp_f32_e32 v2, v68
	v_rcp_f32_e32 v76, v69
	v_rcp_f32_e32 v77, v70
	v_rcp_f32_e32 v78, v71
	s_waitcnt lgkmcnt(0)
	v_rcp_f32_e32 v79, v72
	ds_read_b128 v[68:71], v1 offset:64
	v_rcp_f32_e32 v80, v73
	v_rcp_f32_e32 v81, v74
	v_rcp_f32_e32 v82, v75
	ds_read_b128 v[72:75], v1 offset:96
	s_waitcnt lgkmcnt(1)
	v_rcp_f32_e32 v1, v68
	v_rcp_f32_e32 v68, v69
	v_rcp_f32_e32 v69, v70
	v_rcp_f32_e32 v70, v71
	s_waitcnt lgkmcnt(0)
	v_rcp_f32_e32 v71, v72
	v_rcp_f32_e32 v72, v73
	v_rcp_f32_e32 v73, v74
	v_rcp_f32_e32 v74, v75
	v_lshlrev_b32_e32 v75, 10, v164
	v_mul_f32_e32 v4, v4, v2
	s_barrier
	v_add3_u32 v75, s6, v75, v83
	v_cvt_pk_bf16_f32 v4, v4, v3
	ds_write_b16 v75, v4
	v_mul_f32_e32 v4, v52, v2
	v_cvt_pk_bf16_f32 v4, v4, v3
	ds_write_b16 v75, v4 offset:64
	v_mul_f32_e32 v4, v36, v2
	v_mul_f32_e32 v2, v20, v2
	v_cvt_pk_bf16_f32 v4, v4, v3
	ds_write_b16 v75, v4 offset:128
	v_cvt_pk_bf16_f32 v2, v2, v3
	ds_write_b16 v75, v2 offset:192
	v_mul_f32_e32 v2, v5, v76
	v_cvt_pk_bf16_f32 v2, v2, v3
	ds_write_b16 v75, v2 offset:256
	v_mul_f32_e32 v2, v53, v76
	v_cvt_pk_bf16_f32 v2, v2, v3
	ds_write_b16 v75, v2 offset:320
	v_mul_f32_e32 v2, v37, v76
	v_cvt_pk_bf16_f32 v2, v2, v3
	ds_write_b16 v75, v2 offset:384
	v_mul_f32_e32 v2, v21, v76
	v_cvt_pk_bf16_f32 v2, v2, v3
	ds_write_b16 v75, v2 offset:448
	v_mul_f32_e32 v2, v6, v77
	v_cvt_pk_bf16_f32 v2, v2, v3
	ds_write_b16 v75, v2 offset:512
	v_mul_f32_e32 v2, v54, v77
	v_cvt_pk_bf16_f32 v2, v2, v3
	ds_write_b16 v75, v2 offset:576
	v_mul_f32_e32 v2, v38, v77
	v_cvt_pk_bf16_f32 v2, v2, v3
	ds_write_b16 v75, v2 offset:640
	v_mul_f32_e32 v2, v22, v77
	v_cvt_pk_bf16_f32 v2, v2, v3
	ds_write_b16 v75, v2 offset:704
	v_mul_f32_e32 v2, v7, v78
	v_cvt_pk_bf16_f32 v2, v2, v3
	ds_write_b16 v75, v2 offset:768
	v_mul_f32_e32 v2, v55, v78
	v_cvt_pk_bf16_f32 v2, v2, v3
	ds_write_b16 v75, v2 offset:832
	v_mul_f32_e32 v2, v39, v78
	v_cvt_pk_bf16_f32 v2, v2, v3
	ds_write_b16 v75, v2 offset:896
	v_mul_f32_e32 v2, v23, v78
	v_cvt_pk_bf16_f32 v2, v2, v3
	ds_write_b16 v75, v2 offset:960
	v_mul_f32_e32 v2, v8, v79
	v_cvt_pk_bf16_f32 v2, v2, v3
	ds_write_b16 v75, v2 offset:2048
	v_mul_f32_e32 v2, v56, v79
	v_cvt_pk_bf16_f32 v2, v2, v3
	ds_write_b16 v75, v2 offset:2112
	v_mul_f32_e32 v2, v40, v79
	v_cvt_pk_bf16_f32 v2, v2, v3
	ds_write_b16 v75, v2 offset:2176
	v_mul_f32_e32 v2, v24, v79
	v_cvt_pk_bf16_f32 v2, v2, v3
	ds_write_b16 v75, v2 offset:2240
	v_mul_f32_e32 v2, v9, v80
	v_cvt_pk_bf16_f32 v2, v2, v3
	ds_write_b16 v75, v2 offset:2304
	v_mul_f32_e32 v2, v57, v80
	v_cvt_pk_bf16_f32 v2, v2, v3
	ds_write_b16 v75, v2 offset:2368
	v_mul_f32_e32 v2, v41, v80
	v_cvt_pk_bf16_f32 v2, v2, v3
	ds_write_b16 v75, v2 offset:2432
	v_mul_f32_e32 v2, v25, v80
	v_cvt_pk_bf16_f32 v2, v2, v3
	ds_write_b16 v75, v2 offset:2496
	v_mul_f32_e32 v2, v10, v81
	v_cvt_pk_bf16_f32 v2, v2, v3
	ds_write_b16 v75, v2 offset:2560
	v_mul_f32_e32 v2, v58, v81
	v_cvt_pk_bf16_f32 v2, v2, v3
	ds_write_b16 v75, v2 offset:2624
	v_mul_f32_e32 v2, v42, v81
	v_cvt_pk_bf16_f32 v2, v2, v3
	ds_write_b16 v75, v2 offset:2688
	v_mul_f32_e32 v2, v26, v81
	v_cvt_pk_bf16_f32 v2, v2, v3
	ds_write_b16 v75, v2 offset:2752
	v_mul_f32_e32 v2, v11, v82
	v_cvt_pk_bf16_f32 v2, v2, v3
	ds_write_b16 v75, v2 offset:2816
	v_mul_f32_e32 v2, v59, v82
	v_cvt_pk_bf16_f32 v2, v2, v3
	ds_write_b16 v75, v2 offset:2880
	v_mul_f32_e32 v2, v43, v82
	v_cvt_pk_bf16_f32 v2, v2, v3
	ds_write_b16 v75, v2 offset:2944
	v_mul_f32_e32 v2, v27, v82
	v_cvt_pk_bf16_f32 v2, v2, v3
	ds_write_b16 v75, v2 offset:3008
	v_mul_f32_e32 v2, v12, v1
	v_cvt_pk_bf16_f32 v2, v2, v3
	ds_write_b16 v75, v2 offset:4096
	v_mul_f32_e32 v2, v60, v1
	v_cvt_pk_bf16_f32 v2, v2, v3
	ds_write_b16 v75, v2 offset:4160
	v_mul_f32_e32 v2, v44, v1
	v_mul_f32_e32 v1, v28, v1
	v_cvt_pk_bf16_f32 v2, v2, v3
	ds_write_b16 v75, v2 offset:4224
	v_cvt_pk_bf16_f32 v1, v1, v3
	ds_write_b16 v75, v1 offset:4288
	v_mul_f32_e32 v1, v13, v68
	v_cvt_pk_bf16_f32 v1, v1, v3
	ds_write_b16 v75, v1 offset:4352
	v_mul_f32_e32 v1, v61, v68
	v_cvt_pk_bf16_f32 v1, v1, v3
	ds_write_b16 v75, v1 offset:4416
	v_mul_f32_e32 v1, v45, v68
	v_cvt_pk_bf16_f32 v1, v1, v3
	ds_write_b16 v75, v1 offset:4480
; #define LAS __attribute__((address_space(3)))
; __device__ __forceinline__ unsigned cvt_pk_bf16(float lo, float hi) { unsigned r; asm volatile("v_cvt_pk_bf16_f32 %0, %1, %2" : "=v"(r) : "v"(lo), "v"(hi)); return r; }
; __device__ __forceinline__ float bf_lo(unsigned w) { return __uint_as_float(w << 16); }
; __device__ __forceinline__ float bf_hi(unsigned w) { return __uint_as_float(w & 0xffff0000u); }
; __device__ __forceinline__ int crow(int r, int hi) { return (r & 3) + 8 * (r >> 2) + 4 * hi; }
; template <int ABL> __device__ __forceinline__ void attn_unit(int b, int h, int qb, const bf16_t* Q, const bf16_t* KV, const bf16_t* KPE, bf16_t* MG, float* ssqa, LAS unsigned char* L) {
;     ...
;     for (int r = 0; r < 16; ++r) { const int orow = crow(r, hi);
; #pragma unroll
;       for (int d0 = 0; d0 < 4; ++d0) stg[orow * 128 + d0 * 32 + r32] = (bf16_t)(cvt_pk_bf16(o[d0][r] * rli[r], 0.f) & 0xffffu); }
;     asm volatile("s_waitcnt lgkmcnt(0)" ::: "memory");
;     int ln2; asm volatile("v_mbcnt_lo_u32_b32 %0, -1, 0\n\tv_mbcnt_hi_u32_b32 %0, -1, %0" : "=v"(ln2));
;     const int lrow = ln2 >> 4, ch = ln2 & 15;
; #pragma unroll
;     for (int i = 0; i < 8; ++i) { const int row = i * 4 + lrow;
;       const u32x4 v = *(const LAS u32x4*)(stg + row * 128 + ch * 8);
;       float ss = 0.f;
; #pragma unroll
;       for (int e = 0; e < 4; ++e) { const float a = bf_lo(v[e]), c = bf_hi(v[e]); ss += a * a + c * c; }
;       ss += __shfl_xor(ss, 1); ss += __shfl_xor(ss, 2); ss += __shfl_xor(ss, 4); ss += __shfl_xor(ss, 8);
;       const size_t grow = rowbase + q0 + wid * QBLK + row;
;       *(u32x4*)(MG + grow * LDO + h * 128 + ch * 8) = v;
;       if (ch == 0) ssqa[grow * 8 + h] = ss; }
	v_mul_f32_e32 v1, v29, v68
	v_cvt_pk_bf16_f32 v1, v1, v3
	ds_write_b16 v75, v1 offset:4544
	v_mul_f32_e32 v1, v14, v69
	v_cvt_pk_bf16_f32 v1, v1, v3
	ds_write_b16 v75, v1 offset:4608
	v_mul_f32_e32 v1, v62, v69
	v_cvt_pk_bf16_f32 v1, v1, v3
	ds_write_b16 v75, v1 offset:4672
	v_mul_f32_e32 v1, v46, v69
	v_cvt_pk_bf16_f32 v1, v1, v3
	ds_write_b16 v75, v1 offset:4736
	v_mul_f32_e32 v1, v30, v69
	v_cvt_pk_bf16_f32 v1, v1, v3
	ds_write_b16 v75, v1 offset:4800
	v_mul_f32_e32 v1, v15, v70
	v_cvt_pk_bf16_f32 v1, v1, v3
	ds_write_b16 v75, v1 offset:4864
	v_mul_f32_e32 v1, v63, v70
	v_cvt_pk_bf16_f32 v1, v1, v3
	ds_write_b16 v75, v1 offset:4928
	v_mul_f32_e32 v1, v47, v70
	v_cvt_pk_bf16_f32 v1, v1, v3
	ds_write_b16 v75, v1 offset:4992
	v_mul_f32_e32 v1, v31, v70
	v_cvt_pk_bf16_f32 v1, v1, v3
	ds_write_b16 v75, v1 offset:5056
	v_mul_f32_e32 v1, v16, v71
	v_cvt_pk_bf16_f32 v1, v1, v3
	ds_write_b16 v75, v1 offset:6144
	v_mul_f32_e32 v1, v64, v71
	v_cvt_pk_bf16_f32 v1, v1, v3
	ds_write_b16 v75, v1 offset:6208
	v_mul_f32_e32 v1, v48, v71
	v_cvt_pk_bf16_f32 v1, v1, v3
	ds_write_b16 v75, v1 offset:6272
	v_mul_f32_e32 v1, v32, v71
	v_cvt_pk_bf16_f32 v1, v1, v3
	ds_write_b16 v75, v1 offset:6336
	v_mul_f32_e32 v1, v17, v72
	v_cvt_pk_bf16_f32 v1, v1, v3
	ds_write_b16 v75, v1 offset:6400
	v_mul_f32_e32 v1, v65, v72
	v_cvt_pk_bf16_f32 v1, v1, v3
	ds_write_b16 v75, v1 offset:6464
	v_mul_f32_e32 v1, v49, v72
	v_cvt_pk_bf16_f32 v1, v1, v3
	ds_write_b16 v75, v1 offset:6528
	v_mul_f32_e32 v1, v33, v72
	v_cvt_pk_bf16_f32 v1, v1, v3
	ds_write_b16 v75, v1 offset:6592
	v_mul_f32_e32 v1, v18, v73
	v_cvt_pk_bf16_f32 v1, v1, v3
	ds_write_b16 v75, v1 offset:6656
	v_mul_f32_e32 v1, v66, v73
	v_cvt_pk_bf16_f32 v1, v1, v3
	ds_write_b16 v75, v1 offset:6720
	v_mul_f32_e32 v1, v50, v73
	v_cvt_pk_bf16_f32 v1, v1, v3
	ds_write_b16 v75, v1 offset:6784
	v_mul_f32_e32 v1, v34, v73
	v_cvt_pk_bf16_f32 v1, v1, v3
	ds_write_b16 v75, v1 offset:6848
	v_mul_f32_e32 v1, v19, v74
	v_cvt_pk_bf16_f32 v1, v1, v3
	ds_write_b16 v75, v1 offset:6912
	v_mul_f32_e32 v1, v67, v74
	v_cvt_pk_bf16_f32 v1, v1, v3
	ds_write_b16 v75, v1 offset:6976
	v_mul_f32_e32 v1, v51, v74
	v_cvt_pk_bf16_f32 v1, v1, v3
	ds_write_b16 v75, v1 offset:7040
	v_mul_f32_e32 v1, v35, v74
	v_cvt_pk_bf16_f32 v1, v1, v3
	ds_write_b16 v75, v1 offset:7104
	s_waitcnt lgkmcnt(0)
	v_mbcnt_lo_u32_b32 v1, -1, 0
	v_mbcnt_hi_u32_b32 v1, -1, v1
	v_and_b32_e32 v6, 64, v162
	v_ashrrev_i32_e32 v4, 4, v1
	v_and_b32_e32 v5, 15, v1
	v_xor_b32_e32 v1, 1, v162
	v_add_u32_e32 v6, 64, v6
	v_cmp_lt_i32_e32 vcc, v1, v6
	v_xor_b32_e32 v7, 2, v162
	v_lshlrev_b32_e32 v2, 4, v5
	v_cndmask_b32_e32 v1, v162, v1, vcc
	v_cmp_lt_i32_e32 vcc, v7, v6
	v_add_u32_e32 v12, s6, v2
	v_lshlrev_b32_e32 v1, 2, v1
	v_cndmask_b32_e32 v7, v162, v7, vcc
	v_lshlrev_b32_e32 v10, 2, v7
	v_lshl_add_u32 v7, v4, 8, v12
	ds_read_b128 v[16:19], v7
	v_xor_b32_e32 v7, 4, v162
	v_cmp_lt_i32_e32 vcc, v7, v6
	s_addc_u32 s1, s17, 0
	s_waitcnt lgkmcnt(0)
	v_and_b32_e32 v8, 0xffff0000, v16
	v_cndmask_b32_e32 v7, v162, v7, vcc
	v_lshlrev_b32_e32 v11, 2, v7
	v_lshlrev_b32_e32 v7, 16, v16
	v_mul_f32_e32 v8, v8, v8
	v_and_b32_e32 v9, 0xffff0000, v17
	v_fmac_f32_e32 v8, v7, v7
	v_lshlrev_b32_e32 v7, 16, v17
	v_mul_f32_e32 v9, v9, v9
	v_fmac_f32_e32 v9, v7, v7
	v_add_f32_e32 v7, v8, v9
	v_and_b32_e32 v9, 0xffff0000, v18
	v_lshlrev_b32_e32 v8, 16, v18
	v_mul_f32_e32 v9, v9, v9
	v_fmac_f32_e32 v9, v8, v8
	v_add_f32_e32 v7, v9, v7
	v_and_b32_e32 v9, 0xffff0000, v19
	v_lshlrev_b32_e32 v8, 16, v19
	v_mul_f32_e32 v9, v9, v9
	v_fmac_f32_e32 v9, v8, v8
	v_add_f32_e32 v7, v9, v7
	ds_bpermute_b32 v8, v1, v7
	v_xor_b32_e32 v9, 8, v162
	v_cmp_lt_i32_e32 vcc, v9, v6
	s_waitcnt lgkmcnt(0)
	v_add_f32_e32 v8, v7, v8
	v_cndmask_b32_e32 v6, v162, v9, vcc
	ds_bpermute_b32 v9, v10, v8
	v_lshlrev_b32_e32 v13, 2, v6
	v_lshl_add_u64 v[6:7], s[0:1], 0, v[2:3]
	v_cmp_eq_u32_e32 vcc, 0, v5
	v_ashrrev_i32_e32 v5, 31, v4
	s_waitcnt lgkmcnt(0)
	v_add_f32_e32 v2, v8, v9
	ds_bpermute_b32 v8, v11, v2
	s_lshl_b32 s0, s56, 2
	s_add_u32 s0, s35, s0
	s_addc_u32 s1, s76, 0
	s_waitcnt lgkmcnt(0)
	v_add_f32_e32 v2, v2, v8
	ds_bpermute_b32 v14, v13, v2
	v_lshl_add_u64 v[8:9], s[70:71], 0, v[4:5]
	v_lshlrev_b64 v[20:21], 12, v[8:9]
	v_lshl_add_u64 v[20:21], v[6:7], 0, v[20:21]
	global_store_dwordx4 v[20:21], v[16:19], off sc1
	s_and_saveexec_b64 s[54:55], vcc
	s_cbranch_execz .LBB0_779
	v_lshlrev_b64 v[8:9], 5, v[8:9]
	s_waitcnt lgkmcnt(0)
	v_add_f32_e32 v2, v2, v14
	v_lshl_add_u64 v[8:9], s[0:1], 0, v[8:9]
	global_store_dword v[8:9], v2, off
.LBB0_779:
	s_or_b64 exec, exec, s[54:55]
	v_add_u32_e32 v8, 4, v4
	v_lshl_add_u32 v2, v8, 8, v12
	s_waitcnt lgkmcnt(0)
	ds_read_b128 v[14:17], v2
	s_waitcnt lgkmcnt(0)
	v_and_b32_e32 v5, 0xffff0000, v14
	v_and_b32_e32 v18, 0xffff0000, v15
	v_lshlrev_b32_e32 v2, 16, v14
	v_lshlrev_b32_e32 v9, 16, v15
	v_mul_f32_e32 v5, v5, v5
	v_mul_f32_e32 v18, v18, v18
	v_fmac_f32_e32 v5, v2, v2
	v_fmac_f32_e32 v18, v9, v9
	v_and_b32_e32 v9, 0xffff0000, v16
	v_add_f32_e32 v2, v5, v18
	v_lshlrev_b32_e32 v5, 16, v16
	v_mul_f32_e32 v9, v9, v9
	v_fmac_f32_e32 v9, v5, v5
	v_add_f32_e32 v2, v9, v2
	v_and_b32_e32 v9, 0xffff0000, v17
	v_lshlrev_b32_e32 v5, 16, v17
	v_mul_f32_e32 v9, v9, v9
	v_fmac_f32_e32 v9, v5, v5
	v_add_f32_e32 v2, v9, v2
	ds_bpermute_b32 v5, v1, v2
	v_ashrrev_i32_e32 v9, 31, v8
	v_lshl_add_u64 v[8:9], s[70:71], 0, v[8:9]
	v_lshlrev_b64 v[18:19], 12, v[8:9]
	v_lshl_add_u64 v[18:19], v[6:7], 0, v[18:19]
	s_waitcnt lgkmcnt(0)
	v_add_f32_e32 v2, v2, v5
	ds_bpermute_b32 v5, v10, v2
	global_store_dwordx4 v[18:19], v[14:17], off sc1
	s_waitcnt lgkmcnt(0)
	v_add_f32_e32 v2, v2, v5
	ds_bpermute_b32 v5, v11, v2
	s_waitcnt lgkmcnt(0)
	v_add_f32_e32 v2, v2, v5
	ds_bpermute_b32 v5, v13, v2
	s_and_saveexec_b64 s[54:55], vcc
	s_cbranch_execz .LBB0_781
	v_lshlrev_b64 v[8:9], 5, v[8:9]
	s_waitcnt lgkmcnt(0)
	v_add_f32_e32 v2, v2, v5
	v_lshl_add_u64 v[8:9], s[0:1], 0, v[8:9]
	global_store_dword v[8:9], v2, off
; #define LAS __attribute__((address_space(3)))
; __device__ __forceinline__ float bf_lo(unsigned w) { return __uint_as_float(w << 16); }
; __device__ __forceinline__ float bf_hi(unsigned w) { return __uint_as_float(w & 0xffff0000u); }
; template <int ABL> __device__ __forceinline__ void attn_unit(int b, int h, int qb, const bf16_t* Q, const bf16_t* KV, const bf16_t* KPE, bf16_t* MG, float* ssqa, LAS unsigned char* L) {
;     ...
; #pragma unroll
;     for (int i = 0; i < 8; ++i) { const int row = i * 4 + lrow;
;       const u32x4 v = *(const LAS u32x4*)(stg + row * 128 + ch * 8);
;       float ss = 0.f;
; #pragma unroll
;       for (int e = 0; e < 4; ++e) { const float a = bf_lo(v[e]), c = bf_hi(v[e]); ss += a * a + c * c; }
;       ss += __shfl_xor(ss, 1); ss += __shfl_xor(ss, 2); ss += __shfl_xor(ss, 4); ss += __shfl_xor(ss, 8);
;       const size_t grow = rowbase + q0 + wid * QBLK + row;
;       *(u32x4*)(MG + grow * LDO + h * 128 + ch * 8) = v;
;       if (ch == 0) ssqa[grow * 8 + h] = ss; }
.LBB0_781:
	s_or_b64 exec, exec, s[54:55]
	v_add_u32_e32 v8, 8, v4
	v_lshl_add_u32 v2, v8, 8, v12
	ds_read_b128 v[14:17], v2
	s_waitcnt lgkmcnt(0)
	v_and_b32_e32 v5, 0xffff0000, v14
	v_and_b32_e32 v18, 0xffff0000, v15
	v_lshlrev_b32_e32 v2, 16, v14
	v_lshlrev_b32_e32 v9, 16, v15
	v_mul_f32_e32 v5, v5, v5
	v_mul_f32_e32 v18, v18, v18
	v_fmac_f32_e32 v5, v2, v2
	v_fmac_f32_e32 v18, v9, v9
	v_and_b32_e32 v9, 0xffff0000, v16
	v_add_f32_e32 v2, v5, v18
	v_lshlrev_b32_e32 v5, 16, v16
	v_mul_f32_e32 v9, v9, v9
	v_fmac_f32_e32 v9, v5, v5
	v_add_f32_e32 v2, v9, v2
	v_and_b32_e32 v9, 0xffff0000, v17
	v_lshlrev_b32_e32 v5, 16, v17
	v_mul_f32_e32 v9, v9, v9
	v_fmac_f32_e32 v9, v5, v5
	v_add_f32_e32 v2, v9, v2
	ds_bpermute_b32 v5, v1, v2
	v_ashrrev_i32_e32 v9, 31, v8
	v_lshl_add_u64 v[8:9], s[70:71], 0, v[8:9]
	v_lshlrev_b64 v[18:19], 12, v[8:9]
	v_lshl_add_u64 v[18:19], v[6:7], 0, v[18:19]
	s_waitcnt lgkmcnt(0)
	v_add_f32_e32 v2, v2, v5
	ds_bpermute_b32 v5, v10, v2
	global_store_dwordx4 v[18:19], v[14:17], off sc1
	s_waitcnt lgkmcnt(0)
	v_add_f32_e32 v2, v2, v5
	ds_bpermute_b32 v5, v11, v2
	s_waitcnt lgkmcnt(0)
	v_add_f32_e32 v2, v2, v5
	ds_bpermute_b32 v5, v13, v2
	s_and_saveexec_b64 s[54:55], vcc
	s_cbranch_execz .LBB0_783
	v_lshlrev_b64 v[8:9], 5, v[8:9]
	s_waitcnt lgkmcnt(0)
	v_add_f32_e32 v2, v2, v5
	v_lshl_add_u64 v[8:9], s[0:1], 0, v[8:9]
	global_store_dword v[8:9], v2, off
.LBB0_783:
	s_or_b64 exec, exec, s[54:55]
	v_add_u32_e32 v8, 12, v4
	v_lshl_add_u32 v2, v8, 8, v12
	ds_read_b128 v[14:17], v2
	s_waitcnt lgkmcnt(0)
	v_and_b32_e32 v5, 0xffff0000, v14
	v_and_b32_e32 v18, 0xffff0000, v15
	v_lshlrev_b32_e32 v2, 16, v14
	v_lshlrev_b32_e32 v9, 16, v15
	v_mul_f32_e32 v5, v5, v5
	v_mul_f32_e32 v18, v18, v18
	v_fmac_f32_e32 v5, v2, v2
	v_fmac_f32_e32 v18, v9, v9
	v_and_b32_e32 v9, 0xffff0000, v16
	v_add_f32_e32 v2, v5, v18
	v_lshlrev_b32_e32 v5, 16, v16
	v_mul_f32_e32 v9, v9, v9
	v_fmac_f32_e32 v9, v5, v5
	v_add_f32_e32 v2, v9, v2
	v_and_b32_e32 v9, 0xffff0000, v17
	v_lshlrev_b32_e32 v5, 16, v17
	v_mul_f32_e32 v9, v9, v9
	v_fmac_f32_e32 v9, v5, v5
	v_add_f32_e32 v2, v9, v2
	ds_bpermute_b32 v5, v1, v2
	v_ashrrev_i32_e32 v9, 31, v8
	v_lshl_add_u64 v[8:9], s[70:71], 0, v[8:9]
	v_lshlrev_b64 v[18:19], 12, v[8:9]
	v_lshl_add_u64 v[18:19], v[6:7], 0, v[18:19]
	s_waitcnt lgkmcnt(0)
	v_add_f32_e32 v2, v2, v5
	ds_bpermute_b32 v5, v10, v2
	global_store_dwordx4 v[18:19], v[14:17], off sc1
	s_waitcnt lgkmcnt(0)
	v_add_f32_e32 v2, v2, v5
	ds_bpermute_b32 v5, v11, v2
	s_waitcnt lgkmcnt(0)
	v_add_f32_e32 v2, v2, v5
	ds_bpermute_b32 v5, v13, v2
	s_and_saveexec_b64 s[54:55], vcc
	s_cbranch_execz .LBB0_785
	v_lshlrev_b64 v[8:9], 5, v[8:9]
	s_waitcnt lgkmcnt(0)
	v_add_f32_e32 v2, v2, v5
	v_lshl_add_u64 v[8:9], s[0:1], 0, v[8:9]
	global_store_dword v[8:9], v2, off
.LBB0_785:
	s_or_b64 exec, exec, s[54:55]
	v_add_u32_e32 v8, 16, v4
	v_lshl_add_u32 v2, v8, 8, v12
	ds_read_b128 v[14:17], v2
	s_waitcnt lgkmcnt(0)
	v_and_b32_e32 v5, 0xffff0000, v14
	v_and_b32_e32 v18, 0xffff0000, v15
	v_lshlrev_b32_e32 v2, 16, v14
	v_lshlrev_b32_e32 v9, 16, v15
	v_mul_f32_e32 v5, v5, v5
	v_mul_f32_e32 v18, v18, v18
	v_fmac_f32_e32 v5, v2, v2
	v_fmac_f32_e32 v18, v9, v9
	v_and_b32_e32 v9, 0xffff0000, v16
	v_add_f32_e32 v2, v5, v18
	v_lshlrev_b32_e32 v5, 16, v16
	v_mul_f32_e32 v9, v9, v9
	v_fmac_f32_e32 v9, v5, v5
	v_add_f32_e32 v2, v9, v2
	v_and_b32_e32 v9, 0xffff0000, v17
	v_lshlrev_b32_e32 v5, 16, v17
	v_mul_f32_e32 v9, v9, v9
	v_fmac_f32_e32 v9, v5, v5
	v_add_f32_e32 v2, v9, v2
	ds_bpermute_b32 v5, v1, v2
	v_ashrrev_i32_e32 v9, 31, v8
	v_lshl_add_u64 v[8:9], s[70:71], 0, v[8:9]
	v_lshlrev_b64 v[18:19], 12, v[8:9]
	v_lshl_add_u64 v[18:19], v[6:7], 0, v[18:19]
	s_waitcnt lgkmcnt(0)
	v_add_f32_e32 v2, v2, v5
	ds_bpermute_b32 v5, v10, v2
	global_store_dwordx4 v[18:19], v[14:17], off sc1
	s_waitcnt lgkmcnt(0)
	v_add_f32_e32 v2, v2, v5
	ds_bpermute_b32 v5, v11, v2
	s_waitcnt lgkmcnt(0)
	v_add_f32_e32 v2, v2, v5
	ds_bpermute_b32 v5, v13, v2
	s_and_saveexec_b64 s[54:55], vcc
	s_cbranch_execz .LBB0_787
	v_lshlrev_b64 v[8:9], 5, v[8:9]
	s_waitcnt lgkmcnt(0)
	v_add_f32_e32 v2, v2, v5
	v_lshl_add_u64 v[8:9], s[0:1], 0, v[8:9]
	global_store_dword v[8:9], v2, off
; #define LAS __attribute__((address_space(3)))
; __device__ __forceinline__ float bf_lo(unsigned w) { return __uint_as_float(w << 16); }
; __device__ __forceinline__ float bf_hi(unsigned w) { return __uint_as_float(w & 0xffff0000u); }
; template <int ABL> __device__ __forceinline__ void attn_unit(int b, int h, int qb, const bf16_t* Q, const bf16_t* KV, const bf16_t* KPE, bf16_t* MG, float* ssqa, LAS unsigned char* L) {
;     ...
; #pragma unroll
;     for (int i = 0; i < 8; ++i) { const int row = i * 4 + lrow;
;       const u32x4 v = *(const LAS u32x4*)(stg + row * 128 + ch * 8);
;       float ss = 0.f;
; #pragma unroll
;       for (int e = 0; e < 4; ++e) { const float a = bf_lo(v[e]), c = bf_hi(v[e]); ss += a * a + c * c; }
;       ss += __shfl_xor(ss, 1); ss += __shfl_xor(ss, 2); ss += __shfl_xor(ss, 4); ss += __shfl_xor(ss, 8);
;       const size_t grow = rowbase + q0 + wid * QBLK + row;
;       *(u32x4*)(MG + grow * LDO + h * 128 + ch * 8) = v;
;       if (ch == 0) ssqa[grow * 8 + h] = ss; }
.LBB0_787:
	s_or_b64 exec, exec, s[54:55]
	v_add_u32_e32 v8, 20, v4
	v_lshl_add_u32 v2, v8, 8, v12
	ds_read_b128 v[14:17], v2
	s_waitcnt lgkmcnt(0)
	v_and_b32_e32 v5, 0xffff0000, v14
	v_and_b32_e32 v18, 0xffff0000, v15
	v_lshlrev_b32_e32 v2, 16, v14
	v_lshlrev_b32_e32 v9, 16, v15
	v_mul_f32_e32 v5, v5, v5
	v_mul_f32_e32 v18, v18, v18
	v_fmac_f32_e32 v5, v2, v2
	v_fmac_f32_e32 v18, v9, v9
	v_and_b32_e32 v9, 0xffff0000, v16
	v_add_f32_e32 v2, v5, v18
	v_lshlrev_b32_e32 v5, 16, v16
	v_mul_f32_e32 v9, v9, v9
	v_fmac_f32_e32 v9, v5, v5
	v_add_f32_e32 v2, v9, v2
	v_and_b32_e32 v9, 0xffff0000, v17
	v_lshlrev_b32_e32 v5, 16, v17
	v_mul_f32_e32 v9, v9, v9
	v_fmac_f32_e32 v9, v5, v5
	v_add_f32_e32 v2, v9, v2
	ds_bpermute_b32 v5, v1, v2
	v_ashrrev_i32_e32 v9, 31, v8
	v_lshl_add_u64 v[8:9], s[70:71], 0, v[8:9]
	v_lshlrev_b64 v[18:19], 12, v[8:9]
	v_lshl_add_u64 v[18:19], v[6:7], 0, v[18:19]
	s_waitcnt lgkmcnt(0)
	v_add_f32_e32 v2, v2, v5
	ds_bpermute_b32 v5, v10, v2
	global_store_dwordx4 v[18:19], v[14:17], off sc1
	s_waitcnt lgkmcnt(0)
	v_add_f32_e32 v2, v2, v5
	ds_bpermute_b32 v5, v11, v2
	s_waitcnt lgkmcnt(0)
	v_add_f32_e32 v2, v2, v5
	ds_bpermute_b32 v5, v13, v2
	s_and_saveexec_b64 s[54:55], vcc
	s_cbranch_execz .LBB0_789
	v_lshlrev_b64 v[8:9], 5, v[8:9]
	s_waitcnt lgkmcnt(0)
	v_add_f32_e32 v2, v2, v5
	v_lshl_add_u64 v[8:9], s[0:1], 0, v[8:9]
	global_store_dword v[8:9], v2, off
.LBB0_789:
	s_or_b64 exec, exec, s[54:55]
	v_add_u32_e32 v8, 24, v4
	v_lshl_add_u32 v2, v8, 8, v12
	ds_read_b128 v[14:17], v2
	s_waitcnt lgkmcnt(0)
	v_and_b32_e32 v5, 0xffff0000, v14
	v_and_b32_e32 v18, 0xffff0000, v15
	v_lshlrev_b32_e32 v2, 16, v14
	v_lshlrev_b32_e32 v9, 16, v15
	v_mul_f32_e32 v5, v5, v5
	v_mul_f32_e32 v18, v18, v18
	v_fmac_f32_e32 v5, v2, v2
	v_fmac_f32_e32 v18, v9, v9
	v_and_b32_e32 v9, 0xffff0000, v16
	v_add_f32_e32 v2, v5, v18
	v_lshlrev_b32_e32 v5, 16, v16
	v_mul_f32_e32 v9, v9, v9
	v_fmac_f32_e32 v9, v5, v5
	v_add_f32_e32 v2, v9, v2
	v_and_b32_e32 v9, 0xffff0000, v17
	v_lshlrev_b32_e32 v5, 16, v17
	v_mul_f32_e32 v9, v9, v9
	v_fmac_f32_e32 v9, v5, v5
	v_add_f32_e32 v2, v9, v2
	ds_bpermute_b32 v5, v1, v2
	v_ashrrev_i32_e32 v9, 31, v8
	v_lshl_add_u64 v[8:9], s[70:71], 0, v[8:9]
	v_lshlrev_b64 v[18:19], 12, v[8:9]
	v_lshl_add_u64 v[18:19], v[6:7], 0, v[18:19]
	s_waitcnt lgkmcnt(0)
	v_add_f32_e32 v2, v2, v5
	ds_bpermute_b32 v5, v10, v2
	global_store_dwordx4 v[18:19], v[14:17], off sc1
	s_waitcnt lgkmcnt(0)
	v_add_f32_e32 v2, v2, v5
	ds_bpermute_b32 v5, v11, v2
	s_waitcnt lgkmcnt(0)
	v_add_f32_e32 v2, v2, v5
	ds_bpermute_b32 v5, v13, v2
	s_and_saveexec_b64 s[54:55], vcc
	s_cbranch_execz .LBB0_791
	v_lshlrev_b64 v[8:9], 5, v[8:9]
	s_waitcnt lgkmcnt(0)
	v_add_f32_e32 v2, v2, v5
	v_lshl_add_u64 v[8:9], s[0:1], 0, v[8:9]
	global_store_dword v[8:9], v2, off
.LBB0_791:
	s_or_b64 exec, exec, s[54:55]
	v_add_u32_e32 v4, 28, v4
	v_lshl_add_u32 v2, v4, 8, v12
	ds_read_b128 v[14:17], v2
	s_waitcnt lgkmcnt(0)
	v_and_b32_e32 v5, 0xffff0000, v14
	v_and_b32_e32 v9, 0xffff0000, v15
	v_lshlrev_b32_e32 v2, 16, v14
	v_lshlrev_b32_e32 v8, 16, v15
	v_mul_f32_e32 v5, v5, v5
	v_mul_f32_e32 v9, v9, v9
	v_fmac_f32_e32 v5, v2, v2
	v_fmac_f32_e32 v9, v8, v8
	v_and_b32_e32 v8, 0xffff0000, v16
	v_add_f32_e32 v2, v5, v9
	v_lshlrev_b32_e32 v5, 16, v16
	v_mul_f32_e32 v8, v8, v8
	v_fmac_f32_e32 v8, v5, v5
	v_add_f32_e32 v2, v8, v2
	v_and_b32_e32 v8, 0xffff0000, v17
	v_lshlrev_b32_e32 v5, 16, v17
	v_mul_f32_e32 v8, v8, v8
	v_fmac_f32_e32 v8, v5, v5
	v_add_f32_e32 v2, v8, v2
	ds_bpermute_b32 v1, v1, v2
	v_ashrrev_i32_e32 v5, 31, v4
	v_lshl_add_u64 v[4:5], s[70:71], 0, v[4:5]
	v_lshlrev_b64 v[8:9], 12, v[4:5]
	v_lshl_add_u64 v[6:7], v[6:7], 0, v[8:9]
	s_waitcnt lgkmcnt(0)
	v_add_f32_e32 v1, v2, v1
	ds_bpermute_b32 v2, v10, v1
	global_store_dwordx4 v[6:7], v[14:17], off sc1
	s_waitcnt lgkmcnt(0)
	v_add_f32_e32 v1, v1, v2
	ds_bpermute_b32 v2, v11, v1
	s_waitcnt lgkmcnt(0)
	v_add_f32_e32 v1, v1, v2
	ds_bpermute_b32 v2, v13, v1
	s_and_saveexec_b64 s[54:55], vcc
	s_cbranch_execz .LBB0_745
	v_lshlrev_b64 v[4:5], 5, v[4:5]
	s_waitcnt lgkmcnt(0)
	v_add_f32_e32 v1, v1, v2
	v_lshl_add_u64 v[4:5], s[0:1], 0, v[4:5]
	global_store_dword v[4:5], v1, off
	s_branch .LBB0_745

; #define LAS __attribute__((address_space(3)))
; __device__ __forceinline__ unsigned cvt_pk_bf16(float lo, float hi) { unsigned r; asm volatile("v_cvt_pk_bf16_f32 %0, %1, %2" : "=v"(r) : "v"(lo), "v"(hi)); return r; }
; __device__ __forceinline__ int fresh_lane() { int l; asm volatile("v_mbcnt_lo_u32_b32 %0, -1, 0\n\tv_mbcnt_hi_u32_b32 %0, -1, %0" : "=v"(l)); return l; }
;     __device__ __forceinline__ void operator()(Acc& acc, const Unit& u, int, int, int wr, int wc, int fr, int fq, LAS unsigned char*) const {
;         { const int ln_ = fresh_lane(); fr = ln_ & 15; fq = ln_ >> 4; }
; #pragma unroll
;         for (int ai = 0; ai < 2; ++ai)
; #pragma unroll
;             for (int m = 0; m < 4; ++m) {
;                 const size_t row = (size_t)u.pm * BM + TROW(ai, m); const size_t off = row * DM + u.pn * BM + wc * 32 + 8 * fq; float ss = 0.f;
; #pragma unroll
;                 for (int bj = 0; bj < 2; ++bj) { const f32x4 o0 = acc[ai][bj][m][0], o1 = acc[ai][bj][m][1];
;                     ss += (o0[0] * o0[0] + o0[1] * o0[1]) + (o0[2] * o0[2] + o0[3] * o0[3]) + (o1[0] * o1[0] + o1[1] * o1[1]) + (o1[2] * o1[2] + o1[3] * o1[3]);
;                     u32x4 w; w.x = cvt_pk_bf16(o0[0], o0[1]); w.y = cvt_pk_bf16(o0[2], o0[3]); w.z = cvt_pk_bf16(o1[0], o1[1]); w.w = cvt_pk_bf16(o1[2], o1[3]); *(u32x4*)(x1b + off + bj * HALF) = w; }
;                 ss += __shfl_xor(ss, 16); ss += __shfl_xor(ss, 32); if (fq == 0) ssq2[row * 32 + u.pn * 4 + wc] = ss;
;             }
;     }
.LBB0_871:
	v_mul_f32_e32 v147, v3, v3
	v_mul_f32_e32 v148, v5, v5
	v_fmac_f32_e32 v147, v2, v2
	v_fmac_f32_e32 v148, v4, v4
	v_add_f32_e32 v147, v147, v148
	v_mul_f32_e32 v148, v23, v23
	v_fmac_f32_e32 v148, v22, v22
	v_add_f32_e32 v147, v147, v148
	v_mul_f32_e32 v148, v25, v25
	v_fmac_f32_e32 v148, v24, v24
	v_mbcnt_lo_u32_b32 v138, -1, 0
	v_mbcnt_hi_u32_b32 v138, -1, v138
	v_add_f32_e32 v147, v148, v147
	v_cvt_pk_bf16_f32 v148, v2, v3
	v_cvt_pk_bf16_f32 v149, v4, v5
	v_mul_f32_e32 v4, v11, v11
	v_mul_f32_e32 v5, v13, v13
	v_fmac_f32_e32 v4, v10, v10
	v_fmac_f32_e32 v5, v12, v12
	v_add_f32_e32 v4, v4, v5
	v_mul_f32_e32 v5, v31, v31
	v_fmac_f32_e32 v5, v30, v30
	v_add_f32_e32 v4, v4, v5
	v_mul_f32_e32 v5, v33, v33
	v_fmac_f32_e32 v5, v32, v32
	s_ashr_i32 s39, s38, 31
	v_cvt_pk_bf16_f32 v150, v22, v23
	v_add_f32_e32 v4, v5, v4
	v_and_b32_e32 v22, 64, v145
	v_and_or_b32 v130, v138, 15, s3
	s_lshl_b64 s[64:65], s[38:39], 8
	v_cvt_pk_bf16_f32 v151, v24, v25
	v_add_f32_e32 v5, v147, v4
	v_xor_b32_e32 v4, 16, v145
	v_add_u32_e32 v24, 64, v22
	v_ashrrev_i32_e32 v136, 1, v138
	v_cmp_gt_u32_e32 vcc, 16, v138
	v_lshl_add_u64 v[138:139], s[64:65], 0, v[130:131]
	v_cmp_lt_i32_e64 s[4:5], v4, v24
	s_lshl_b32 s62, s40, 8
	v_lshlrev_b64 v[152:153], 12, v[138:139]
	v_cndmask_b32_e64 v4, v145, v4, s[4:5]
	s_ashr_i32 s63, s62, 31
	v_lshl_add_u64 v[2:3], s[14:15], 0, v[152:153]
	v_lshlrev_b32_e32 v4, 2, v4
	v_and_b32_e32 v136, -8, v136
	v_lshl_add_u64 v[2:3], s[62:63], 1, v[2:3]
	ds_bpermute_b32 v25, v4, v5
	v_ashrrev_i32_e32 v137, 31, v136
	v_lshl_add_u64 v[2:3], v[2:3], 0, s[10:11]
	v_lshl_add_u64 v[22:23], v[136:137], 1, v[2:3]
	v_xor_b32_e32 v3, 32, v145
	v_cmp_lt_i32_e64 s[4:5], v3, v24
	s_waitcnt lgkmcnt(0)
	v_add_f32_e32 v2, v5, v25
	global_store_dwordx4 v[22:23], v[148:151], off sc1
	v_cndmask_b32_e64 v3, v145, v3, s[4:5]
	v_lshlrev_b32_e32 v5, 2, v3
	ds_bpermute_b32 v3, v5, v2
	v_cvt_pk_bf16_f32 v10, v10, v11
	v_cvt_pk_bf16_f32 v11, v12, v13
	v_cvt_pk_bf16_f32 v12, v30, v31
	v_cvt_pk_bf16_f32 v13, v32, v33
	global_store_dwordx4 v[22:23], v[10:13], off offset:256 sc1
	s_and_saveexec_b64 s[4:5], vcc
	s_cbranch_execz .LBB0_873
	s_waitcnt lgkmcnt(0)
	v_add_f32_e32 v10, v2, v3
	s_lshl_b32 s54, s40, 2
	v_lshlrev_b64 v[2:3], 7, v[138:139]
	s_ashr_i32 s55, s54, 31
	v_lshl_add_u64 v[2:3], s[22:23], 0, v[2:3]
	v_lshl_add_u64 v[2:3], s[54:55], 2, v[2:3]
	s_lshl_b32 s54, s2, 2
	s_mov_b32 s55, s11
	v_lshl_add_u64 v[2:3], v[2:3], 0, s[54:55]
	global_store_dword v[2:3], v10, off
.LBB0_873:
	s_or_b64 exec, exec, s[4:5]
	v_mul_f32_e32 v12, v7, v7
	v_mul_f32_e32 v13, v9, v9
	v_fmac_f32_e32 v12, v6, v6
	v_fmac_f32_e32 v13, v8, v8
	v_add_f32_e32 v12, v12, v13
	v_mul_f32_e32 v13, v27, v27
	v_fmac_f32_e32 v13, v26, v26
	v_add_f32_e32 v12, v12, v13
	v_mul_f32_e32 v13, v29, v29
	v_fmac_f32_e32 v13, v28, v28
	v_add_f32_e32 v12, v13, v12
	v_mul_f32_e32 v13, v19, v19
	v_mul_f32_e32 v22, v21, v21
	v_fmac_f32_e32 v13, v18, v18
	v_fmac_f32_e32 v22, v20, v20
	v_add_f32_e32 v13, v13, v22
	v_mul_f32_e32 v22, v47, v47
	v_fmac_f32_e32 v22, v46, v46
	v_add_f32_e32 v13, v13, v22
	v_mul_f32_e32 v22, v49, v49
	v_fmac_f32_e32 v22, v48, v48
	v_or_b32_e32 v2, 16, v130
	s_waitcnt lgkmcnt(0)
	v_mov_b32_e32 v3, v131
	v_add_f32_e32 v13, v22, v13
	v_lshl_add_u64 v[2:3], s[64:65], 0, v[2:3]
	v_add_f32_e32 v22, v12, v13
	v_lshlrev_b64 v[10:11], 12, v[2:3]
	ds_bpermute_b32 v23, v4, v22
	v_lshl_add_u64 v[10:11], s[14:15], 0, v[10:11]
	v_lshl_add_u64 v[10:11], s[62:63], 1, v[10:11]
	v_lshl_add_u64 v[10:11], v[10:11], 0, s[10:11]
	v_cvt_pk_bf16_f32 v6, v6, v7
	v_lshl_add_u64 v[12:13], v[136:137], 1, v[10:11]
	v_cvt_pk_bf16_f32 v7, v8, v9
	v_cvt_pk_bf16_f32 v8, v26, v27
	v_cvt_pk_bf16_f32 v9, v28, v29
	global_store_dwordx4 v[12:13], v[6:9], off sc1
	s_waitcnt lgkmcnt(0)
	s_nop 0
	v_add_f32_e32 v6, v22, v23
	ds_bpermute_b32 v7, v5, v6
	v_cvt_pk_bf16_f32 v8, v18, v19
	v_cvt_pk_bf16_f32 v9, v20, v21
	v_cvt_pk_bf16_f32 v10, v46, v47
	v_cvt_pk_bf16_f32 v11, v48, v49
	global_store_dwordx4 v[12:13], v[8:11], off offset:256 sc1
	s_and_saveexec_b64 s[4:5], vcc
	s_cbranch_execz .LBB0_875
	s_lshl_b32 s54, s40, 2
	v_lshlrev_b64 v[2:3], 7, v[2:3]
	s_ashr_i32 s55, s54, 31
	v_lshl_add_u64 v[2:3], s[22:23], 0, v[2:3]
	v_lshl_add_u64 v[2:3], s[54:55], 2, v[2:3]
	s_lshl_b32 s54, s2, 2
	s_mov_b32 s55, s11
	s_waitcnt lgkmcnt(0)
	v_add_f32_e32 v6, v6, v7
	v_lshl_add_u64 v[2:3], v[2:3], 0, s[54:55]
	global_store_dword v[2:3], v6, off
.LBB0_875:
	s_or_b64 exec, exec, s[4:5]
	v_mul_f32_e32 v6, v15, v15
	s_waitcnt lgkmcnt(0)
	v_mul_f32_e32 v7, v17, v17
	v_fmac_f32_e32 v6, v14, v14
	v_fmac_f32_e32 v7, v16, v16
	v_add_f32_e32 v6, v6, v7
	v_mul_f32_e32 v7, v43, v43
	v_fmac_f32_e32 v7, v42, v42
	v_add_f32_e32 v6, v6, v7
	v_mul_f32_e32 v7, v45, v45
	v_fmac_f32_e32 v7, v44, v44
	v_add_f32_e32 v12, v7, v6
	v_cvt_pk_bf16_f32 v6, v14, v15
	v_mul_f32_e32 v13, v39, v39
	v_mul_f32_e32 v14, v41, v41
	v_fmac_f32_e32 v13, v38, v38
	v_fmac_f32_e32 v14, v40, v40
	v_add_f32_e32 v13, v13, v14
	v_mul_f32_e32 v14, v59, v59
	v_fmac_f32_e32 v14, v58, v58
	v_add_f32_e32 v13, v13, v14
	v_mul_f32_e32 v14, v61, v61
	v_fmac_f32_e32 v14, v60, v60
	v_or_b32_e32 v2, 32, v130
	v_mov_b32_e32 v3, v131
	v_add_f32_e32 v13, v14, v13
	v_lshl_add_u64 v[2:3], s[64:65], 0, v[2:3]
	v_add_f32_e32 v14, v12, v13
	v_lshlrev_b64 v[10:11], 12, v[2:3]
	ds_bpermute_b32 v15, v4, v14
	v_lshl_add_u64 v[10:11], s[14:15], 0, v[10:11]
	v_lshl_add_u64 v[10:11], s[62:63], 1, v[10:11]
	v_lshl_add_u64 v[10:11], v[10:11], 0, s[10:11]
	v_lshl_add_u64 v[12:13], v[136:137], 1, v[10:11]
	v_cvt_pk_bf16_f32 v7, v16, v17
	v_cvt_pk_bf16_f32 v8, v42, v43
	v_cvt_pk_bf16_f32 v9, v44, v45
	global_store_dwordx4 v[12:13], v[6:9], off sc1
	s_waitcnt lgkmcnt(0)
	s_nop 0
	v_add_f32_e32 v6, v14, v15
	ds_bpermute_b32 v7, v5, v6
	v_cvt_pk_bf16_f32 v8, v38, v39
	v_cvt_pk_bf16_f32 v9, v40, v41
	v_cvt_pk_bf16_f32 v10, v58, v59
	v_cvt_pk_bf16_f32 v11, v60, v61
	global_store_dwordx4 v[12:13], v[8:11], off offset:256 sc1
	s_and_saveexec_b64 s[4:5], vcc
	s_cbranch_execz .LBB0_877
	s_lshl_b32 s54, s40, 2
	v_lshlrev_b64 v[2:3], 7, v[2:3]
	s_ashr_i32 s55, s54, 31
	v_lshl_add_u64 v[2:3], s[22:23], 0, v[2:3]
	v_lshl_add_u64 v[2:3], s[54:55], 2, v[2:3]
	s_lshl_b32 s54, s2, 2
	s_mov_b32 s55, s11
	s_waitcnt lgkmcnt(0)
	v_add_f32_e32 v6, v6, v7
	v_lshl_add_u64 v[2:3], v[2:3], 0, s[54:55]
	global_store_dword v[2:3], v6, off
; #define LAS __attribute__((address_space(3)))
; __device__ __forceinline__ unsigned cvt_pk_bf16(float lo, float hi) { unsigned r; asm volatile("v_cvt_pk_bf16_f32 %0, %1, %2" : "=v"(r) : "v"(lo), "v"(hi)); return r; }
; __device__ __forceinline__ int fresh_lane() { int l; asm volatile("v_mbcnt_lo_u32_b32 %0, -1, 0\n\tv_mbcnt_hi_u32_b32 %0, -1, %0" : "=v"(l)); return l; }
;     __device__ __forceinline__ void operator()(Acc& acc, const Unit& u, int, int, int wr, int wc, int fr, int fq, LAS unsigned char*) const {
;         { const int ln_ = fresh_lane(); fr = ln_ & 15; fq = ln_ >> 4; }
; #pragma unroll
;         for (int ai = 0; ai < 2; ++ai)
; #pragma unroll
;             for (int m = 0; m < 4; ++m) {
;                 const size_t row = (size_t)u.pm * BM + TROW(ai, m); const size_t off = row * DM + u.pn * BM + wc * 32 + 8 * fq; float ss = 0.f;
; #pragma unroll
;                 for (int bj = 0; bj < 2; ++bj) { const f32x4 o0 = acc[ai][bj][m][0], o1 = acc[ai][bj][m][1];
;                     ss += (o0[0] * o0[0] + o0[1] * o0[1]) + (o0[2] * o0[2] + o0[3] * o0[3]) + (o1[0] * o1[0] + o1[1] * o1[1]) + (o1[2] * o1[2] + o1[3] * o1[3]);
;                     u32x4 w; w.x = cvt_pk_bf16(o0[0], o0[1]); w.y = cvt_pk_bf16(o0[2], o0[3]); w.z = cvt_pk_bf16(o1[0], o1[1]); w.w = cvt_pk_bf16(o1[2], o1[3]); *(u32x4*)(x1b + off + bj * HALF) = w; }
;                 ss += __shfl_xor(ss, 16); ss += __shfl_xor(ss, 32); if (fq == 0) ssq2[row * 32 + u.pn * 4 + wc] = ss;
;             }
;     }
.LBB0_877:
	s_or_b64 exec, exec, s[4:5]
	v_mul_f32_e32 v6, v35, v35
	s_waitcnt lgkmcnt(0)
	v_mul_f32_e32 v7, v37, v37
	v_mul_f32_e32 v13, v51, v51
	v_mul_f32_e32 v14, v53, v53
	v_fmac_f32_e32 v6, v34, v34
	v_fmac_f32_e32 v7, v36, v36
	v_fmac_f32_e32 v13, v50, v50
	v_fmac_f32_e32 v14, v52, v52
	v_add_f32_e32 v6, v6, v7
	v_mul_f32_e32 v7, v55, v55
	v_add_f32_e32 v13, v13, v14
	v_mul_f32_e32 v14, v67, v67
	v_fmac_f32_e32 v7, v54, v54
	v_fmac_f32_e32 v14, v66, v66
	v_add_f32_e32 v6, v6, v7
	v_mul_f32_e32 v7, v57, v57
	v_add_f32_e32 v13, v13, v14
	v_mul_f32_e32 v14, v69, v69
	v_fmac_f32_e32 v7, v56, v56
	v_fmac_f32_e32 v14, v68, v68
	v_or_b32_e32 v2, 48, v130
	v_mov_b32_e32 v3, v131
	v_add_f32_e32 v12, v7, v6
	v_add_f32_e32 v13, v14, v13
	v_lshl_add_u64 v[2:3], s[64:65], 0, v[2:3]
	v_add_f32_e32 v14, v12, v13
	v_lshlrev_b64 v[10:11], 12, v[2:3]
	ds_bpermute_b32 v15, v4, v14
	v_lshl_add_u64 v[10:11], s[14:15], 0, v[10:11]
	v_lshl_add_u64 v[10:11], s[62:63], 1, v[10:11]
	v_lshl_add_u64 v[10:11], v[10:11], 0, s[10:11]
	v_cvt_pk_bf16_f32 v6, v34, v35
	v_lshl_add_u64 v[12:13], v[136:137], 1, v[10:11]
	v_cvt_pk_bf16_f32 v7, v36, v37
	v_cvt_pk_bf16_f32 v8, v54, v55
	v_cvt_pk_bf16_f32 v9, v56, v57
	global_store_dwordx4 v[12:13], v[6:9], off sc1
	s_waitcnt lgkmcnt(0)
	s_nop 0
	v_add_f32_e32 v6, v14, v15
	ds_bpermute_b32 v7, v5, v6
	v_cvt_pk_bf16_f32 v8, v50, v51
	v_cvt_pk_bf16_f32 v9, v52, v53
	v_cvt_pk_bf16_f32 v10, v66, v67
	v_cvt_pk_bf16_f32 v11, v68, v69
	global_store_dwordx4 v[12:13], v[8:11], off offset:256 sc1
	s_and_saveexec_b64 s[4:5], vcc
	s_cbranch_execz .LBB0_879
	s_lshl_b32 s54, s40, 2
	v_lshlrev_b64 v[2:3], 7, v[2:3]
	s_ashr_i32 s55, s54, 31
	v_lshl_add_u64 v[2:3], s[22:23], 0, v[2:3]
	v_lshl_add_u64 v[2:3], s[54:55], 2, v[2:3]
	s_lshl_b32 s54, s2, 2
	s_mov_b32 s55, s11
	s_waitcnt lgkmcnt(0)
	v_add_f32_e32 v6, v6, v7
	v_lshl_add_u64 v[2:3], v[2:3], 0, s[54:55]
	global_store_dword v[2:3], v6, off
.LBB0_879:
	s_or_b64 exec, exec, s[4:5]
	v_mul_f32_e32 v6, v63, v63
	s_waitcnt lgkmcnt(0)
	v_mul_f32_e32 v7, v65, v65
	v_mul_f32_e32 v13, v75, v75
	v_mul_f32_e32 v14, v77, v77
	v_fmac_f32_e32 v6, v62, v62
	v_fmac_f32_e32 v7, v64, v64
	v_fmac_f32_e32 v13, v74, v74
	v_fmac_f32_e32 v14, v76, v76
	v_add_f32_e32 v6, v6, v7
	v_mul_f32_e32 v7, v79, v79
	v_add_f32_e32 v13, v13, v14
	v_mul_f32_e32 v14, v95, v95
	v_fmac_f32_e32 v7, v78, v78
	v_fmac_f32_e32 v14, v94, v94
	v_add_f32_e32 v6, v6, v7
	v_mul_f32_e32 v7, v81, v81
	v_add_f32_e32 v13, v13, v14
	v_mul_f32_e32 v14, v97, v97
	v_fmac_f32_e32 v7, v80, v80
	v_fmac_f32_e32 v14, v96, v96
	v_add_u32_e32 v2, 0x80, v130
	v_mov_b32_e32 v3, v131
	v_add_f32_e32 v12, v7, v6
	v_add_f32_e32 v13, v14, v13
	v_lshl_add_u64 v[2:3], s[64:65], 0, v[2:3]
	v_add_f32_e32 v14, v12, v13
	v_lshlrev_b64 v[10:11], 12, v[2:3]
	ds_bpermute_b32 v15, v4, v14
	v_lshl_add_u64 v[10:11], s[14:15], 0, v[10:11]
	v_lshl_add_u64 v[10:11], s[62:63], 1, v[10:11]
	v_lshl_add_u64 v[10:11], v[10:11], 0, s[10:11]
	v_cvt_pk_bf16_f32 v6, v62, v63
	v_lshl_add_u64 v[12:13], v[136:137], 1, v[10:11]
	v_cvt_pk_bf16_f32 v7, v64, v65
	v_cvt_pk_bf16_f32 v8, v78, v79
	v_cvt_pk_bf16_f32 v9, v80, v81
	global_store_dwordx4 v[12:13], v[6:9], off sc1
	s_waitcnt lgkmcnt(0)
	s_nop 0
	v_add_f32_e32 v6, v14, v15
	ds_bpermute_b32 v7, v5, v6
	v_cvt_pk_bf16_f32 v8, v74, v75
	v_cvt_pk_bf16_f32 v9, v76, v77
	v_cvt_pk_bf16_f32 v10, v94, v95
	v_cvt_pk_bf16_f32 v11, v96, v97
	global_store_dwordx4 v[12:13], v[8:11], off offset:256 sc1
	s_and_saveexec_b64 s[4:5], vcc
	s_cbranch_execz .LBB0_881
	s_lshl_b32 s54, s40, 2
	v_lshlrev_b64 v[2:3], 7, v[2:3]
	s_ashr_i32 s55, s54, 31
	v_lshl_add_u64 v[2:3], s[22:23], 0, v[2:3]
	v_lshl_add_u64 v[2:3], s[54:55], 2, v[2:3]
	s_lshl_b32 s54, s2, 2
	s_mov_b32 s55, s11
	s_waitcnt lgkmcnt(0)
	v_add_f32_e32 v6, v6, v7
	v_lshl_add_u64 v[2:3], v[2:3], 0, s[54:55]
	global_store_dword v[2:3], v6, off
.LBB0_881:
	s_or_b64 exec, exec, s[4:5]
	v_mul_f32_e32 v6, v71, v71
	s_waitcnt lgkmcnt(0)
	v_mul_f32_e32 v7, v73, v73
	v_mul_f32_e32 v13, v87, v87
	v_mul_f32_e32 v14, v89, v89
	v_fmac_f32_e32 v6, v70, v70
	v_fmac_f32_e32 v7, v72, v72
	v_fmac_f32_e32 v13, v86, v86
	v_fmac_f32_e32 v14, v88, v88
	v_add_f32_e32 v6, v6, v7
	v_mul_f32_e32 v7, v91, v91
	v_add_f32_e32 v13, v13, v14
	v_mul_f32_e32 v14, v111, v111
	v_fmac_f32_e32 v7, v90, v90
	v_fmac_f32_e32 v14, v110, v110
	v_add_f32_e32 v6, v6, v7
	v_mul_f32_e32 v7, v93, v93
	v_add_f32_e32 v13, v13, v14
	v_mul_f32_e32 v14, v113, v113
	v_fmac_f32_e32 v7, v92, v92
	v_fmac_f32_e32 v14, v112, v112
	v_add_u32_e32 v2, 0x90, v130
	v_mov_b32_e32 v3, v131
	v_add_f32_e32 v12, v7, v6
	v_add_f32_e32 v13, v14, v13
	v_lshl_add_u64 v[2:3], s[64:65], 0, v[2:3]
	v_add_f32_e32 v14, v12, v13
	v_lshlrev_b64 v[10:11], 12, v[2:3]
	ds_bpermute_b32 v15, v4, v14
	v_lshl_add_u64 v[10:11], s[14:15], 0, v[10:11]
	v_lshl_add_u64 v[10:11], s[62:63], 1, v[10:11]
	v_lshl_add_u64 v[10:11], v[10:11], 0, s[10:11]
	v_cvt_pk_bf16_f32 v6, v70, v71
	v_lshl_add_u64 v[12:13], v[136:137], 1, v[10:11]
	v_cvt_pk_bf16_f32 v7, v72, v73
	v_cvt_pk_bf16_f32 v8, v90, v91
	v_cvt_pk_bf16_f32 v9, v92, v93
	global_store_dwordx4 v[12:13], v[6:9], off sc1
	s_waitcnt lgkmcnt(0)
	s_nop 0
	v_add_f32_e32 v6, v14, v15
	ds_bpermute_b32 v7, v5, v6
	v_cvt_pk_bf16_f32 v8, v86, v87
	v_cvt_pk_bf16_f32 v9, v88, v89
	v_cvt_pk_bf16_f32 v10, v110, v111
	v_cvt_pk_bf16_f32 v11, v112, v113
	global_store_dwordx4 v[12:13], v[8:11], off offset:256 sc1
	s_and_saveexec_b64 s[4:5], vcc
	s_cbranch_execz .LBB0_883
	s_lshl_b32 s54, s40, 2
	v_lshlrev_b64 v[2:3], 7, v[2:3]
	s_ashr_i32 s55, s54, 31
	v_lshl_add_u64 v[2:3], s[22:23], 0, v[2:3]
	v_lshl_add_u64 v[2:3], s[54:55], 2, v[2:3]
	s_lshl_b32 s54, s2, 2
	s_mov_b32 s55, s11
	s_waitcnt lgkmcnt(0)
	v_add_f32_e32 v6, v6, v7
	v_lshl_add_u64 v[2:3], v[2:3], 0, s[54:55]
	global_store_dword v[2:3], v6, off
; #define LAS __attribute__((address_space(3)))
; __device__ __forceinline__ unsigned cvt_pk_bf16(float lo, float hi) { unsigned r; asm volatile("v_cvt_pk_bf16_f32 %0, %1, %2" : "=v"(r) : "v"(lo), "v"(hi)); return r; }
; __device__ __forceinline__ int fresh_lane() { int l; asm volatile("v_mbcnt_lo_u32_b32 %0, -1, 0\n\tv_mbcnt_hi_u32_b32 %0, -1, %0" : "=v"(l)); return l; }
;     __device__ __forceinline__ void operator()(Acc& acc, const Unit& u, int, int, int wr, int wc, int fr, int fq, LAS unsigned char*) const {
;         { const int ln_ = fresh_lane(); fr = ln_ & 15; fq = ln_ >> 4; }
; #pragma unroll
;         for (int ai = 0; ai < 2; ++ai)
; #pragma unroll
;             for (int m = 0; m < 4; ++m) {
;                 const size_t row = (size_t)u.pm * BM + TROW(ai, m); const size_t off = row * DM + u.pn * BM + wc * 32 + 8 * fq; float ss = 0.f;
; #pragma unroll
;                 for (int bj = 0; bj < 2; ++bj) { const f32x4 o0 = acc[ai][bj][m][0], o1 = acc[ai][bj][m][1];
;                     ss += (o0[0] * o0[0] + o0[1] * o0[1]) + (o0[2] * o0[2] + o0[3] * o0[3]) + (o1[0] * o1[0] + o1[1] * o1[1]) + (o1[2] * o1[2] + o1[3] * o1[3]);
;                     u32x4 w; w.x = cvt_pk_bf16(o0[0], o0[1]); w.y = cvt_pk_bf16(o0[2], o0[3]); w.z = cvt_pk_bf16(o1[0], o1[1]); w.w = cvt_pk_bf16(o1[2], o1[3]); *(u32x4*)(x1b + off + bj * HALF) = w; }
;                 ss += __shfl_xor(ss, 16); ss += __shfl_xor(ss, 32); if (fq == 0) ssq2[row * 32 + u.pn * 4 + wc] = ss;
;             }
;     }
.LBB0_883:
	s_or_b64 exec, exec, s[4:5]
	v_mul_f32_e32 v6, v83, v83
	s_waitcnt lgkmcnt(0)
	v_mul_f32_e32 v7, v85, v85
	v_mul_f32_e32 v13, v103, v103
	v_mul_f32_e32 v14, v105, v105
	v_fmac_f32_e32 v6, v82, v82
	v_fmac_f32_e32 v7, v84, v84
	v_fmac_f32_e32 v13, v102, v102
	v_fmac_f32_e32 v14, v104, v104
	v_add_f32_e32 v6, v6, v7
	v_mul_f32_e32 v7, v107, v107
	v_add_f32_e32 v13, v13, v14
	v_mul_f32_e32 v14, v123, v123
	v_fmac_f32_e32 v7, v106, v106
	v_fmac_f32_e32 v14, v122, v122
	v_add_f32_e32 v6, v6, v7
	v_mul_f32_e32 v7, v109, v109
	v_add_f32_e32 v13, v13, v14
	v_mul_f32_e32 v14, v125, v125
	v_fmac_f32_e32 v7, v108, v108
	v_fmac_f32_e32 v14, v124, v124
	v_add_u32_e32 v2, 0xa0, v130
	v_mov_b32_e32 v3, v131
	v_add_f32_e32 v12, v7, v6
	v_add_f32_e32 v13, v14, v13
	v_lshl_add_u64 v[2:3], s[64:65], 0, v[2:3]
	v_add_f32_e32 v14, v12, v13
	v_lshlrev_b64 v[10:11], 12, v[2:3]
	ds_bpermute_b32 v15, v4, v14
	v_lshl_add_u64 v[10:11], s[14:15], 0, v[10:11]
	v_lshl_add_u64 v[10:11], s[62:63], 1, v[10:11]
	v_lshl_add_u64 v[10:11], v[10:11], 0, s[10:11]
	v_cvt_pk_bf16_f32 v6, v82, v83
	v_lshl_add_u64 v[12:13], v[136:137], 1, v[10:11]
	v_cvt_pk_bf16_f32 v7, v84, v85
	v_cvt_pk_bf16_f32 v8, v106, v107
	v_cvt_pk_bf16_f32 v9, v108, v109
	global_store_dwordx4 v[12:13], v[6:9], off sc1
	s_waitcnt lgkmcnt(0)
	s_nop 0
	v_add_f32_e32 v6, v14, v15
	ds_bpermute_b32 v7, v5, v6
	v_cvt_pk_bf16_f32 v8, v102, v103
	v_cvt_pk_bf16_f32 v9, v104, v105
	v_cvt_pk_bf16_f32 v10, v122, v123
	v_cvt_pk_bf16_f32 v11, v124, v125
	global_store_dwordx4 v[12:13], v[8:11], off offset:256 sc1
	s_and_saveexec_b64 s[4:5], vcc
	s_cbranch_execz .LBB0_885
	s_lshl_b32 s54, s40, 2
	v_lshlrev_b64 v[2:3], 7, v[2:3]
	s_ashr_i32 s55, s54, 31
	v_lshl_add_u64 v[2:3], s[22:23], 0, v[2:3]
	v_lshl_add_u64 v[2:3], s[54:55], 2, v[2:3]
	s_lshl_b32 s54, s2, 2
	s_mov_b32 s55, s11
	s_waitcnt lgkmcnt(0)
	v_add_f32_e32 v6, v6, v7
	v_lshl_add_u64 v[2:3], v[2:3], 0, s[54:55]
	global_store_dword v[2:3], v6, off
.LBB0_885:
	s_or_b64 exec, exec, s[4:5]
	v_mul_f32_e32 v6, v99, v99
	s_waitcnt lgkmcnt(0)
	v_mul_f32_e32 v7, v101, v101
	v_mul_f32_e32 v13, v115, v115
	v_mul_f32_e32 v14, v117, v117
	v_fmac_f32_e32 v6, v98, v98
	v_fmac_f32_e32 v7, v100, v100
	v_fmac_f32_e32 v13, v114, v114
	v_fmac_f32_e32 v14, v116, v116
	v_add_f32_e32 v6, v6, v7
	v_mul_f32_e32 v7, v119, v119
	v_add_f32_e32 v13, v13, v14
	v_mul_f32_e32 v14, v127, v127
	v_fmac_f32_e32 v7, v118, v118
	v_fmac_f32_e32 v14, v126, v126
	v_add_f32_e32 v6, v6, v7
	v_mul_f32_e32 v7, v121, v121
	v_add_f32_e32 v13, v13, v14
	v_mul_f32_e32 v14, v129, v129
	v_fmac_f32_e32 v7, v120, v120
	v_fmac_f32_e32 v14, v128, v128
	v_add_f32_e32 v12, v7, v6
	v_add_f32_e32 v13, v14, v13
	v_add_f32_e32 v12, v12, v13
	ds_bpermute_b32 v4, v4, v12
	v_add_u32_e32 v130, 0xb0, v130
	v_lshl_add_u64 v[2:3], s[64:65], 0, v[130:131]
	v_lshlrev_b64 v[10:11], 12, v[2:3]
	v_lshl_add_u64 v[10:11], s[14:15], 0, v[10:11]
	s_waitcnt lgkmcnt(0)
	v_add_f32_e32 v4, v12, v4
	ds_bpermute_b32 v5, v5, v4
	v_lshl_add_u64 v[10:11], s[62:63], 1, v[10:11]
	v_lshl_add_u64 v[10:11], v[10:11], 0, s[10:11]
	v_cvt_pk_bf16_f32 v6, v98, v99
	v_cvt_pk_bf16_f32 v7, v100, v101
	v_cvt_pk_bf16_f32 v8, v118, v119
	v_cvt_pk_bf16_f32 v9, v120, v121
	v_lshl_add_u64 v[10:11], v[136:137], 1, v[10:11]
	global_store_dwordx4 v[10:11], v[6:9], off sc1
	s_nop 1
	v_cvt_pk_bf16_f32 v6, v114, v115
	v_cvt_pk_bf16_f32 v7, v116, v117
	v_cvt_pk_bf16_f32 v8, v126, v127
	v_cvt_pk_bf16_f32 v9, v128, v129
	global_store_dwordx4 v[10:11], v[6:9], off offset:256 sc1
	s_and_saveexec_b64 s[4:5], vcc
	s_cbranch_execz .LBB0_887
	s_lshl_b32 s54, s40, 2
	v_lshlrev_b64 v[2:3], 7, v[2:3]
	s_ashr_i32 s55, s54, 31
	v_lshl_add_u64 v[2:3], s[22:23], 0, v[2:3]
	v_lshl_add_u64 v[2:3], s[54:55], 2, v[2:3]
	s_lshl_b32 s54, s2, 2
	s_mov_b32 s55, s11
	s_waitcnt lgkmcnt(0)
	v_add_f32_e32 v4, v4, v5
	v_lshl_add_u64 v[2:3], v[2:3], 0, s[54:55]
	global_store_dword v[2:3], v4, off
